# aa1 + nt (streaming) cache hint on P0's once-read f32 weight loads (adaLN weights and the 7 transpose loops, 288 loads)
# speedup vs baseline: 1.0038x; 1.0038x over previous
.LBB0_99:
	s_mul_hi_i32 s14, s19, 0x2aaaaaab
	s_lshr_b32 s15, s14, 31
	s_ashr_i32 s20, s14, 6
	s_add_i32 s20, s20, s15
	s_mul_i32 s14, s20, 0x180
	s_sub_i32 s14, s19, s14
	s_lshl_b32 s14, s14, 5
	s_ashr_i32 s15, s14, 31
	s_mul_i32 s22, s20, 0x6000000
	s_lshl_b64 s[16:17], s[14:15], 2
	s_mul_hi_i32 s21, s20, 0x6000000
	s_add_u32 s16, s22, s16
	s_addc_u32 s17, s21, s17
	v_lshl_add_u64 v[12:13], v[10:11], 0, s[16:17]
	s_mov_b64 s[16:17], 0
	v_mov_b32_e32 v6, v18
	v_mov_b32_e32 v22, v9
	v_mov_b32_e32 v14, 0
	v_mov_b32_e32 v15, v7
	v_mov_b32_e32 v16, 0
	v_mov_b32_e32 v17, v7
	v_mov_b32_e32 v21, 0
	v_add_co_u32_e32 v24, vcc, 0xfffac000, v12
	s_nop 0
	v_addc_co_u32_e32 v25, vcc, -1, v13, vcc
	v_add_co_u32_e32 v26, vcc, 0xfffb8000, v12
	global_load_dword v64, v[24:25], off nt
	s_nop 0
	v_addc_co_u32_e32 v27, vcc, -1, v13, vcc
	v_add_co_u32_e32 v24, vcc, 0xfffc4000, v12
	s_nop 1
	v_addc_co_u32_e32 v25, vcc, -1, v13, vcc
	v_add_co_u32_e32 v28, vcc, 0xfffd0000, v12
	global_load_dword v66, v[26:27], off nt
	global_load_dword v68, v[24:25], off nt
	v_addc_co_u32_e32 v29, vcc, -1, v13, vcc
	v_add_co_u32_e32 v24, vcc, 0xfffdc000, v12
	s_nop 1
	v_addc_co_u32_e32 v25, vcc, -1, v13, vcc
	v_add_co_u32_e32 v26, vcc, 0xfffe8000, v12
	global_load_dword v70, v[28:29], off nt
	global_load_dword v72, v[24:25], off nt
	v_addc_co_u32_e32 v27, vcc, -1, v13, vcc
	v_add_co_u32_e32 v24, vcc, 0xffff4000, v12
	global_load_dword v74, v[26:27], off nt
	s_nop 0
	v_addc_co_u32_e32 v25, vcc, -1, v13, vcc
	global_load_dword v76, v[24:25], off nt
	global_load_dword v78, v[12:13], off nt
	v_lshl_add_u64 v[12:13], v[12:13], 0, s[12:13]
	v_add_co_u32_e32 v24, vcc, 0xfffac000, v12
	s_nop 0
	v_addc_co_u32_e32 v25, vcc, -1, v13, vcc
	v_add_co_u32_e32 v26, vcc, 0xfffb8000, v12
	global_load_dword v96, v[24:25], off nt
	s_nop 0
	v_addc_co_u32_e32 v27, vcc, -1, v13, vcc
	v_add_co_u32_e32 v24, vcc, 0xfffc4000, v12
	s_nop 1
	v_addc_co_u32_e32 v25, vcc, -1, v13, vcc
	v_add_co_u32_e32 v28, vcc, 0xfffd0000, v12
	global_load_dword v98, v[26:27], off nt
	global_load_dword v100, v[24:25], off nt
	v_addc_co_u32_e32 v29, vcc, -1, v13, vcc
	v_add_co_u32_e32 v24, vcc, 0xfffdc000, v12
	s_nop 1
	v_addc_co_u32_e32 v25, vcc, -1, v13, vcc
	v_add_co_u32_e32 v26, vcc, 0xfffe8000, v12
	global_load_dword v102, v[28:29], off nt
	global_load_dword v104, v[24:25], off nt
	v_addc_co_u32_e32 v27, vcc, -1, v13, vcc
	v_add_co_u32_e32 v24, vcc, 0xffff4000, v12
	global_load_dword v106, v[26:27], off nt
	s_nop 0
	v_addc_co_u32_e32 v25, vcc, -1, v13, vcc
	global_load_dword v108, v[24:25], off nt
	global_load_dword v110, v[12:13], off nt
	v_lshl_add_u64 v[12:13], v[12:13], 0, s[12:13]
	v_add_co_u32_e32 v24, vcc, 0xfffac000, v12
	s_nop 0
	v_addc_co_u32_e32 v25, vcc, -1, v13, vcc
	v_add_co_u32_e32 v26, vcc, 0xfffb8000, v12
	global_load_dword v112, v[24:25], off nt
	s_nop 0
	v_addc_co_u32_e32 v27, vcc, -1, v13, vcc
	v_add_co_u32_e32 v24, vcc, 0xfffc4000, v12
	s_nop 1
	v_addc_co_u32_e32 v25, vcc, -1, v13, vcc
	v_add_co_u32_e32 v28, vcc, 0xfffd0000, v12
	global_load_dword v114, v[26:27], off nt
	global_load_dword v116, v[24:25], off nt
	v_addc_co_u32_e32 v29, vcc, -1, v13, vcc
	v_add_co_u32_e32 v24, vcc, 0xfffdc000, v12
	s_nop 1
	v_addc_co_u32_e32 v25, vcc, -1, v13, vcc
	v_add_co_u32_e32 v26, vcc, 0xfffe8000, v12
	global_load_dword v118, v[28:29], off nt
	global_load_dword v120, v[24:25], off nt
	v_addc_co_u32_e32 v27, vcc, -1, v13, vcc
	v_add_co_u32_e32 v24, vcc, 0xffff4000, v12
	global_load_dword v122, v[26:27], off nt
	s_nop 0
	v_addc_co_u32_e32 v25, vcc, -1, v13, vcc
	global_load_dword v124, v[24:25], off nt
	global_load_dword v126, v[12:13], off nt
	v_lshl_add_u64 v[12:13], v[12:13], 0, s[12:13]
	s_mov_b32 s100, 3
.Lada_loop:
	v_add_co_u32_e32 v24, vcc, 0xfffac000, v12
	s_nop 0
	v_addc_co_u32_e32 v25, vcc, -1, v13, vcc
	v_add_co_u32_e32 v26, vcc, 0xfffb8000, v12
	global_load_dword v128, v[24:25], off nt
	s_nop 0
	v_addc_co_u32_e32 v27, vcc, -1, v13, vcc
	v_add_co_u32_e32 v24, vcc, 0xfffc4000, v12
	s_nop 1
	v_addc_co_u32_e32 v25, vcc, -1, v13, vcc
	v_add_co_u32_e32 v28, vcc, 0xfffd0000, v12
	global_load_dword v130, v[26:27], off nt
	global_load_dword v132, v[24:25], off nt
	v_addc_co_u32_e32 v29, vcc, -1, v13, vcc
	v_add_co_u32_e32 v24, vcc, 0xfffdc000, v12
	s_nop 1
	v_addc_co_u32_e32 v25, vcc, -1, v13, vcc
	v_add_co_u32_e32 v26, vcc, 0xfffe8000, v12
	global_load_dword v134, v[28:29], off nt
	global_load_dword v136, v[24:25], off nt
	v_addc_co_u32_e32 v27, vcc, -1, v13, vcc
	v_add_co_u32_e32 v24, vcc, 0xffff4000, v12
	global_load_dword v138, v[26:27], off nt
	s_nop 0
	v_addc_co_u32_e32 v25, vcc, -1, v13, vcc
	global_load_dword v140, v[24:25], off nt
	global_load_dword v142, v[12:13], off nt
	v_lshl_add_u64 v[12:13], v[12:13], 0, s[12:13]
	ds_read_b128 v[24:27], v6
	ds_read_b128 v[28:31], v6 offset:16
	ds_read_b128 v[32:35], v6 offset:8192
	ds_read_b128 v[36:39], v6 offset:8208
	ds_read_b128 v[40:43], v6 offset:16384
	ds_read_b128 v[44:47], v6 offset:16400
	ds_read_b128 v[48:51], v6 offset:24576
	ds_read_b128 v[52:55], v6 offset:24592
	ds_read_b128 v[56:59], v6 offset:32768
	ds_read_b128 v[60:63], v6 offset:32784
	s_waitcnt lgkmcnt(9)
	v_mov_b32_e32 v80, v24
	s_waitcnt lgkmcnt(7)
	v_mov_b32_e32 v81, v32
	v_mov_b32_e32 v32, v25
	v_mov_b32_e32 v24, v26
	v_mov_b32_e32 v25, v34
	v_mov_b32_e32 v34, v27
	v_mov_b32_e32 v26, v28
	s_waitcnt lgkmcnt(6)
	v_mov_b32_e32 v27, v36
	v_mov_b32_e32 v36, v29
	v_mov_b32_e32 v28, v30
	v_mov_b32_e32 v29, v38
	v_mov_b32_e32 v38, v31
	s_waitcnt lgkmcnt(5)
	v_mov_b32_e32 v30, v40
	s_waitcnt lgkmcnt(3)
	v_mov_b32_e32 v31, v48
	v_mov_b32_e32 v48, v41
	v_mov_b32_e32 v40, v42
	v_mov_b32_e32 v41, v50
	v_mov_b32_e32 v50, v43
	v_mov_b32_e32 v42, v44
	s_waitcnt lgkmcnt(2)
	v_mov_b32_e32 v43, v52
	v_mov_b32_e32 v52, v45
	v_mov_b32_e32 v44, v46
	v_mov_b32_e32 v45, v54
	v_mov_b32_e32 v54, v47
	v_add_u32_e32 v6, 32, v6
	s_waitcnt vmcnt(31)
	v_pk_fma_f32 v[14:15], v[80:81], v[64:65], v[14:15] op_sel_hi:[1,0,1]
	v_pk_fma_f32 v[16:17], v[30:31], v[64:65], v[16:17] op_sel_hi:[1,0,1]
	s_waitcnt lgkmcnt(1)
	v_fmac_f32_e32 v21, v56, v64
	s_waitcnt vmcnt(30)
	v_fmac_f32_e32 v21, v57, v66
	v_pk_fma_f32 v[14:15], v[32:33], v[66:67], v[14:15] op_sel_hi:[1,0,1]
	v_pk_fma_f32 v[16:17], v[48:49], v[66:67], v[16:17] op_sel_hi:[1,0,1]
	s_waitcnt vmcnt(29)
	v_fmac_f32_e32 v21, v58, v68
	v_pk_fma_f32 v[14:15], v[24:25], v[68:69], v[14:15] op_sel_hi:[1,0,1]
	v_pk_fma_f32 v[16:17], v[40:41], v[68:69], v[16:17] op_sel_hi:[1,0,1]
	s_waitcnt vmcnt(28)
	v_fmac_f32_e32 v21, v59, v70
	v_pk_fma_f32 v[14:15], v[34:35], v[70:71], v[14:15] op_sel_hi:[1,0,1]
	v_pk_fma_f32 v[16:17], v[50:51], v[70:71], v[16:17] op_sel_hi:[1,0,1]
	s_waitcnt vmcnt(27) lgkmcnt(0)
	v_fmac_f32_e32 v21, v60, v72
	v_pk_fma_f32 v[14:15], v[26:27], v[72:73], v[14:15] op_sel_hi:[1,0,1]
	v_pk_fma_f32 v[16:17], v[42:43], v[72:73], v[16:17] op_sel_hi:[1,0,1]
	s_waitcnt vmcnt(26)
	v_fmac_f32_e32 v21, v61, v74
	v_pk_fma_f32 v[14:15], v[36:37], v[74:75], v[14:15] op_sel_hi:[1,0,1]
	v_pk_fma_f32 v[16:17], v[52:53], v[74:75], v[16:17] op_sel_hi:[1,0,1]
	s_waitcnt vmcnt(25)
	v_fmac_f32_e32 v21, v62, v76
	v_pk_fma_f32 v[14:15], v[28:29], v[76:77], v[14:15] op_sel_hi:[1,0,1]
	v_pk_fma_f32 v[16:17], v[44:45], v[76:77], v[16:17] op_sel_hi:[1,0,1]
	s_waitcnt vmcnt(24)
	v_pk_fma_f32 v[14:15], v[38:39], v[78:79], v[14:15] op_sel_hi:[1,0,1]
	v_pk_fma_f32 v[16:17], v[54:55], v[78:79], v[16:17] op_sel_hi:[1,0,1]
	v_fmac_f32_e32 v21, v63, v78
	v_add_co_u32_e32 v24, vcc, 0xfffac000, v12
	s_nop 0
	v_addc_co_u32_e32 v25, vcc, -1, v13, vcc
	v_add_co_u32_e32 v26, vcc, 0xfffb8000, v12
	global_load_dword v64, v[24:25], off nt
	s_nop 0
	v_addc_co_u32_e32 v27, vcc, -1, v13, vcc
	v_add_co_u32_e32 v24, vcc, 0xfffc4000, v12
	s_nop 1
	v_addc_co_u32_e32 v25, vcc, -1, v13, vcc
	v_add_co_u32_e32 v28, vcc, 0xfffd0000, v12
	global_load_dword v66, v[26:27], off nt
	global_load_dword v68, v[24:25], off nt
	v_addc_co_u32_e32 v29, vcc, -1, v13, vcc
	v_add_co_u32_e32 v24, vcc, 0xfffdc000, v12
	s_nop 1
	v_addc_co_u32_e32 v25, vcc, -1, v13, vcc
	v_add_co_u32_e32 v26, vcc, 0xfffe8000, v12
	global_load_dword v70, v[28:29], off nt
	global_load_dword v72, v[24:25], off nt
	v_addc_co_u32_e32 v27, vcc, -1, v13, vcc
	v_add_co_u32_e32 v24, vcc, 0xffff4000, v12
	global_load_dword v74, v[26:27], off nt
	s_nop 0
	v_addc_co_u32_e32 v25, vcc, -1, v13, vcc
	global_load_dword v76, v[24:25], off nt
	global_load_dword v78, v[12:13], off nt
	v_lshl_add_u64 v[12:13], v[12:13], 0, s[12:13]
	ds_read_b128 v[24:27], v6
	ds_read_b128 v[28:31], v6 offset:16
	ds_read_b128 v[32:35], v6 offset:8192
	ds_read_b128 v[36:39], v6 offset:8208
	ds_read_b128 v[40:43], v6 offset:16384
	ds_read_b128 v[44:47], v6 offset:16400
	ds_read_b128 v[48:51], v6 offset:24576
	ds_read_b128 v[52:55], v6 offset:24592
	ds_read_b128 v[56:59], v6 offset:32768
	ds_read_b128 v[60:63], v6 offset:32784
	s_waitcnt lgkmcnt(9)
	v_mov_b32_e32 v80, v24
	s_waitcnt lgkmcnt(7)
	v_mov_b32_e32 v81, v32
	v_mov_b32_e32 v32, v25
	v_mov_b32_e32 v24, v26
	v_mov_b32_e32 v25, v34
	v_mov_b32_e32 v34, v27
	v_mov_b32_e32 v26, v28
	s_waitcnt lgkmcnt(6)
	v_mov_b32_e32 v27, v36
	v_mov_b32_e32 v36, v29
	v_mov_b32_e32 v28, v30
	v_mov_b32_e32 v29, v38
	v_mov_b32_e32 v38, v31
	s_waitcnt lgkmcnt(5)
	v_mov_b32_e32 v30, v40
	s_waitcnt lgkmcnt(3)
	v_mov_b32_e32 v31, v48
	v_mov_b32_e32 v48, v41
	v_mov_b32_e32 v40, v42
	v_mov_b32_e32 v41, v50
	v_mov_b32_e32 v50, v43
	v_mov_b32_e32 v42, v44
	s_waitcnt lgkmcnt(2)
	v_mov_b32_e32 v43, v52
	v_mov_b32_e32 v52, v45
	v_mov_b32_e32 v44, v46
	v_mov_b32_e32 v45, v54
	v_mov_b32_e32 v54, v47
	v_add_u32_e32 v6, 32, v6
	s_waitcnt vmcnt(31)
	v_pk_fma_f32 v[14:15], v[80:81], v[96:97], v[14:15] op_sel_hi:[1,0,1]
	v_pk_fma_f32 v[16:17], v[30:31], v[96:97], v[16:17] op_sel_hi:[1,0,1]
	s_waitcnt lgkmcnt(1)
	v_fmac_f32_e32 v21, v56, v96
	s_waitcnt vmcnt(30)
	v_fmac_f32_e32 v21, v57, v98
	v_pk_fma_f32 v[14:15], v[32:33], v[98:99], v[14:15] op_sel_hi:[1,0,1]
	v_pk_fma_f32 v[16:17], v[48:49], v[98:99], v[16:17] op_sel_hi:[1,0,1]
	s_waitcnt vmcnt(29)
	v_fmac_f32_e32 v21, v58, v100
	v_pk_fma_f32 v[14:15], v[24:25], v[100:101], v[14:15] op_sel_hi:[1,0,1]
	v_pk_fma_f32 v[16:17], v[40:41], v[100:101], v[16:17] op_sel_hi:[1,0,1]
	s_waitcnt vmcnt(28)
	v_fmac_f32_e32 v21, v59, v102
	v_pk_fma_f32 v[14:15], v[34:35], v[102:103], v[14:15] op_sel_hi:[1,0,1]
	v_pk_fma_f32 v[16:17], v[50:51], v[102:103], v[16:17] op_sel_hi:[1,0,1]
	s_waitcnt vmcnt(27) lgkmcnt(0)
	v_fmac_f32_e32 v21, v60, v104
	v_pk_fma_f32 v[14:15], v[26:27], v[104:105], v[14:15] op_sel_hi:[1,0,1]
	v_pk_fma_f32 v[16:17], v[42:43], v[104:105], v[16:17] op_sel_hi:[1,0,1]
	s_waitcnt vmcnt(26)
	v_fmac_f32_e32 v21, v61, v106
	v_pk_fma_f32 v[14:15], v[36:37], v[106:107], v[14:15] op_sel_hi:[1,0,1]
	v_pk_fma_f32 v[16:17], v[52:53], v[106:107], v[16:17] op_sel_hi:[1,0,1]
	s_waitcnt vmcnt(25)
	v_fmac_f32_e32 v21, v62, v108
	v_pk_fma_f32 v[14:15], v[28:29], v[108:109], v[14:15] op_sel_hi:[1,0,1]
	v_pk_fma_f32 v[16:17], v[44:45], v[108:109], v[16:17] op_sel_hi:[1,0,1]
	s_waitcnt vmcnt(24)
	v_pk_fma_f32 v[14:15], v[38:39], v[110:111], v[14:15] op_sel_hi:[1,0,1]
	v_pk_fma_f32 v[16:17], v[54:55], v[110:111], v[16:17] op_sel_hi:[1,0,1]
	v_fmac_f32_e32 v21, v63, v110
	v_add_co_u32_e32 v24, vcc, 0xfffac000, v12
	s_nop 0
	v_addc_co_u32_e32 v25, vcc, -1, v13, vcc
	v_add_co_u32_e32 v26, vcc, 0xfffb8000, v12
	global_load_dword v96, v[24:25], off nt
	s_nop 0
	v_addc_co_u32_e32 v27, vcc, -1, v13, vcc
	v_add_co_u32_e32 v24, vcc, 0xfffc4000, v12
	s_nop 1
	v_addc_co_u32_e32 v25, vcc, -1, v13, vcc
	v_add_co_u32_e32 v28, vcc, 0xfffd0000, v12
	global_load_dword v98, v[26:27], off nt
	global_load_dword v100, v[24:25], off nt
	v_addc_co_u32_e32 v29, vcc, -1, v13, vcc
	v_add_co_u32_e32 v24, vcc, 0xfffdc000, v12
	s_nop 1
	v_addc_co_u32_e32 v25, vcc, -1, v13, vcc
	v_add_co_u32_e32 v26, vcc, 0xfffe8000, v12
	global_load_dword v102, v[28:29], off nt
	global_load_dword v104, v[24:25], off nt
	v_addc_co_u32_e32 v27, vcc, -1, v13, vcc
	v_add_co_u32_e32 v24, vcc, 0xffff4000, v12
	global_load_dword v106, v[26:27], off nt
	s_nop 0
	v_addc_co_u32_e32 v25, vcc, -1, v13, vcc
	global_load_dword v108, v[24:25], off nt
	global_load_dword v110, v[12:13], off nt
	v_lshl_add_u64 v[12:13], v[12:13], 0, s[12:13]
	ds_read_b128 v[24:27], v6
	ds_read_b128 v[28:31], v6 offset:16
	ds_read_b128 v[32:35], v6 offset:8192
	ds_read_b128 v[36:39], v6 offset:8208
	ds_read_b128 v[40:43], v6 offset:16384
	ds_read_b128 v[44:47], v6 offset:16400
	ds_read_b128 v[48:51], v6 offset:24576
	ds_read_b128 v[52:55], v6 offset:24592
	ds_read_b128 v[56:59], v6 offset:32768
	ds_read_b128 v[60:63], v6 offset:32784
	s_waitcnt lgkmcnt(9)
	v_mov_b32_e32 v80, v24
	s_waitcnt lgkmcnt(7)
	v_mov_b32_e32 v81, v32
	v_mov_b32_e32 v32, v25
	v_mov_b32_e32 v24, v26
	v_mov_b32_e32 v25, v34
	v_mov_b32_e32 v34, v27
	v_mov_b32_e32 v26, v28
	s_waitcnt lgkmcnt(6)
	v_mov_b32_e32 v27, v36
	v_mov_b32_e32 v36, v29
	v_mov_b32_e32 v28, v30
	v_mov_b32_e32 v29, v38
	v_mov_b32_e32 v38, v31
	s_waitcnt lgkmcnt(5)
	v_mov_b32_e32 v30, v40
	s_waitcnt lgkmcnt(3)
	v_mov_b32_e32 v31, v48
	v_mov_b32_e32 v48, v41
	v_mov_b32_e32 v40, v42
	v_mov_b32_e32 v41, v50
	v_mov_b32_e32 v50, v43
	v_mov_b32_e32 v42, v44
	s_waitcnt lgkmcnt(2)
	v_mov_b32_e32 v43, v52
	v_mov_b32_e32 v52, v45
	v_mov_b32_e32 v44, v46
	v_mov_b32_e32 v45, v54
	v_mov_b32_e32 v54, v47
	v_add_u32_e32 v6, 32, v6
	s_waitcnt vmcnt(31)
	v_pk_fma_f32 v[14:15], v[80:81], v[112:113], v[14:15] op_sel_hi:[1,0,1]
	v_pk_fma_f32 v[16:17], v[30:31], v[112:113], v[16:17] op_sel_hi:[1,0,1]
	s_waitcnt lgkmcnt(1)
	v_fmac_f32_e32 v21, v56, v112
	s_waitcnt vmcnt(30)
	v_fmac_f32_e32 v21, v57, v114
	v_pk_fma_f32 v[14:15], v[32:33], v[114:115], v[14:15] op_sel_hi:[1,0,1]
	v_pk_fma_f32 v[16:17], v[48:49], v[114:115], v[16:17] op_sel_hi:[1,0,1]
	s_waitcnt vmcnt(29)
	v_fmac_f32_e32 v21, v58, v116
	v_pk_fma_f32 v[14:15], v[24:25], v[116:117], v[14:15] op_sel_hi:[1,0,1]
	v_pk_fma_f32 v[16:17], v[40:41], v[116:117], v[16:17] op_sel_hi:[1,0,1]
	s_waitcnt vmcnt(28)
	v_fmac_f32_e32 v21, v59, v118
	v_pk_fma_f32 v[14:15], v[34:35], v[118:119], v[14:15] op_sel_hi:[1,0,1]
	v_pk_fma_f32 v[16:17], v[50:51], v[118:119], v[16:17] op_sel_hi:[1,0,1]
	s_waitcnt vmcnt(27) lgkmcnt(0)
	v_fmac_f32_e32 v21, v60, v120
	v_pk_fma_f32 v[14:15], v[26:27], v[120:121], v[14:15] op_sel_hi:[1,0,1]
	v_pk_fma_f32 v[16:17], v[42:43], v[120:121], v[16:17] op_sel_hi:[1,0,1]
	s_waitcnt vmcnt(26)
	v_fmac_f32_e32 v21, v61, v122
	v_pk_fma_f32 v[14:15], v[36:37], v[122:123], v[14:15] op_sel_hi:[1,0,1]
	v_pk_fma_f32 v[16:17], v[52:53], v[122:123], v[16:17] op_sel_hi:[1,0,1]
	s_waitcnt vmcnt(25)
	v_fmac_f32_e32 v21, v62, v124
	v_pk_fma_f32 v[14:15], v[28:29], v[124:125], v[14:15] op_sel_hi:[1,0,1]
	v_pk_fma_f32 v[16:17], v[44:45], v[124:125], v[16:17] op_sel_hi:[1,0,1]
	s_waitcnt vmcnt(24)
	v_pk_fma_f32 v[14:15], v[38:39], v[126:127], v[14:15] op_sel_hi:[1,0,1]
	v_pk_fma_f32 v[16:17], v[54:55], v[126:127], v[16:17] op_sel_hi:[1,0,1]
	v_fmac_f32_e32 v21, v63, v126
	v_add_co_u32_e32 v24, vcc, 0xfffac000, v12
	s_nop 0
	v_addc_co_u32_e32 v25, vcc, -1, v13, vcc
	v_add_co_u32_e32 v26, vcc, 0xfffb8000, v12
	global_load_dword v112, v[24:25], off nt
	s_nop 0
	v_addc_co_u32_e32 v27, vcc, -1, v13, vcc
	v_add_co_u32_e32 v24, vcc, 0xfffc4000, v12
	s_nop 1
	v_addc_co_u32_e32 v25, vcc, -1, v13, vcc
	v_add_co_u32_e32 v28, vcc, 0xfffd0000, v12
	global_load_dword v114, v[26:27], off nt
	global_load_dword v116, v[24:25], off nt
	v_addc_co_u32_e32 v29, vcc, -1, v13, vcc
	v_add_co_u32_e32 v24, vcc, 0xfffdc000, v12
	s_nop 1
	v_addc_co_u32_e32 v25, vcc, -1, v13, vcc
	v_add_co_u32_e32 v26, vcc, 0xfffe8000, v12
	global_load_dword v118, v[28:29], off nt
	global_load_dword v120, v[24:25], off nt
	v_addc_co_u32_e32 v27, vcc, -1, v13, vcc
	v_add_co_u32_e32 v24, vcc, 0xffff4000, v12
	global_load_dword v122, v[26:27], off nt
	s_nop 0
	v_addc_co_u32_e32 v25, vcc, -1, v13, vcc
	global_load_dword v124, v[24:25], off nt
	global_load_dword v126, v[12:13], off nt
	v_lshl_add_u64 v[12:13], v[12:13], 0, s[12:13]
	ds_read_b128 v[24:27], v6
	ds_read_b128 v[28:31], v6 offset:16
	ds_read_b128 v[32:35], v6 offset:8192
	ds_read_b128 v[36:39], v6 offset:8208
	ds_read_b128 v[40:43], v6 offset:16384
	ds_read_b128 v[44:47], v6 offset:16400
	ds_read_b128 v[48:51], v6 offset:24576
	ds_read_b128 v[52:55], v6 offset:24592
	ds_read_b128 v[56:59], v6 offset:32768
	ds_read_b128 v[60:63], v6 offset:32784
	s_waitcnt lgkmcnt(9)
	v_mov_b32_e32 v80, v24
	s_waitcnt lgkmcnt(7)
	v_mov_b32_e32 v81, v32
	v_mov_b32_e32 v32, v25
	v_mov_b32_e32 v24, v26
	v_mov_b32_e32 v25, v34
	v_mov_b32_e32 v34, v27
	v_mov_b32_e32 v26, v28
	s_waitcnt lgkmcnt(6)
	v_mov_b32_e32 v27, v36
	v_mov_b32_e32 v36, v29
	v_mov_b32_e32 v28, v30
	v_mov_b32_e32 v29, v38
	v_mov_b32_e32 v38, v31
	s_waitcnt lgkmcnt(5)
	v_mov_b32_e32 v30, v40
	s_waitcnt lgkmcnt(3)
	v_mov_b32_e32 v31, v48
	v_mov_b32_e32 v48, v41
	v_mov_b32_e32 v40, v42
	v_mov_b32_e32 v41, v50
	v_mov_b32_e32 v50, v43
	v_mov_b32_e32 v42, v44
	s_waitcnt lgkmcnt(2)
	v_mov_b32_e32 v43, v52
	v_mov_b32_e32 v52, v45
	v_mov_b32_e32 v44, v46
	v_mov_b32_e32 v45, v54
	v_mov_b32_e32 v54, v47
	v_add_u32_e32 v6, 32, v6
	s_waitcnt vmcnt(31)
	v_pk_fma_f32 v[14:15], v[80:81], v[128:129], v[14:15] op_sel_hi:[1,0,1]
	v_pk_fma_f32 v[16:17], v[30:31], v[128:129], v[16:17] op_sel_hi:[1,0,1]
	s_waitcnt lgkmcnt(1)
	v_fmac_f32_e32 v21, v56, v128
	s_waitcnt vmcnt(30)
	v_fmac_f32_e32 v21, v57, v130
	v_pk_fma_f32 v[14:15], v[32:33], v[130:131], v[14:15] op_sel_hi:[1,0,1]
	v_pk_fma_f32 v[16:17], v[48:49], v[130:131], v[16:17] op_sel_hi:[1,0,1]
	s_waitcnt vmcnt(29)
	v_fmac_f32_e32 v21, v58, v132
	v_pk_fma_f32 v[14:15], v[24:25], v[132:133], v[14:15] op_sel_hi:[1,0,1]
	v_pk_fma_f32 v[16:17], v[40:41], v[132:133], v[16:17] op_sel_hi:[1,0,1]
	s_waitcnt vmcnt(28)
	v_fmac_f32_e32 v21, v59, v134
	v_pk_fma_f32 v[14:15], v[34:35], v[134:135], v[14:15] op_sel_hi:[1,0,1]
	v_pk_fma_f32 v[16:17], v[50:51], v[134:135], v[16:17] op_sel_hi:[1,0,1]
	s_waitcnt vmcnt(27) lgkmcnt(0)
	v_fmac_f32_e32 v21, v60, v136
	v_pk_fma_f32 v[14:15], v[26:27], v[136:137], v[14:15] op_sel_hi:[1,0,1]
	v_pk_fma_f32 v[16:17], v[42:43], v[136:137], v[16:17] op_sel_hi:[1,0,1]
	s_waitcnt vmcnt(26)
	v_fmac_f32_e32 v21, v61, v138
	v_pk_fma_f32 v[14:15], v[36:37], v[138:139], v[14:15] op_sel_hi:[1,0,1]
	v_pk_fma_f32 v[16:17], v[52:53], v[138:139], v[16:17] op_sel_hi:[1,0,1]
	s_waitcnt vmcnt(25)
	v_fmac_f32_e32 v21, v62, v140
	v_pk_fma_f32 v[14:15], v[28:29], v[140:141], v[14:15] op_sel_hi:[1,0,1]
	v_pk_fma_f32 v[16:17], v[44:45], v[140:141], v[16:17] op_sel_hi:[1,0,1]
	s_waitcnt vmcnt(24)
	v_pk_fma_f32 v[14:15], v[38:39], v[142:143], v[14:15] op_sel_hi:[1,0,1]
	v_pk_fma_f32 v[16:17], v[54:55], v[142:143], v[16:17] op_sel_hi:[1,0,1]
	v_fmac_f32_e32 v21, v63, v142
	s_sub_u32 s100, s100, 1
	s_cmp_lg_u32 s100, 0
	s_cbranch_scc1 .Lada_loop
	v_add_co_u32_e32 v24, vcc, 0xfffac000, v12
	s_nop 0
	v_addc_co_u32_e32 v25, vcc, -1, v13, vcc
	v_add_co_u32_e32 v26, vcc, 0xfffb8000, v12
	global_load_dword v128, v[24:25], off nt
	s_nop 0
	v_addc_co_u32_e32 v27, vcc, -1, v13, vcc
	v_add_co_u32_e32 v24, vcc, 0xfffc4000, v12
	s_nop 1
	v_addc_co_u32_e32 v25, vcc, -1, v13, vcc
	v_add_co_u32_e32 v28, vcc, 0xfffd0000, v12
	global_load_dword v130, v[26:27], off nt
	global_load_dword v132, v[24:25], off nt
	v_addc_co_u32_e32 v29, vcc, -1, v13, vcc
	v_add_co_u32_e32 v24, vcc, 0xfffdc000, v12
	s_nop 1
	v_addc_co_u32_e32 v25, vcc, -1, v13, vcc
	v_add_co_u32_e32 v26, vcc, 0xfffe8000, v12
	global_load_dword v134, v[28:29], off nt
	global_load_dword v136, v[24:25], off nt
	v_addc_co_u32_e32 v27, vcc, -1, v13, vcc
	v_add_co_u32_e32 v24, vcc, 0xffff4000, v12
	global_load_dword v138, v[26:27], off nt
	s_nop 0
	v_addc_co_u32_e32 v25, vcc, -1, v13, vcc
	global_load_dword v140, v[24:25], off nt
	global_load_dword v142, v[12:13], off nt
	v_lshl_add_u64 v[12:13], v[12:13], 0, s[12:13]
	ds_read_b128 v[24:27], v6
	ds_read_b128 v[28:31], v6 offset:16
	ds_read_b128 v[32:35], v6 offset:8192
	ds_read_b128 v[36:39], v6 offset:8208
	ds_read_b128 v[40:43], v6 offset:16384
	ds_read_b128 v[44:47], v6 offset:16400
	ds_read_b128 v[48:51], v6 offset:24576
	ds_read_b128 v[52:55], v6 offset:24592
	ds_read_b128 v[56:59], v6 offset:32768
	ds_read_b128 v[60:63], v6 offset:32784
	s_waitcnt lgkmcnt(9)
	v_mov_b32_e32 v80, v24
	s_waitcnt lgkmcnt(7)
	v_mov_b32_e32 v81, v32
	v_mov_b32_e32 v32, v25
	v_mov_b32_e32 v24, v26
	v_mov_b32_e32 v25, v34
	v_mov_b32_e32 v34, v27
	v_mov_b32_e32 v26, v28
	s_waitcnt lgkmcnt(6)
	v_mov_b32_e32 v27, v36
	v_mov_b32_e32 v36, v29
	v_mov_b32_e32 v28, v30
	v_mov_b32_e32 v29, v38
	v_mov_b32_e32 v38, v31
	s_waitcnt lgkmcnt(5)
	v_mov_b32_e32 v30, v40
	s_waitcnt lgkmcnt(3)
	v_mov_b32_e32 v31, v48
	v_mov_b32_e32 v48, v41
	v_mov_b32_e32 v40, v42
	v_mov_b32_e32 v41, v50
	v_mov_b32_e32 v50, v43
	v_mov_b32_e32 v42, v44
	s_waitcnt lgkmcnt(2)
	v_mov_b32_e32 v43, v52
	v_mov_b32_e32 v52, v45
	v_mov_b32_e32 v44, v46
	v_mov_b32_e32 v45, v54
	v_mov_b32_e32 v54, v47
	v_add_u32_e32 v6, 32, v6
	s_waitcnt vmcnt(31)
	v_pk_fma_f32 v[14:15], v[80:81], v[64:65], v[14:15] op_sel_hi:[1,0,1]
	v_pk_fma_f32 v[16:17], v[30:31], v[64:65], v[16:17] op_sel_hi:[1,0,1]
	s_waitcnt lgkmcnt(1)
	v_fmac_f32_e32 v21, v56, v64
	s_waitcnt vmcnt(30)
	v_fmac_f32_e32 v21, v57, v66
	v_pk_fma_f32 v[14:15], v[32:33], v[66:67], v[14:15] op_sel_hi:[1,0,1]
	v_pk_fma_f32 v[16:17], v[48:49], v[66:67], v[16:17] op_sel_hi:[1,0,1]
	s_waitcnt vmcnt(29)
	v_fmac_f32_e32 v21, v58, v68
	v_pk_fma_f32 v[14:15], v[24:25], v[68:69], v[14:15] op_sel_hi:[1,0,1]
	v_pk_fma_f32 v[16:17], v[40:41], v[68:69], v[16:17] op_sel_hi:[1,0,1]
	s_waitcnt vmcnt(28)
	v_fmac_f32_e32 v21, v59, v70
	v_pk_fma_f32 v[14:15], v[34:35], v[70:71], v[14:15] op_sel_hi:[1,0,1]
	v_pk_fma_f32 v[16:17], v[50:51], v[70:71], v[16:17] op_sel_hi:[1,0,1]
	s_waitcnt vmcnt(27) lgkmcnt(0)
	v_fmac_f32_e32 v21, v60, v72
	v_pk_fma_f32 v[14:15], v[26:27], v[72:73], v[14:15] op_sel_hi:[1,0,1]
	v_pk_fma_f32 v[16:17], v[42:43], v[72:73], v[16:17] op_sel_hi:[1,0,1]
	s_waitcnt vmcnt(26)
	v_fmac_f32_e32 v21, v61, v74
	v_pk_fma_f32 v[14:15], v[36:37], v[74:75], v[14:15] op_sel_hi:[1,0,1]
	v_pk_fma_f32 v[16:17], v[52:53], v[74:75], v[16:17] op_sel_hi:[1,0,1]
	s_waitcnt vmcnt(25)
	v_fmac_f32_e32 v21, v62, v76
	v_pk_fma_f32 v[14:15], v[28:29], v[76:77], v[14:15] op_sel_hi:[1,0,1]
	v_pk_fma_f32 v[16:17], v[44:45], v[76:77], v[16:17] op_sel_hi:[1,0,1]
	s_waitcnt vmcnt(24)
	v_pk_fma_f32 v[14:15], v[38:39], v[78:79], v[14:15] op_sel_hi:[1,0,1]
	v_pk_fma_f32 v[16:17], v[54:55], v[78:79], v[16:17] op_sel_hi:[1,0,1]
	v_fmac_f32_e32 v21, v63, v78
	ds_read_b128 v[24:27], v6
	ds_read_b128 v[28:31], v6 offset:16
	ds_read_b128 v[32:35], v6 offset:8192
	ds_read_b128 v[36:39], v6 offset:8208
	ds_read_b128 v[40:43], v6 offset:16384
	ds_read_b128 v[44:47], v6 offset:16400
	ds_read_b128 v[48:51], v6 offset:24576
	ds_read_b128 v[52:55], v6 offset:24592
	ds_read_b128 v[56:59], v6 offset:32768
	ds_read_b128 v[60:63], v6 offset:32784
	s_waitcnt lgkmcnt(9)
	v_mov_b32_e32 v80, v24
	s_waitcnt lgkmcnt(7)
	v_mov_b32_e32 v81, v32
	v_mov_b32_e32 v32, v25
	v_mov_b32_e32 v24, v26
	v_mov_b32_e32 v25, v34
	v_mov_b32_e32 v34, v27
	v_mov_b32_e32 v26, v28
	s_waitcnt lgkmcnt(6)
	v_mov_b32_e32 v27, v36
	v_mov_b32_e32 v36, v29
	v_mov_b32_e32 v28, v30
	v_mov_b32_e32 v29, v38
	v_mov_b32_e32 v38, v31
	s_waitcnt lgkmcnt(5)
	v_mov_b32_e32 v30, v40
	s_waitcnt lgkmcnt(3)
	v_mov_b32_e32 v31, v48
	v_mov_b32_e32 v48, v41
	v_mov_b32_e32 v40, v42
	v_mov_b32_e32 v41, v50
	v_mov_b32_e32 v50, v43
	v_mov_b32_e32 v42, v44
	s_waitcnt lgkmcnt(2)
	v_mov_b32_e32 v43, v52
	v_mov_b32_e32 v52, v45
	v_mov_b32_e32 v44, v46
	v_mov_b32_e32 v45, v54
	v_mov_b32_e32 v54, v47
	v_add_u32_e32 v6, 32, v6
	s_waitcnt vmcnt(23)
	v_pk_fma_f32 v[14:15], v[80:81], v[96:97], v[14:15] op_sel_hi:[1,0,1]
	v_pk_fma_f32 v[16:17], v[30:31], v[96:97], v[16:17] op_sel_hi:[1,0,1]
	s_waitcnt lgkmcnt(1)
	v_fmac_f32_e32 v21, v56, v96
	s_waitcnt vmcnt(22)
	v_fmac_f32_e32 v21, v57, v98
	v_pk_fma_f32 v[14:15], v[32:33], v[98:99], v[14:15] op_sel_hi:[1,0,1]
	v_pk_fma_f32 v[16:17], v[48:49], v[98:99], v[16:17] op_sel_hi:[1,0,1]
	s_waitcnt vmcnt(21)
	v_fmac_f32_e32 v21, v58, v100
	v_pk_fma_f32 v[14:15], v[24:25], v[100:101], v[14:15] op_sel_hi:[1,0,1]
	v_pk_fma_f32 v[16:17], v[40:41], v[100:101], v[16:17] op_sel_hi:[1,0,1]
	s_waitcnt vmcnt(20)
	v_fmac_f32_e32 v21, v59, v102
	v_pk_fma_f32 v[14:15], v[34:35], v[102:103], v[14:15] op_sel_hi:[1,0,1]
	v_pk_fma_f32 v[16:17], v[50:51], v[102:103], v[16:17] op_sel_hi:[1,0,1]
	s_waitcnt vmcnt(19) lgkmcnt(0)
	v_fmac_f32_e32 v21, v60, v104
	v_pk_fma_f32 v[14:15], v[26:27], v[104:105], v[14:15] op_sel_hi:[1,0,1]
	v_pk_fma_f32 v[16:17], v[42:43], v[104:105], v[16:17] op_sel_hi:[1,0,1]
	s_waitcnt vmcnt(18)
	v_fmac_f32_e32 v21, v61, v106
	v_pk_fma_f32 v[14:15], v[36:37], v[106:107], v[14:15] op_sel_hi:[1,0,1]
	v_pk_fma_f32 v[16:17], v[52:53], v[106:107], v[16:17] op_sel_hi:[1,0,1]
	s_waitcnt vmcnt(17)
	v_fmac_f32_e32 v21, v62, v108
	v_pk_fma_f32 v[14:15], v[28:29], v[108:109], v[14:15] op_sel_hi:[1,0,1]
	v_pk_fma_f32 v[16:17], v[44:45], v[108:109], v[16:17] op_sel_hi:[1,0,1]
	s_waitcnt vmcnt(16)
	v_pk_fma_f32 v[14:15], v[38:39], v[110:111], v[14:15] op_sel_hi:[1,0,1]
	v_pk_fma_f32 v[16:17], v[54:55], v[110:111], v[16:17] op_sel_hi:[1,0,1]
	v_fmac_f32_e32 v21, v63, v110
	ds_read_b128 v[24:27], v6
	ds_read_b128 v[28:31], v6 offset:16
	ds_read_b128 v[32:35], v6 offset:8192
	ds_read_b128 v[36:39], v6 offset:8208
	ds_read_b128 v[40:43], v6 offset:16384
	ds_read_b128 v[44:47], v6 offset:16400
	ds_read_b128 v[48:51], v6 offset:24576
	ds_read_b128 v[52:55], v6 offset:24592
	ds_read_b128 v[56:59], v6 offset:32768
	ds_read_b128 v[60:63], v6 offset:32784
	s_waitcnt lgkmcnt(9)
	v_mov_b32_e32 v80, v24
	s_waitcnt lgkmcnt(7)
	v_mov_b32_e32 v81, v32
	v_mov_b32_e32 v32, v25
	v_mov_b32_e32 v24, v26
	v_mov_b32_e32 v25, v34
	v_mov_b32_e32 v34, v27
	v_mov_b32_e32 v26, v28
	s_waitcnt lgkmcnt(6)
	v_mov_b32_e32 v27, v36
	v_mov_b32_e32 v36, v29
	v_mov_b32_e32 v28, v30
	v_mov_b32_e32 v29, v38
	v_mov_b32_e32 v38, v31
	s_waitcnt lgkmcnt(5)
	v_mov_b32_e32 v30, v40
	s_waitcnt lgkmcnt(3)
	v_mov_b32_e32 v31, v48
	v_mov_b32_e32 v48, v41
	v_mov_b32_e32 v40, v42
	v_mov_b32_e32 v41, v50
	v_mov_b32_e32 v50, v43
	v_mov_b32_e32 v42, v44
	s_waitcnt lgkmcnt(2)
	v_mov_b32_e32 v43, v52
	v_mov_b32_e32 v52, v45
	v_mov_b32_e32 v44, v46
	v_mov_b32_e32 v45, v54
	v_mov_b32_e32 v54, v47
	v_add_u32_e32 v6, 32, v6
	s_waitcnt vmcnt(15)
	v_pk_fma_f32 v[14:15], v[80:81], v[112:113], v[14:15] op_sel_hi:[1,0,1]
	v_pk_fma_f32 v[16:17], v[30:31], v[112:113], v[16:17] op_sel_hi:[1,0,1]
	s_waitcnt lgkmcnt(1)
	v_fmac_f32_e32 v21, v56, v112
	s_waitcnt vmcnt(14)
	v_fmac_f32_e32 v21, v57, v114
	v_pk_fma_f32 v[14:15], v[32:33], v[114:115], v[14:15] op_sel_hi:[1,0,1]
	v_pk_fma_f32 v[16:17], v[48:49], v[114:115], v[16:17] op_sel_hi:[1,0,1]
	s_waitcnt vmcnt(13)
	v_fmac_f32_e32 v21, v58, v116
	v_pk_fma_f32 v[14:15], v[24:25], v[116:117], v[14:15] op_sel_hi:[1,0,1]
	v_pk_fma_f32 v[16:17], v[40:41], v[116:117], v[16:17] op_sel_hi:[1,0,1]
	s_waitcnt vmcnt(12)
	v_fmac_f32_e32 v21, v59, v118
	v_pk_fma_f32 v[14:15], v[34:35], v[118:119], v[14:15] op_sel_hi:[1,0,1]
	v_pk_fma_f32 v[16:17], v[50:51], v[118:119], v[16:17] op_sel_hi:[1,0,1]
	s_waitcnt vmcnt(11) lgkmcnt(0)
	v_fmac_f32_e32 v21, v60, v120
	v_pk_fma_f32 v[14:15], v[26:27], v[120:121], v[14:15] op_sel_hi:[1,0,1]
	v_pk_fma_f32 v[16:17], v[42:43], v[120:121], v[16:17] op_sel_hi:[1,0,1]
	s_waitcnt vmcnt(10)
	v_fmac_f32_e32 v21, v61, v122
	v_pk_fma_f32 v[14:15], v[36:37], v[122:123], v[14:15] op_sel_hi:[1,0,1]
	v_pk_fma_f32 v[16:17], v[52:53], v[122:123], v[16:17] op_sel_hi:[1,0,1]
	s_waitcnt vmcnt(9)
	v_fmac_f32_e32 v21, v62, v124
	v_pk_fma_f32 v[14:15], v[28:29], v[124:125], v[14:15] op_sel_hi:[1,0,1]
	v_pk_fma_f32 v[16:17], v[44:45], v[124:125], v[16:17] op_sel_hi:[1,0,1]
	s_waitcnt vmcnt(8)
	v_pk_fma_f32 v[14:15], v[38:39], v[126:127], v[14:15] op_sel_hi:[1,0,1]
	v_pk_fma_f32 v[16:17], v[54:55], v[126:127], v[16:17] op_sel_hi:[1,0,1]
	v_fmac_f32_e32 v21, v63, v126
	ds_read_b128 v[24:27], v6
	ds_read_b128 v[28:31], v6 offset:16
	ds_read_b128 v[32:35], v6 offset:8192
	ds_read_b128 v[36:39], v6 offset:8208
	ds_read_b128 v[40:43], v6 offset:16384
	ds_read_b128 v[44:47], v6 offset:16400
	ds_read_b128 v[48:51], v6 offset:24576
	ds_read_b128 v[52:55], v6 offset:24592
	ds_read_b128 v[56:59], v6 offset:32768
	ds_read_b128 v[60:63], v6 offset:32784
	s_waitcnt lgkmcnt(9)
	v_mov_b32_e32 v80, v24
	s_waitcnt lgkmcnt(7)
	v_mov_b32_e32 v81, v32
	v_mov_b32_e32 v32, v25
	v_mov_b32_e32 v24, v26
	v_mov_b32_e32 v25, v34
	v_mov_b32_e32 v34, v27
	v_mov_b32_e32 v26, v28
	s_waitcnt lgkmcnt(6)
	v_mov_b32_e32 v27, v36
	v_mov_b32_e32 v36, v29
	v_mov_b32_e32 v28, v30
	v_mov_b32_e32 v29, v38
	v_mov_b32_e32 v38, v31
	s_waitcnt lgkmcnt(5)
	v_mov_b32_e32 v30, v40
	s_waitcnt lgkmcnt(3)
	v_mov_b32_e32 v31, v48
	v_mov_b32_e32 v48, v41
	v_mov_b32_e32 v40, v42
	v_mov_b32_e32 v41, v50
	v_mov_b32_e32 v50, v43
	v_mov_b32_e32 v42, v44
	s_waitcnt lgkmcnt(2)
	v_mov_b32_e32 v43, v52
	v_mov_b32_e32 v52, v45
	v_mov_b32_e32 v44, v46
	v_mov_b32_e32 v45, v54
	v_mov_b32_e32 v54, v47
	v_add_u32_e32 v6, 32, v6
	s_waitcnt vmcnt(7)
	v_pk_fma_f32 v[14:15], v[80:81], v[128:129], v[14:15] op_sel_hi:[1,0,1]
	v_pk_fma_f32 v[16:17], v[30:31], v[128:129], v[16:17] op_sel_hi:[1,0,1]
	s_waitcnt lgkmcnt(1)
	v_fmac_f32_e32 v21, v56, v128
	s_waitcnt vmcnt(6)
	v_fmac_f32_e32 v21, v57, v130
	v_pk_fma_f32 v[14:15], v[32:33], v[130:131], v[14:15] op_sel_hi:[1,0,1]
	v_pk_fma_f32 v[16:17], v[48:49], v[130:131], v[16:17] op_sel_hi:[1,0,1]
	s_waitcnt vmcnt(5)
	v_fmac_f32_e32 v21, v58, v132
	v_pk_fma_f32 v[14:15], v[24:25], v[132:133], v[14:15] op_sel_hi:[1,0,1]
	v_pk_fma_f32 v[16:17], v[40:41], v[132:133], v[16:17] op_sel_hi:[1,0,1]
	s_waitcnt vmcnt(4)
	v_fmac_f32_e32 v21, v59, v134
	v_pk_fma_f32 v[14:15], v[34:35], v[134:135], v[14:15] op_sel_hi:[1,0,1]
	v_pk_fma_f32 v[16:17], v[50:51], v[134:135], v[16:17] op_sel_hi:[1,0,1]
	s_waitcnt vmcnt(3) lgkmcnt(0)
	v_fmac_f32_e32 v21, v60, v136
	v_pk_fma_f32 v[14:15], v[26:27], v[136:137], v[14:15] op_sel_hi:[1,0,1]
	v_pk_fma_f32 v[16:17], v[42:43], v[136:137], v[16:17] op_sel_hi:[1,0,1]
	s_waitcnt vmcnt(2)
	v_fmac_f32_e32 v21, v61, v138
	v_pk_fma_f32 v[14:15], v[36:37], v[138:139], v[14:15] op_sel_hi:[1,0,1]
	v_pk_fma_f32 v[16:17], v[52:53], v[138:139], v[16:17] op_sel_hi:[1,0,1]
	s_waitcnt vmcnt(1)
	v_fmac_f32_e32 v21, v62, v140
	v_pk_fma_f32 v[14:15], v[28:29], v[140:141], v[14:15] op_sel_hi:[1,0,1]
	v_pk_fma_f32 v[16:17], v[44:45], v[140:141], v[16:17] op_sel_hi:[1,0,1]
	s_waitcnt vmcnt(0)
	v_pk_fma_f32 v[14:15], v[38:39], v[142:143], v[14:15] op_sel_hi:[1,0,1]
	v_pk_fma_f32 v[16:17], v[54:55], v[142:143], v[16:17] op_sel_hi:[1,0,1]
	v_fmac_f32_e32 v21, v63, v142
	s_or_b64 exec, exec, s[16:17]
	v_add_u32_e32 v6, 0xa000, v19
	ds_write2_b32 v6, v14, v15 offset1:32
	ds_write2_b32 v6, v16, v17 offset0:64 offset1:96
	ds_write_b32 v19, v21 offset:41472
	s_waitcnt lgkmcnt(0)
	s_barrier
	s_and_saveexec_b64 s[16:17], s[4:5]
	s_cbranch_execz .LBB0_98
	s_load_dwordx2 s[22:23], s[6:7], 0x28
	s_mul_i32 s21, s20, 0x3000
	s_add_i32 s21, s21, s14
	v_or_b32_e32 v12, s21, v8
	v_ashrrev_i32_e32 v13, 31, v12
	s_waitcnt lgkmcnt(0)
	v_lshl_add_u64 v[12:13], v[12:13], 2, s[22:23]
	global_load_dword v21, v[12:13], off
	v_add_u32_e32 v16, v3, v1
	v_mad_u64_u32 v[12:13], s[20:21], s20, 5, v[2:3]
	v_mov_b64_e32 v[14:15], s[10:11]
	v_add_u32_e32 v17, 0xa000, v16
	v_add_u32_e32 v22, 0xa400, v16
	v_add_u32_e32 v23, 0xaa00, v16
	v_add_u32_e32 v24, 0xae00, v16
	v_add_u32_e32 v26, 0xb400, v16
	v_add_u32_e32 v28, 0xb800, v16
	v_add_u32_e32 v30, 0xbe00, v16
	v_add_u32_e32 v32, 0xc200, v16
	v_mad_i64_i32 v[12:13], s[20:21], v12, s18, v[14:15]
	ds_read2_b32 v[14:15], v17 offset1:160
	ds_read2_b32 v[16:17], v22 offset0:64 offset1:224
	ds_read2_b32 v[22:23], v23 offset1:160
	ds_read2_b32 v[24:25], v24 offset0:64 offset1:224
	ds_read2_b32 v[26:27], v26 offset1:160
	ds_read2_b32 v[28:29], v28 offset0:64 offset1:224
	ds_read2_b32 v[30:31], v30 offset1:160
	ds_read2_b32 v[32:33], v32 offset0:64 offset1:224
	s_waitcnt lgkmcnt(7)
	v_add_f32_e32 v14, 0, v14
	v_add_f32_e32 v14, v14, v15
	s_waitcnt lgkmcnt(6)
	v_add_f32_e32 v14, v14, v16
	v_add_f32_e32 v14, v14, v17
	s_waitcnt lgkmcnt(5)
	v_add_f32_e32 v14, v14, v22
	v_add_f32_e32 v14, v14, v23
	s_waitcnt lgkmcnt(4)
	v_add_f32_e32 v14, v14, v24
	v_add_f32_e32 v14, v14, v25
	s_waitcnt lgkmcnt(3)
	v_add_f32_e32 v14, v14, v26
	v_add_f32_e32 v14, v14, v27
	s_waitcnt lgkmcnt(2)
	v_add_f32_e32 v14, v14, v28
	v_add_f32_e32 v14, v14, v29
	s_waitcnt lgkmcnt(1)
	v_add_f32_e32 v14, v14, v30
	v_add_f32_e32 v14, v14, v31
	s_waitcnt lgkmcnt(0)
	v_add_f32_e32 v14, v14, v32
	v_lshlrev_b32_e32 v6, 2, v8
	v_lshl_add_u64 v[12:13], s[14:15], 2, v[12:13]
	v_add_f32_e32 v14, v14, v33
	v_lshl_add_u64 v[12:13], v[12:13], 0, v[6:7]
	s_waitcnt vmcnt(0)
	v_add_f32_e32 v14, v14, v21
	global_store_dword v[12:13], v14, off
	s_branch .LBB0_98

.LBB0_106:
	v_mul_hi_i32 v3, v7, s38
	v_lshrrev_b32_e32 v4, 31, v3
	v_ashrrev_i32_e32 v3, 10, v3
	v_add_u32_e32 v12, v3, v4
	v_mul_i32_i24_e32 v3, 0x5b10, v12
	v_sub_u32_e32 v3, v7, v3
	v_cmp_lt_i32_e32 vcc, s39, v3
	s_and_saveexec_b64 s[24:25], vcc
	s_xor_b64 s[24:25], exec, s[24:25]
	s_cbranch_execz .LBB0_140
	v_cmp_lt_u32_e32 vcc, s40, v3
	s_and_saveexec_b64 s[26:27], vcc
	s_xor_b64 s[26:27], exec, s[26:27]
	s_cbranch_execz .LBB0_135
	v_cmp_lt_u32_e32 vcc, s41, v3
	s_and_saveexec_b64 s[28:29], vcc
	s_xor_b64 s[28:29], exec, s[28:29]
	s_cbranch_execz .LBB0_130
	v_cmp_lt_u32_e32 vcc, s42, v3
	s_and_saveexec_b64 s[30:31], vcc
	s_xor_b64 s[30:31], exec, s[30:31]
	s_cbranch_execz .LBB0_125
	v_cmp_lt_u32_e32 vcc, s43, v3
	s_and_saveexec_b64 s[34:35], vcc
	s_xor_b64 s[34:35], exec, s[34:35]
	s_cbranch_execz .LBB0_120
	v_cmp_lt_u32_e32 vcc, s44, v3
	s_and_saveexec_b64 s[36:37], vcc
	s_xor_b64 s[36:37], exec, s[36:37]
	s_cbranch_execz .LBB0_115
	s_load_dwordx2 s[58:59], s[6:7], 0x60
	v_add_u32_e32 v3, 0xffffa530, v3
	v_ashrrev_i32_e32 v13, 31, v12
	v_lshlrev_b32_e32 v4, 5, v3
	v_lshlrev_b64 v[14:15], 19, v[12:13]
	v_and_b32_e32 v11, 0x3e0, v4
	s_waitcnt lgkmcnt(0)
	v_lshl_add_u64 v[16:17], s[58:59], 0, v[14:15]
	v_lshlrev_b32_e32 v3, 1, v3
	v_lshlrev_b32_e32 v4, 2, v11
	v_and_b32_e32 v14, 0x7fffffc0, v3
	v_lshl_add_u64 v[16:17], v[16:17], 0, v[4:5]
	v_mov_b32_e32 v9, v5
	s_mov_b32 s58, 1
	v_lshl_add_u64 v[16:17], v[16:17], 0, v[8:9]
	v_mov_b32_e32 v3, v14
	s_mov_b32 s59, 0
	s_mov_b32 s60, 32
	v_mov_b32_e32 v105, v5
	s_lshl_b32 s61, s58, 1
	s_lshl_b32 s62, s59, 1
	v_or_b32_e32 v113, s62, v2
	s_add_i32 s63, s61, 4
	s_add_i32 s64, s62, 4
	s_add_i32 s66, s62, 8
	v_add_u32_e32 v104, v113, v14
	v_or_b32_e32 v115, s63, v1
	v_or_b32_e32 v129, s64, v2
	v_mov_b32_e32 v131, v5
	v_or_b32_e32 v109, s61, v1
	s_add_i32 s68, s62, 12
	v_or_b32_e32 v151, s66, v2
	v_lshlrev_b64 v[144:145], 12, v[104:105]
	v_add_u32_e32 v130, v115, v3
	v_add_u32_e32 v104, v129, v14
	v_mov_b32_e32 v119, v5
	s_add_i32 s65, s61, 8
	s_add_i32 s67, s61, 12
	s_add_i32 s70, s62, 16
	v_add_u32_e32 v118, v109, v3
	v_or_b32_e32 v153, s68, v2
	v_lshlrev_b64 v[130:131], 12, v[130:131]
	v_lshlrev_b64 v[146:147], 12, v[104:105]
	v_add_u32_e32 v104, v151, v14
	s_add_i32 s72, s62, 20
	v_or_b32_e32 v150, s65, v1
	v_or_b32_e32 v152, s67, v1
	v_or_b32_e32 v155, s70, v2
	v_lshlrev_b64 v[118:119], 12, v[118:119]
	v_lshl_add_u64 v[144:145], v[16:17], 0, v[144:145]
	v_lshl_add_u64 v[130:131], v[16:17], 0, v[130:131]
	v_lshlrev_b64 v[148:149], 12, v[104:105]
	v_add_u32_e32 v104, v153, v14
	v_mov_b32_e32 v133, v5
	v_mov_b32_e32 v135, v5
	s_add_i32 s69, s61, 16
	s_add_i32 s71, s61, 20
	s_add_i32 s74, s62, 24
	v_or_b32_e32 v157, s72, v2
	v_add_u32_e32 v132, v150, v3
	v_add_u32_e32 v134, v152, v3
	v_lshl_add_u64 v[118:119], v[16:17], 0, v[118:119]
	v_lshl_add_u64 v[146:147], v[16:17], 0, v[146:147]
	global_load_dword v162, v[144:145], off nt
	global_load_dword v163, v[118:119], off nt
	global_load_dword v164, v[146:147], off nt
	global_load_dword v165, v[130:131], off nt
	v_lshlrev_b64 v[130:131], 12, v[104:105]
	v_add_u32_e32 v104, v155, v14
	s_add_i32 s73, s61, 24
	s_add_i32 s61, s61, 28
	s_add_i32 s62, s62, 28
	v_or_b32_e32 v154, s69, v1
	v_or_b32_e32 v156, s71, v1
	v_or_b32_e32 v159, s74, v2
	v_lshlrev_b64 v[132:133], 12, v[132:133]
	v_lshlrev_b64 v[134:135], 12, v[134:135]
	v_lshl_add_u64 v[118:119], v[16:17], 0, v[148:149]
	v_lshl_add_u64 v[130:131], v[16:17], 0, v[130:131]
	v_lshlrev_b64 v[144:145], 12, v[104:105]
	v_add_u32_e32 v104, v157, v14
	v_mov_b32_e32 v137, v5
	v_mov_b32_e32 v139, v5
	v_or_b32_e32 v158, s73, v1
	v_or_b32_e32 v160, s61, v1
	v_or_b32_e32 v161, s62, v2
	v_add_u32_e32 v136, v154, v3
	v_add_u32_e32 v138, v156, v3
	v_lshl_add_u64 v[132:133], v[16:17], 0, v[132:133]
	v_lshl_add_u64 v[134:135], v[16:17], 0, v[134:135]
	global_load_dword v166, v[118:119], off nt
	global_load_dword v167, v[132:133], off nt
	global_load_dword v168, v[130:131], off nt
	global_load_dword v169, v[134:135], off nt
	v_lshlrev_b64 v[130:131], 12, v[104:105]
	v_add_u32_e32 v104, v159, v14
	v_mov_b32_e32 v141, v5
	v_mov_b32_e32 v143, v5
	v_add_u32_e32 v140, v158, v3
	v_add_u32_e32 v142, v160, v3
	v_lshlrev_b64 v[136:137], 12, v[136:137]
	v_lshlrev_b64 v[138:139], 12, v[138:139]
	v_lshl_add_u64 v[118:119], v[16:17], 0, v[144:145]
	v_lshl_add_u64 v[130:131], v[16:17], 0, v[130:131]
	v_lshlrev_b64 v[132:133], 12, v[104:105]
	v_add_u32_e32 v104, v161, v14
	v_lshlrev_b64 v[140:141], 12, v[140:141]
	v_lshlrev_b64 v[142:143], 12, v[142:143]
	v_lshl_add_u64 v[136:137], v[16:17], 0, v[136:137]
	v_lshl_add_u64 v[138:139], v[16:17], 0, v[138:139]
	global_load_dword v170, v[118:119], off nt
	global_load_dword v171, v[136:137], off nt
	global_load_dword v172, v[130:131], off nt
	global_load_dword v173, v[138:139], off nt
	v_lshl_add_u64 v[118:119], v[16:17], 0, v[132:133]
	v_lshlrev_b64 v[130:131], 12, v[104:105]
	v_lshl_add_u64 v[140:141], v[16:17], 0, v[140:141]
	v_lshl_add_u64 v[142:143], v[16:17], 0, v[142:143]
	v_lshl_add_u64 v[130:131], v[16:17], 0, v[130:131]
	global_load_dword v104, v[118:119], off nt
	global_load_dword v174, v[140:141], off nt
	global_load_dword v175, v[130:131], off nt
	global_load_dword v176, v[142:143], off nt
	s_add_i32 s59, s59, 16
	s_add_i32 s58, s58, 16
	s_add_i32 s60, s60, -16
	v_mad_u64_u32 v[118:119], s[62:63], v113, s33, v[6:7]
	v_mad_u64_u32 v[130:131], s[62:63], v109, s33, v[6:7]
	v_mad_u64_u32 v[132:133], s[62:63], v129, s33, v[6:7]
	v_mad_u64_u32 v[134:135], s[62:63], v115, s33, v[6:7]
	v_mad_u64_u32 v[136:137], s[62:63], v151, s33, v[6:7]
	v_mad_u64_u32 v[138:139], s[62:63], v150, s33, v[6:7]
	v_mad_u64_u32 v[140:141], s[62:63], v153, s33, v[6:7]
	v_mad_u64_u32 v[142:143], s[62:63], v152, s33, v[6:7]
	v_mad_u64_u32 v[144:145], s[62:63], v155, s33, v[6:7]
	v_mad_u64_u32 v[146:147], s[62:63], v154, s33, v[6:7]
	v_mad_u64_u32 v[148:149], s[62:63], v157, s33, v[6:7]
	v_mad_u64_u32 v[150:151], s[62:63], v156, s33, v[6:7]
	v_mad_u64_u32 v[152:153], s[62:63], v159, s33, v[6:7]
	v_mad_u64_u32 v[154:155], s[62:63], v158, s33, v[6:7]
	v_mad_u64_u32 v[156:157], s[62:63], v161, s33, v[6:7]
	v_mad_u64_u32 v[158:159], s[62:63], v160, s33, v[6:7]
	s_lshl_b32 s61, s58, 1
	s_lshl_b32 s62, s59, 1
	v_or_b32_e32 v13, s62, v2
	s_add_i32 s63, s61, 4
	s_add_i32 s64, s62, 4
	s_add_i32 s66, s62, 8
	v_add_u32_e32 v4, v13, v14
	v_or_b32_e32 v15, s63, v1
	v_or_b32_e32 v29, s64, v2
	v_mov_b32_e32 v31, v5
	v_or_b32_e32 v9, s61, v1
	s_add_i32 s68, s62, 12
	v_or_b32_e32 v51, s66, v2
	v_lshlrev_b64 v[44:45], 12, v[4:5]
	v_add_u32_e32 v30, v15, v3
	v_add_u32_e32 v4, v29, v14
	v_mov_b32_e32 v19, v5
	s_add_i32 s65, s61, 8
	s_add_i32 s67, s61, 12
	s_add_i32 s70, s62, 16
	v_add_u32_e32 v18, v9, v3
	v_or_b32_e32 v53, s68, v2
	v_lshlrev_b64 v[30:31], 12, v[30:31]
	v_lshlrev_b64 v[46:47], 12, v[4:5]
	v_add_u32_e32 v4, v51, v14
	s_add_i32 s72, s62, 20
	v_or_b32_e32 v50, s65, v1
	v_or_b32_e32 v52, s67, v1
	v_or_b32_e32 v55, s70, v2
	v_lshlrev_b64 v[18:19], 12, v[18:19]
	v_lshl_add_u64 v[44:45], v[16:17], 0, v[44:45]
	v_lshl_add_u64 v[30:31], v[16:17], 0, v[30:31]
	v_lshlrev_b64 v[48:49], 12, v[4:5]
	v_add_u32_e32 v4, v53, v14
	v_mov_b32_e32 v33, v5
	v_mov_b32_e32 v35, v5
	s_add_i32 s69, s61, 16
	s_add_i32 s71, s61, 20
	s_add_i32 s74, s62, 24
	v_or_b32_e32 v57, s72, v2
	v_add_u32_e32 v32, v50, v3
	v_add_u32_e32 v34, v52, v3
	v_lshl_add_u64 v[18:19], v[16:17], 0, v[18:19]
	v_lshl_add_u64 v[46:47], v[16:17], 0, v[46:47]
	global_load_dword v62, v[44:45], off nt
	global_load_dword v63, v[18:19], off nt
	global_load_dword v64, v[46:47], off nt
	global_load_dword v65, v[30:31], off nt
	v_lshlrev_b64 v[30:31], 12, v[4:5]
	v_add_u32_e32 v4, v55, v14
	s_add_i32 s73, s61, 24
	s_add_i32 s61, s61, 28
	s_add_i32 s62, s62, 28
	v_or_b32_e32 v54, s69, v1
	v_or_b32_e32 v56, s71, v1
	v_or_b32_e32 v59, s74, v2
	v_lshlrev_b64 v[32:33], 12, v[32:33]
	v_lshlrev_b64 v[34:35], 12, v[34:35]
	v_lshl_add_u64 v[18:19], v[16:17], 0, v[48:49]
	v_lshl_add_u64 v[30:31], v[16:17], 0, v[30:31]
	v_lshlrev_b64 v[44:45], 12, v[4:5]
	v_add_u32_e32 v4, v57, v14
	v_mov_b32_e32 v37, v5
	v_mov_b32_e32 v39, v5
	v_or_b32_e32 v58, s73, v1
	v_or_b32_e32 v60, s61, v1
	v_or_b32_e32 v61, s62, v2
	v_add_u32_e32 v36, v54, v3
	v_add_u32_e32 v38, v56, v3
	v_lshl_add_u64 v[32:33], v[16:17], 0, v[32:33]
	v_lshl_add_u64 v[34:35], v[16:17], 0, v[34:35]
	global_load_dword v66, v[18:19], off nt
	global_load_dword v67, v[32:33], off nt
	global_load_dword v68, v[30:31], off nt
	global_load_dword v69, v[34:35], off nt
	v_lshlrev_b64 v[30:31], 12, v[4:5]
	v_add_u32_e32 v4, v59, v14
	v_mov_b32_e32 v41, v5
	v_mov_b32_e32 v43, v5
	v_add_u32_e32 v40, v58, v3
	v_add_u32_e32 v42, v60, v3
	v_lshlrev_b64 v[36:37], 12, v[36:37]
	v_lshlrev_b64 v[38:39], 12, v[38:39]
	v_lshl_add_u64 v[18:19], v[16:17], 0, v[44:45]
	v_lshl_add_u64 v[30:31], v[16:17], 0, v[30:31]
	v_lshlrev_b64 v[32:33], 12, v[4:5]
	v_add_u32_e32 v4, v61, v14
	v_lshlrev_b64 v[40:41], 12, v[40:41]
	v_lshlrev_b64 v[42:43], 12, v[42:43]
	v_lshl_add_u64 v[36:37], v[16:17], 0, v[36:37]
	v_lshl_add_u64 v[38:39], v[16:17], 0, v[38:39]
	global_load_dword v70, v[18:19], off nt
	global_load_dword v71, v[36:37], off nt
	global_load_dword v72, v[30:31], off nt
	global_load_dword v73, v[38:39], off nt
	v_lshl_add_u64 v[18:19], v[16:17], 0, v[32:33]
	v_lshlrev_b64 v[30:31], 12, v[4:5]
	v_lshl_add_u64 v[40:41], v[16:17], 0, v[40:41]
	v_lshl_add_u64 v[42:43], v[16:17], 0, v[42:43]
	v_lshl_add_u64 v[30:31], v[16:17], 0, v[30:31]
	global_load_dword v4, v[18:19], off nt
	global_load_dword v74, v[40:41], off nt
	global_load_dword v75, v[30:31], off nt
	global_load_dword v76, v[42:43], off nt
	s_add_i32 s59, s59, 16
	s_add_i32 s58, s58, 16
	s_add_i32 s60, s60, -16
	v_mad_u64_u32 v[18:19], s[62:63], v13, s33, v[6:7]
	v_mad_u64_u32 v[30:31], s[62:63], v9, s33, v[6:7]
	v_mad_u64_u32 v[32:33], s[62:63], v29, s33, v[6:7]
	v_mad_u64_u32 v[34:35], s[62:63], v15, s33, v[6:7]
	v_mad_u64_u32 v[36:37], s[62:63], v51, s33, v[6:7]
	v_mad_u64_u32 v[38:39], s[62:63], v50, s33, v[6:7]
	v_mad_u64_u32 v[40:41], s[62:63], v53, s33, v[6:7]
	v_mad_u64_u32 v[42:43], s[62:63], v52, s33, v[6:7]
	v_mad_u64_u32 v[44:45], s[62:63], v55, s33, v[6:7]
	v_mad_u64_u32 v[46:47], s[62:63], v54, s33, v[6:7]
	v_mad_u64_u32 v[48:49], s[62:63], v57, s33, v[6:7]
	v_mad_u64_u32 v[50:51], s[62:63], v56, s33, v[6:7]
	v_mad_u64_u32 v[52:53], s[62:63], v59, s33, v[6:7]
	v_mad_u64_u32 v[54:55], s[62:63], v58, s33, v[6:7]
	v_mad_u64_u32 v[56:57], s[62:63], v61, s33, v[6:7]
	v_mad_u64_u32 v[58:59], s[62:63], v60, s33, v[6:7]
	s_waitcnt vmcnt(31)
	ds_write_b32 v118, v162
	s_waitcnt vmcnt(30)
	ds_write_b32 v130, v163
	s_waitcnt vmcnt(29)
	ds_write_b32 v132, v164
	s_waitcnt vmcnt(28)
	ds_write_b32 v134, v165
	s_waitcnt vmcnt(27)
	ds_write_b32 v136, v166
	s_waitcnt vmcnt(26)
	ds_write_b32 v138, v167
	s_waitcnt vmcnt(25)
	ds_write_b32 v140, v168
	s_waitcnt vmcnt(24)
	ds_write_b32 v142, v169
	s_waitcnt vmcnt(23)
	ds_write_b32 v144, v170
	s_waitcnt vmcnt(22)
	ds_write_b32 v146, v171
	s_waitcnt vmcnt(21)
	ds_write_b32 v148, v172
	s_waitcnt vmcnt(20)
	ds_write_b32 v150, v173
	s_waitcnt vmcnt(19)
	ds_write_b32 v152, v104
	s_waitcnt vmcnt(18)
	ds_write_b32 v154, v174
	s_waitcnt vmcnt(17)
	ds_write_b32 v156, v175
	s_waitcnt vmcnt(16)
	ds_write_b32 v158, v176
	s_waitcnt vmcnt(15)
	ds_write_b32 v18, v62
	s_waitcnt vmcnt(14)
	ds_write_b32 v30, v63
	s_waitcnt vmcnt(13)
	ds_write_b32 v32, v64
	s_waitcnt vmcnt(12)
	ds_write_b32 v34, v65
	s_waitcnt vmcnt(11)
	ds_write_b32 v36, v66
	s_waitcnt vmcnt(10)
	ds_write_b32 v38, v67
	s_waitcnt vmcnt(9)
	ds_write_b32 v40, v68
	s_waitcnt vmcnt(8)
	ds_write_b32 v42, v69
	s_waitcnt vmcnt(7)
	ds_write_b32 v44, v70
	s_waitcnt vmcnt(6)
	ds_write_b32 v46, v71
	s_waitcnt vmcnt(5)
	ds_write_b32 v48, v72
	s_waitcnt vmcnt(4)
	ds_write_b32 v50, v73
	s_waitcnt vmcnt(3)
	ds_write_b32 v52, v4
	s_waitcnt vmcnt(2)
	ds_write_b32 v54, v74
	s_waitcnt vmcnt(1)
	ds_write_b32 v56, v75
	s_waitcnt vmcnt(0)
	ds_write_b32 v58, v76
	s_waitcnt lgkmcnt(0)
	ds_read2_b32 v[16:17], v22 offset1:8
	ds_read2_b32 v[30:31], v22 offset0:33 offset1:41
	v_mul_hi_i32_i24_e32 v13, 0x1c0000, v12
	v_mul_i32_i24_e32 v12, 0x1c0000, v12
	ds_read2_b32 v[32:33], v22 offset0:66 offset1:74
	v_lshl_add_u64 v[12:13], s[8:9], 0, v[12:13]
	v_lshlrev_b32_e32 v4, 1, v14
	ds_read2_b32 v[34:35], v22 offset0:99 offset1:107
	v_lshl_add_u64 v[12:13], v[12:13], 0, v[4:5]
	s_waitcnt lgkmcnt(3)
	v_bfe_u32 v4, v16, 16, 1
	v_add_u32_e32 v3, 0x300, v11
	v_mov_b32_e32 v11, v5
	v_add3_u32 v4, v16, v4, s45
	s_waitcnt lgkmcnt(2)
	v_bfe_u32 v9, v30, 16, 1
	ds_read2_b32 v[36:37], v22 offset0:132 offset1:140
	v_lshl_add_u64 v[12:13], v[12:13], 0, v[10:11]
	v_lshrrev_b32_e32 v4, 16, v4
	v_add3_u32 v9, v30, v9, s45
	ds_read2_b32 v[38:39], v22 offset0:165 offset1:173
	v_lshl_add_u64 v[18:19], v[12:13], 0, s[22:23]
	v_and_or_b32 v12, v9, s46, v4
	s_waitcnt lgkmcnt(3)
	v_bfe_u32 v4, v32, 16, 1
	v_add3_u32 v4, v32, v4, s45
	s_waitcnt lgkmcnt(2)
	v_bfe_u32 v9, v34, 16, 1
	ds_read2_b32 v[40:41], v22 offset0:198 offset1:206
	v_lshrrev_b32_e32 v4, 16, v4
	v_add3_u32 v9, v34, v9, s45
	ds_read2_b32 v[42:43], v22 offset0:231 offset1:239
	v_and_or_b32 v13, v9, s46, v4
	s_waitcnt lgkmcnt(3)
	v_bfe_u32 v4, v36, 16, 1
	v_add3_u32 v4, v36, v4, s45
	s_waitcnt lgkmcnt(2)
	v_bfe_u32 v9, v38, 16, 1
	v_lshrrev_b32_e32 v4, 16, v4
	v_add3_u32 v9, v38, v9, s45
	v_and_or_b32 v14, v9, s46, v4
	s_waitcnt lgkmcnt(1)
	v_bfe_u32 v4, v40, 16, 1
	v_add3_u32 v4, v40, v4, s45
	s_waitcnt lgkmcnt(0)
	v_bfe_u32 v9, v42, 16, 1
	v_lshrrev_b32_e32 v4, 16, v4
	v_add3_u32 v9, v42, v9, s45
	v_and_or_b32 v15, v9, s46, v4
	v_or_b32_e32 v4, v3, v21
	v_lshlrev_b32_e32 v4, 10, v4
	v_lshl_add_u64 v[44:45], v[18:19], 0, v[4:5]
	v_bfe_u32 v4, v17, 16, 1
	v_add3_u32 v4, v17, v4, s45
	v_bfe_u32 v9, v31, 16, 1
	v_lshrrev_b32_e32 v4, 16, v4
	v_add3_u32 v9, v31, v9, s45
	global_store_dwordx4 v[44:45], v[12:15], off
	ds_read2_b32 v[16:17], v22 offset0:16 offset1:24
	v_readlane_b32 s66, v253, 1
	v_and_or_b32 v12, v9, s46, v4
	v_bfe_u32 v4, v33, 16, 1
	v_add3_u32 v4, v33, v4, s45
	v_bfe_u32 v9, v35, 16, 1
	v_lshrrev_b32_e32 v4, 16, v4
	v_add3_u32 v9, v35, v9, s45
	v_and_or_b32 v13, v9, s46, v4
	v_bfe_u32 v4, v37, 16, 1
	v_add3_u32 v4, v37, v4, s45
	v_bfe_u32 v9, v39, 16, 1
	v_lshrrev_b32_e32 v4, 16, v4
	v_add3_u32 v9, v39, v9, s45
	v_and_or_b32 v14, v9, s46, v4
	v_bfe_u32 v4, v41, 16, 1
	v_add3_u32 v4, v41, v4, s45
	v_bfe_u32 v9, v43, 16, 1
	v_lshrrev_b32_e32 v4, 16, v4
	v_add3_u32 v9, v43, v9, s45
	v_and_or_b32 v15, v9, s46, v4
	v_or_b32_e32 v4, v3, v23
	v_lshlrev_b32_e32 v4, 10, v4
	v_lshl_add_u64 v[30:31], v[18:19], 0, v[4:5]
	global_store_dwordx4 v[30:31], v[12:15], off
	ds_read2_b32 v[30:31], v22 offset0:49 offset1:57
	ds_read2_b32 v[32:33], v22 offset0:82 offset1:90
	ds_read2_b32 v[34:35], v22 offset0:115 offset1:123
	s_waitcnt lgkmcnt(3)
	v_bfe_u32 v4, v16, 16, 1
	v_add3_u32 v4, v16, v4, s45
	s_waitcnt lgkmcnt(2)
	v_bfe_u32 v9, v30, 16, 1
	ds_read2_b32 v[36:37], v22 offset0:148 offset1:156
	v_lshrrev_b32_e32 v4, 16, v4
	v_add3_u32 v9, v30, v9, s45
	ds_read2_b32 v[38:39], v22 offset0:181 offset1:189
	v_and_or_b32 v12, v9, s46, v4
	s_waitcnt lgkmcnt(3)
	v_bfe_u32 v4, v32, 16, 1
	v_add3_u32 v4, v32, v4, s45
	s_waitcnt lgkmcnt(2)
	v_bfe_u32 v9, v34, 16, 1
	ds_read2_b32 v[40:41], v22 offset0:214 offset1:222
	v_lshrrev_b32_e32 v4, 16, v4
	v_add3_u32 v9, v34, v9, s45
	ds_read2_b32 v[42:43], v22 offset0:247 offset1:255
	v_and_or_b32 v13, v9, s46, v4
	s_waitcnt lgkmcnt(3)
	v_bfe_u32 v4, v36, 16, 1
	v_add3_u32 v4, v36, v4, s45
	s_waitcnt lgkmcnt(2)
	v_bfe_u32 v9, v38, 16, 1
	v_lshrrev_b32_e32 v4, 16, v4
	v_add3_u32 v9, v38, v9, s45
	v_and_or_b32 v14, v9, s46, v4
	s_waitcnt lgkmcnt(1)
	v_bfe_u32 v4, v40, 16, 1
	v_add3_u32 v4, v40, v4, s45
	s_waitcnt lgkmcnt(0)
	v_bfe_u32 v9, v42, 16, 1
	v_lshrrev_b32_e32 v4, 16, v4
	v_add3_u32 v9, v42, v9, s45
	v_and_or_b32 v15, v9, s46, v4
	v_or_b32_e32 v4, v3, v24
	v_lshlrev_b32_e32 v4, 10, v4
	v_lshl_add_u64 v[44:45], v[18:19], 0, v[4:5]
	v_bfe_u32 v4, v17, 16, 1
	v_add3_u32 v4, v17, v4, s45
	v_bfe_u32 v9, v31, 16, 1
	v_lshrrev_b32_e32 v4, 16, v4
	v_add3_u32 v9, v31, v9, s45
	global_store_dwordx4 v[44:45], v[12:15], off
	v_or_b32_e32 v3, v3, v25
	s_nop 0
	v_and_or_b32 v12, v9, s46, v4
	v_bfe_u32 v4, v33, 16, 1
	v_add3_u32 v4, v33, v4, s45
	v_bfe_u32 v9, v35, 16, 1
	v_lshrrev_b32_e32 v4, 16, v4
	v_add3_u32 v9, v35, v9, s45
	v_and_or_b32 v13, v9, s46, v4
	v_bfe_u32 v4, v37, 16, 1
	v_add3_u32 v4, v37, v4, s45
	v_bfe_u32 v9, v39, 16, 1
	v_lshrrev_b32_e32 v4, 16, v4
	v_add3_u32 v9, v39, v9, s45
	v_and_or_b32 v14, v9, s46, v4
	v_bfe_u32 v4, v41, 16, 1
	v_add3_u32 v4, v41, v4, s45
	v_bfe_u32 v9, v43, 16, 1
	v_lshrrev_b32_e32 v4, 16, v4
	v_add3_u32 v9, v43, v9, s45
	v_and_or_b32 v15, v9, s46, v4
	v_lshlrev_b32_e32 v4, 10, v3
	v_lshl_add_u64 v[16:17], v[18:19], 0, v[4:5]
	global_store_dwordx4 v[16:17], v[12:15], off
	s_waitcnt lgkmcnt(0)
.LBB0_115:
	s_andn2_saveexec_b64 s[36:37], s[36:37]
	s_cbranch_execz .LBB0_119
	v_subrev_u16_e32 v3, 64, v3
	s_load_dwordx2 s[58:59], s[6:7], 0x58
	v_mul_lo_u16_sdwa v4, v3, s47 dst_sel:DWORD dst_unused:UNUSED_PAD src0_sel:BYTE_0 src1_sel:DWORD
	v_lshrrev_b16_e32 v4, 12, v4
	v_mul_lo_u16_e32 v9, 24, v4
	v_sub_u16_e32 v3, v3, v9
	v_mul_hi_i32_i24_e32 v15, 0x120000, v12
	v_mul_i32_i24_e32 v14, 0x120000, v12
	s_waitcnt lgkmcnt(0)
	v_lshl_add_u64 v[16:17], s[58:59], 0, v[14:15]
	v_lshlrev_b32_e32 v14, 6, v4
	v_lshlrev_b32_sdwa v4, v27, v3 dst_sel:DWORD dst_unused:UNUSED_PAD src0_sel:DWORD src1_sel:BYTE_0
	v_lshl_add_u64 v[16:17], v[16:17], 0, v[4:5]
	v_mov_b32_e32 v9, v5
	v_lshlrev_b32_sdwa v13, v26, v3 dst_sel:DWORD dst_unused:UNUSED_PAD src0_sel:DWORD src1_sel:BYTE_0
	v_lshl_add_u64 v[16:17], v[16:17], 0, v[8:9]
	v_mov_b32_e32 v3, v14
	s_mov_b32 s58, 1
	s_mov_b32 s59, 0
	s_mov_b32 s60, 32
	s_lshl_b32 s61, s58, 1
	s_lshl_b32 s62, s59, 1
	v_or_b32_e32 v104, s61, v1
	v_or_b32_e32 v109, s62, v2
	s_add_i32 s63, s61, 4
	s_add_i32 s64, s62, 4
	s_add_i32 s65, s61, 8
	s_add_i32 s66, s62, 8
	s_add_i32 s67, s61, 12
	s_add_i32 s68, s62, 12
	s_add_i32 s69, s61, 16
	s_add_i32 s70, s62, 16
	s_add_i32 s71, s61, 20
	s_add_i32 s72, s62, 20
	s_add_i32 s73, s61, 24
	s_add_i32 s74, s62, 24
	s_add_i32 s61, s61, 28
	s_add_i32 s62, s62, 28
	v_add_u32_e32 v111, v104, v3
	v_add_u32_e32 v115, v109, v14
	v_or_b32_e32 v129, s63, v1
	v_or_b32_e32 v160, s64, v2
	v_or_b32_e32 v161, s65, v1
	v_or_b32_e32 v162, s66, v2
	v_or_b32_e32 v163, s67, v1
	v_or_b32_e32 v164, s68, v2
	v_or_b32_e32 v165, s69, v1
	v_or_b32_e32 v166, s70, v2
	v_or_b32_e32 v167, s71, v1
	v_or_b32_e32 v168, s72, v2
	v_or_b32_e32 v169, s73, v1
	v_or_b32_e32 v170, s74, v2
	v_or_b32_e32 v171, s61, v1
	v_or_b32_e32 v172, s62, v2
	v_mad_u64_u32 v[118:119], s[62:63], v115, s48, v[16:17]
	v_mad_u64_u32 v[130:131], s[62:63], v111, s48, v[16:17]
	v_add_u32_e32 v111, v129, v3
	v_add_u32_e32 v115, v160, v14
	v_add_u32_e32 v138, v161, v3
	v_add_u32_e32 v136, v162, v14
	v_add_u32_e32 v142, v163, v3
	v_add_u32_e32 v140, v164, v14
	v_add_u32_e32 v146, v165, v3
	v_add_u32_e32 v144, v166, v14
	v_add_u32_e32 v150, v167, v3
	v_add_u32_e32 v148, v168, v14
	v_add_u32_e32 v154, v169, v3
	v_add_u32_e32 v152, v170, v14
	v_add_u32_e32 v158, v171, v3
	v_add_u32_e32 v156, v172, v14
	v_mad_u64_u32 v[132:133], s[62:63], v115, s48, v[16:17]
	v_mad_u64_u32 v[134:135], s[62:63], v111, s48, v[16:17]
	v_mad_u64_u32 v[136:137], s[62:63], v136, s48, v[16:17]
	v_mad_u64_u32 v[138:139], s[62:63], v138, s48, v[16:17]
	v_mad_u64_u32 v[140:141], s[62:63], v140, s48, v[16:17]
	v_mad_u64_u32 v[142:143], s[62:63], v142, s48, v[16:17]
	v_mad_u64_u32 v[144:145], s[62:63], v144, s48, v[16:17]
	v_mad_u64_u32 v[146:147], s[62:63], v146, s48, v[16:17]
	v_mad_u64_u32 v[148:149], s[62:63], v148, s48, v[16:17]
	v_mad_u64_u32 v[150:151], s[62:63], v150, s48, v[16:17]
	v_mad_u64_u32 v[152:153], s[62:63], v152, s48, v[16:17]
	v_mad_u64_u32 v[154:155], s[62:63], v154, s48, v[16:17]
	v_mad_u64_u32 v[156:157], s[62:63], v156, s48, v[16:17]
	v_mad_u64_u32 v[158:159], s[62:63], v158, s48, v[16:17]
	global_load_dword v111, v[118:119], off nt
	global_load_dword v115, v[130:131], off nt
	global_load_dword v173, v[132:133], off nt
	global_load_dword v174, v[134:135], off nt
	global_load_dword v175, v[136:137], off nt
	global_load_dword v176, v[138:139], off nt
	global_load_dword v177, v[140:141], off nt
	global_load_dword v178, v[142:143], off nt
	global_load_dword v179, v[144:145], off nt
	global_load_dword v180, v[146:147], off nt
	global_load_dword v181, v[148:149], off nt
	global_load_dword v182, v[150:151], off nt
	global_load_dword v183, v[152:153], off nt
	global_load_dword v184, v[154:155], off nt
	global_load_dword v185, v[156:157], off nt
	global_load_dword v186, v[158:159], off nt
	s_add_i32 s59, s59, 16
	s_add_i32 s58, s58, 16
	s_add_i32 s60, s60, -16
	v_mad_u64_u32 v[118:119], s[62:63], v109, s33, v[6:7]
	v_mad_u64_u32 v[130:131], s[62:63], v104, s33, v[6:7]
	v_mad_u64_u32 v[132:133], s[62:63], v160, s33, v[6:7]
	v_mad_u64_u32 v[134:135], s[62:63], v129, s33, v[6:7]
	v_mad_u64_u32 v[136:137], s[62:63], v162, s33, v[6:7]
	v_mad_u64_u32 v[138:139], s[62:63], v161, s33, v[6:7]
	v_mad_u64_u32 v[140:141], s[62:63], v164, s33, v[6:7]
	v_mad_u64_u32 v[142:143], s[62:63], v163, s33, v[6:7]
	v_mad_u64_u32 v[144:145], s[62:63], v166, s33, v[6:7]
	v_mad_u64_u32 v[146:147], s[62:63], v165, s33, v[6:7]
	v_mad_u64_u32 v[148:149], s[62:63], v168, s33, v[6:7]
	v_mad_u64_u32 v[150:151], s[62:63], v167, s33, v[6:7]
	v_mad_u64_u32 v[152:153], s[62:63], v170, s33, v[6:7]
	v_mad_u64_u32 v[154:155], s[62:63], v169, s33, v[6:7]
	v_mad_u64_u32 v[156:157], s[62:63], v172, s33, v[6:7]
	v_mad_u64_u32 v[158:159], s[62:63], v171, s33, v[6:7]
	s_lshl_b32 s61, s58, 1
	s_lshl_b32 s62, s59, 1
	v_or_b32_e32 v4, s61, v1
	v_or_b32_e32 v9, s62, v2
	s_add_i32 s63, s61, 4
	s_add_i32 s64, s62, 4
	s_add_i32 s65, s61, 8
	s_add_i32 s66, s62, 8
	s_add_i32 s67, s61, 12
	s_add_i32 s68, s62, 12
	s_add_i32 s69, s61, 16
	s_add_i32 s70, s62, 16
	s_add_i32 s71, s61, 20
	s_add_i32 s72, s62, 20
	s_add_i32 s73, s61, 24
	s_add_i32 s74, s62, 24
	s_add_i32 s61, s61, 28
	s_add_i32 s62, s62, 28
	v_add_u32_e32 v11, v4, v3
	v_add_u32_e32 v15, v9, v14
	v_or_b32_e32 v29, s63, v1
	v_or_b32_e32 v60, s64, v2
	v_or_b32_e32 v61, s65, v1
	v_or_b32_e32 v62, s66, v2
	v_or_b32_e32 v63, s67, v1
	v_or_b32_e32 v64, s68, v2
	v_or_b32_e32 v65, s69, v1
	v_or_b32_e32 v66, s70, v2
	v_or_b32_e32 v67, s71, v1
	v_or_b32_e32 v68, s72, v2
	v_or_b32_e32 v69, s73, v1
	v_or_b32_e32 v70, s74, v2
	v_or_b32_e32 v71, s61, v1
	v_or_b32_e32 v72, s62, v2
	v_mad_u64_u32 v[18:19], s[62:63], v15, s48, v[16:17]
	v_mad_u64_u32 v[30:31], s[62:63], v11, s48, v[16:17]
	v_add_u32_e32 v11, v29, v3
	v_add_u32_e32 v15, v60, v14
	v_add_u32_e32 v38, v61, v3
	v_add_u32_e32 v36, v62, v14
	v_add_u32_e32 v42, v63, v3
	v_add_u32_e32 v40, v64, v14
	v_add_u32_e32 v46, v65, v3
	v_add_u32_e32 v44, v66, v14
	v_add_u32_e32 v50, v67, v3
	v_add_u32_e32 v48, v68, v14
	v_add_u32_e32 v54, v69, v3
	v_add_u32_e32 v52, v70, v14
	v_add_u32_e32 v58, v71, v3
	v_add_u32_e32 v56, v72, v14
	v_mad_u64_u32 v[32:33], s[62:63], v15, s48, v[16:17]
	v_mad_u64_u32 v[34:35], s[62:63], v11, s48, v[16:17]
	v_mad_u64_u32 v[36:37], s[62:63], v36, s48, v[16:17]
	v_mad_u64_u32 v[38:39], s[62:63], v38, s48, v[16:17]
	v_mad_u64_u32 v[40:41], s[62:63], v40, s48, v[16:17]
	v_mad_u64_u32 v[42:43], s[62:63], v42, s48, v[16:17]
	v_mad_u64_u32 v[44:45], s[62:63], v44, s48, v[16:17]
	v_mad_u64_u32 v[46:47], s[62:63], v46, s48, v[16:17]
	v_mad_u64_u32 v[48:49], s[62:63], v48, s48, v[16:17]
	v_mad_u64_u32 v[50:51], s[62:63], v50, s48, v[16:17]
	v_mad_u64_u32 v[52:53], s[62:63], v52, s48, v[16:17]
	v_mad_u64_u32 v[54:55], s[62:63], v54, s48, v[16:17]
	v_mad_u64_u32 v[56:57], s[62:63], v56, s48, v[16:17]
	v_mad_u64_u32 v[58:59], s[62:63], v58, s48, v[16:17]
	global_load_dword v11, v[18:19], off nt
	global_load_dword v15, v[30:31], off nt
	global_load_dword v73, v[32:33], off nt
	global_load_dword v74, v[34:35], off nt
	global_load_dword v75, v[36:37], off nt
	global_load_dword v76, v[38:39], off nt
	global_load_dword v77, v[40:41], off nt
	global_load_dword v78, v[42:43], off nt
	global_load_dword v79, v[44:45], off nt
	global_load_dword v80, v[46:47], off nt
	global_load_dword v81, v[48:49], off nt
	global_load_dword v82, v[50:51], off nt
	global_load_dword v83, v[52:53], off nt
	global_load_dword v84, v[54:55], off nt
	global_load_dword v85, v[56:57], off nt
	global_load_dword v86, v[58:59], off nt
	s_add_i32 s59, s59, 16
	s_add_i32 s58, s58, 16
	s_add_i32 s60, s60, -16
	v_mad_u64_u32 v[18:19], s[62:63], v9, s33, v[6:7]
	v_mad_u64_u32 v[30:31], s[62:63], v4, s33, v[6:7]
	v_mad_u64_u32 v[32:33], s[62:63], v60, s33, v[6:7]
	v_mad_u64_u32 v[34:35], s[62:63], v29, s33, v[6:7]
	v_mad_u64_u32 v[36:37], s[62:63], v62, s33, v[6:7]
	v_mad_u64_u32 v[38:39], s[62:63], v61, s33, v[6:7]
	v_mad_u64_u32 v[40:41], s[62:63], v64, s33, v[6:7]
	v_mad_u64_u32 v[42:43], s[62:63], v63, s33, v[6:7]
	v_mad_u64_u32 v[44:45], s[62:63], v66, s33, v[6:7]
	v_mad_u64_u32 v[46:47], s[62:63], v65, s33, v[6:7]
	v_mad_u64_u32 v[48:49], s[62:63], v68, s33, v[6:7]
	v_mad_u64_u32 v[50:51], s[62:63], v67, s33, v[6:7]
	v_mad_u64_u32 v[52:53], s[62:63], v70, s33, v[6:7]
	v_mad_u64_u32 v[54:55], s[62:63], v69, s33, v[6:7]
	v_mad_u64_u32 v[56:57], s[62:63], v72, s33, v[6:7]
	v_mad_u64_u32 v[58:59], s[62:63], v71, s33, v[6:7]
	s_waitcnt vmcnt(31)
	ds_write_b32 v118, v111
	s_waitcnt vmcnt(30)
	ds_write_b32 v130, v115
	s_waitcnt vmcnt(29)
	ds_write_b32 v132, v173
	s_waitcnt vmcnt(28)
	ds_write_b32 v134, v174
	s_waitcnt vmcnt(27)
	ds_write_b32 v136, v175
	s_waitcnt vmcnt(26)
	ds_write_b32 v138, v176
	s_waitcnt vmcnt(25)
	ds_write_b32 v140, v177
	s_waitcnt vmcnt(24)
	ds_write_b32 v142, v178
	s_waitcnt vmcnt(23)
	ds_write_b32 v144, v179
	s_waitcnt vmcnt(22)
	ds_write_b32 v146, v180
	s_waitcnt vmcnt(21)
	ds_write_b32 v148, v181
	s_waitcnt vmcnt(20)
	ds_write_b32 v150, v182
	s_waitcnt vmcnt(19)
	ds_write_b32 v152, v183
	s_waitcnt vmcnt(18)
	ds_write_b32 v154, v184
	s_waitcnt vmcnt(17)
	ds_write_b32 v156, v185
	s_waitcnt vmcnt(16)
	ds_write_b32 v158, v186
	s_waitcnt vmcnt(15)
	ds_write_b32 v18, v11
	s_waitcnt vmcnt(14)
	ds_write_b32 v30, v15
	s_waitcnt vmcnt(13)
	ds_write_b32 v32, v73
	s_waitcnt vmcnt(12)
	ds_write_b32 v34, v74
	s_waitcnt vmcnt(11)
	ds_write_b32 v36, v75
	s_waitcnt vmcnt(10)
	ds_write_b32 v38, v76
	s_waitcnt vmcnt(9)
	ds_write_b32 v40, v77
	s_waitcnt vmcnt(8)
	ds_write_b32 v42, v78
	s_waitcnt vmcnt(7)
	ds_write_b32 v44, v79
	s_waitcnt vmcnt(6)
	ds_write_b32 v46, v80
	s_waitcnt vmcnt(5)
	ds_write_b32 v48, v81
	s_waitcnt vmcnt(4)
	ds_write_b32 v50, v82
	s_waitcnt vmcnt(3)
	ds_write_b32 v52, v83
	s_waitcnt vmcnt(2)
	ds_write_b32 v54, v84
	s_waitcnt vmcnt(1)
	ds_write_b32 v56, v85
	s_waitcnt vmcnt(0)
	ds_write_b32 v58, v86
	s_waitcnt lgkmcnt(0)
	ds_read2_b32 v[18:19], v22 offset1:8
	ds_read2_b32 v[32:33], v22 offset0:33 offset1:41
	ds_read2_b32 v[34:35], v22 offset0:66 offset1:74
	v_mul_hi_i32_i24_e32 v17, 0x1c0000, v12
	v_mul_i32_i24_e32 v16, 0x1c0000, v12
	ds_read2_b32 v[36:37], v22 offset0:99 offset1:107
	v_lshl_add_u64 v[16:17], s[10:11], 0, v[16:17]
	v_lshlrev_b32_e32 v4, 1, v14
	s_waitcnt lgkmcnt(3)
	v_bfe_u32 v3, v18, 16, 1
	v_lshl_add_u64 v[14:15], v[16:17], 0, v[4:5]
	v_add3_u32 v3, v18, v3, s45
	s_waitcnt lgkmcnt(2)
	v_bfe_u32 v4, v32, 16, 1
	ds_read2_b32 v[38:39], v22 offset0:132 offset1:140
	v_mov_b32_e32 v11, v5
	v_lshrrev_b32_e32 v3, 16, v3
	v_add3_u32 v4, v32, v4, s45
	ds_read2_b32 v[40:41], v22 offset0:165 offset1:173
	v_lshl_add_u64 v[30:31], v[14:15], 0, v[10:11]
	v_and_or_b32 v14, v4, s46, v3
	s_waitcnt lgkmcnt(3)
	v_bfe_u32 v3, v34, 16, 1
	v_add3_u32 v3, v34, v3, s45
	s_waitcnt lgkmcnt(2)
	v_bfe_u32 v4, v36, 16, 1
	ds_read2_b32 v[42:43], v22 offset0:198 offset1:206
	v_lshrrev_b32_e32 v3, 16, v3
	v_add3_u32 v4, v36, v4, s45
	ds_read2_b32 v[44:45], v22 offset0:231 offset1:239
	v_and_or_b32 v15, v4, s46, v3
	s_waitcnt lgkmcnt(3)
	v_bfe_u32 v3, v38, 16, 1
	v_add3_u32 v3, v38, v3, s45
	s_waitcnt lgkmcnt(2)
	v_bfe_u32 v4, v40, 16, 1
	v_lshrrev_b32_e32 v3, 16, v3
	v_add3_u32 v4, v40, v4, s45
	v_and_or_b32 v16, v4, s46, v3
	s_waitcnt lgkmcnt(1)
	v_bfe_u32 v3, v42, 16, 1
	v_add3_u32 v3, v42, v3, s45
	s_waitcnt lgkmcnt(0)
	v_bfe_u32 v4, v44, 16, 1
	v_lshrrev_b32_e32 v3, 16, v3
	v_add3_u32 v4, v44, v4, s45
	v_and_or_b32 v17, v4, s46, v3
	v_or_b32_e32 v3, v13, v21
	v_lshlrev_b32_e32 v4, 10, v3
	v_bfe_u32 v3, v19, 16, 1
	v_lshl_add_u64 v[46:47], v[30:31], 0, v[4:5]
	v_add3_u32 v3, v19, v3, s45
	v_bfe_u32 v4, v33, 16, 1
	v_lshrrev_b32_e32 v3, 16, v3
	v_add3_u32 v4, v33, v4, s45
	global_store_dwordx4 v[46:47], v[14:17], off
	ds_read2_b32 v[18:19], v22 offset0:16 offset1:24
	v_readlane_b32 s66, v253, 1
	v_and_or_b32 v14, v4, s46, v3
	v_bfe_u32 v3, v35, 16, 1
	v_add3_u32 v3, v35, v3, s45
	v_bfe_u32 v4, v37, 16, 1
	v_lshrrev_b32_e32 v3, 16, v3
	v_add3_u32 v4, v37, v4, s45
	v_and_or_b32 v15, v4, s46, v3
	v_bfe_u32 v3, v39, 16, 1
	v_add3_u32 v3, v39, v3, s45
	v_bfe_u32 v4, v41, 16, 1
	v_lshrrev_b32_e32 v3, 16, v3
	v_add3_u32 v4, v41, v4, s45
	v_and_or_b32 v16, v4, s46, v3
	v_bfe_u32 v3, v43, 16, 1
	v_add3_u32 v3, v43, v3, s45
	v_bfe_u32 v4, v45, 16, 1
	v_lshrrev_b32_e32 v3, 16, v3
	v_add3_u32 v4, v45, v4, s45
	v_and_or_b32 v17, v4, s46, v3
	v_or_b32_e32 v3, v13, v23
	v_lshlrev_b32_e32 v4, 10, v3
	v_lshl_add_u64 v[32:33], v[30:31], 0, v[4:5]
	global_store_dwordx4 v[32:33], v[14:17], off
	ds_read2_b32 v[32:33], v22 offset0:49 offset1:57
	ds_read2_b32 v[34:35], v22 offset0:82 offset1:90
	ds_read2_b32 v[36:37], v22 offset0:115 offset1:123
	s_waitcnt lgkmcnt(3)
	v_bfe_u32 v3, v18, 16, 1
	v_add3_u32 v3, v18, v3, s45
	s_waitcnt lgkmcnt(2)
	v_bfe_u32 v4, v32, 16, 1
	ds_read2_b32 v[38:39], v22 offset0:148 offset1:156
	v_lshrrev_b32_e32 v3, 16, v3
	v_add3_u32 v4, v32, v4, s45
	ds_read2_b32 v[40:41], v22 offset0:181 offset1:189
	v_and_or_b32 v14, v4, s46, v3
	s_waitcnt lgkmcnt(3)
	v_bfe_u32 v3, v34, 16, 1
	v_add3_u32 v3, v34, v3, s45
	s_waitcnt lgkmcnt(2)
	v_bfe_u32 v4, v36, 16, 1
	ds_read2_b32 v[42:43], v22 offset0:214 offset1:222
	v_lshrrev_b32_e32 v3, 16, v3
	v_add3_u32 v4, v36, v4, s45
	ds_read2_b32 v[44:45], v22 offset0:247 offset1:255
	v_and_or_b32 v15, v4, s46, v3
	s_waitcnt lgkmcnt(3)
	v_bfe_u32 v3, v38, 16, 1
	v_add3_u32 v3, v38, v3, s45
	s_waitcnt lgkmcnt(2)
	v_bfe_u32 v4, v40, 16, 1
	v_lshrrev_b32_e32 v3, 16, v3
	v_add3_u32 v4, v40, v4, s45
	v_and_or_b32 v16, v4, s46, v3
	s_waitcnt lgkmcnt(1)
	v_bfe_u32 v3, v42, 16, 1
	v_add3_u32 v3, v42, v3, s45
	s_waitcnt lgkmcnt(0)
	v_bfe_u32 v4, v44, 16, 1
	v_lshrrev_b32_e32 v3, 16, v3
	v_add3_u32 v4, v44, v4, s45
	v_and_or_b32 v17, v4, s46, v3
	v_or_b32_e32 v3, v13, v24
	v_lshlrev_b32_e32 v4, 10, v3
	v_bfe_u32 v3, v19, 16, 1
	v_lshl_add_u64 v[46:47], v[30:31], 0, v[4:5]
	v_add3_u32 v3, v19, v3, s45
	v_bfe_u32 v4, v33, 16, 1
	v_lshrrev_b32_e32 v3, 16, v3
	v_add3_u32 v4, v33, v4, s45
	global_store_dwordx4 v[46:47], v[14:17], off
	s_nop 1
	v_and_or_b32 v14, v4, s46, v3
	v_bfe_u32 v3, v35, 16, 1
	v_add3_u32 v3, v35, v3, s45
	v_bfe_u32 v4, v37, 16, 1
	v_lshrrev_b32_e32 v3, 16, v3
	v_add3_u32 v4, v37, v4, s45
	v_and_or_b32 v15, v4, s46, v3
	v_bfe_u32 v3, v39, 16, 1
	v_add3_u32 v3, v39, v3, s45
	v_bfe_u32 v4, v41, 16, 1
	v_lshrrev_b32_e32 v3, 16, v3
	v_add3_u32 v4, v41, v4, s45
	v_and_or_b32 v16, v4, s46, v3
	v_bfe_u32 v3, v43, 16, 1
	v_add3_u32 v3, v43, v3, s45
	v_bfe_u32 v4, v45, 16, 1
	v_lshrrev_b32_e32 v3, 16, v3
	v_add3_u32 v4, v45, v4, s45
	v_and_or_b32 v17, v4, s46, v3
	v_or_b32_e32 v3, v13, v25
	v_lshlrev_b32_e32 v4, 10, v3
	v_lshl_add_u64 v[12:13], v[30:31], 0, v[4:5]
	global_store_dwordx4 v[12:13], v[14:17], off
	s_waitcnt lgkmcnt(0)

.LBB0_120:
	s_andn2_saveexec_b64 s[34:35], s[34:35]
	s_cbranch_execz .LBB0_124
	s_load_dwordx2 s[36:37], s[6:7], 0xb0
	v_and_b32_e32 v4, 0x7fc0, v3
	v_lshlrev_b32_e32 v3, 5, v3
	v_and_b32_e32 v13, 0x7e0, v3
	v_add_u32_e32 v14, 0xffffbbc0, v4
	s_waitcnt lgkmcnt(0)
	v_mov_b64_e32 v[16:17], s[36:37]
	v_mad_i64_i32 v[16:17], s[36:37], v12, s49, v[16:17]
	v_lshlrev_b32_e32 v4, 2, v13
	v_lshl_add_u64 v[16:17], v[16:17], 0, v[4:5]
	v_mov_b32_e32 v9, v5
	v_lshl_add_u64 v[16:17], v[16:17], 0, v[8:9]
	v_mov_b32_e32 v3, v14
	s_mov_b32 s36, 1
	s_mov_b32 s37, 0
	s_mov_b32 s58, 32
	s_lshl_b32 s59, s36, 1
	s_lshl_b32 s60, s37, 1
	v_or_b32_e32 v104, s59, v1
	v_or_b32_e32 v109, s60, v2
	s_add_i32 s61, s59, 4
	s_add_i32 s62, s60, 4
	s_add_i32 s63, s59, 8
	s_add_i32 s64, s60, 8
	s_add_i32 s65, s59, 12
	s_add_i32 s66, s60, 12
	s_add_i32 s67, s59, 16
	s_add_i32 s68, s60, 16
	s_add_i32 s69, s59, 20
	s_add_i32 s70, s60, 20
	s_add_i32 s71, s59, 24
	s_add_i32 s72, s60, 24
	s_add_i32 s59, s59, 28
	s_add_i32 s60, s60, 28
	v_add_u32_e32 v130, v109, v14
	v_or_b32_e32 v111, s61, v1
	v_or_b32_e32 v115, s62, v2
	v_or_b32_e32 v129, s63, v1
	v_or_b32_e32 v160, s64, v2
	v_or_b32_e32 v161, s65, v1
	v_or_b32_e32 v162, s66, v2
	v_or_b32_e32 v163, s67, v1
	v_or_b32_e32 v164, s68, v2
	v_or_b32_e32 v165, s69, v1
	v_or_b32_e32 v166, s70, v2
	v_or_b32_e32 v167, s71, v1
	v_or_b32_e32 v168, s72, v2
	v_or_b32_e32 v169, s59, v1
	v_or_b32_e32 v170, s60, v2
	v_add_u32_e32 v118, v104, v3
	v_ashrrev_i32_e32 v131, 31, v130
	v_add_u32_e32 v132, v111, v3
	v_add_u32_e32 v134, v115, v14
	v_add_u32_e32 v136, v129, v3
	v_add_u32_e32 v138, v160, v14
	v_add_u32_e32 v140, v161, v3
	v_add_u32_e32 v142, v162, v14
	v_add_u32_e32 v144, v163, v3
	v_add_u32_e32 v146, v164, v14
	v_add_u32_e32 v148, v165, v3
	v_add_u32_e32 v150, v166, v14
	v_add_u32_e32 v152, v167, v3
	v_add_u32_e32 v154, v168, v14
	v_add_u32_e32 v156, v169, v3
	v_add_u32_e32 v158, v170, v14
	v_ashrrev_i32_e32 v119, 31, v118
	v_lshlrev_b64 v[130:131], 13, v[130:131]
	v_ashrrev_i32_e32 v135, 31, v134
	v_ashrrev_i32_e32 v133, 31, v132
	v_ashrrev_i32_e32 v139, 31, v138
	v_ashrrev_i32_e32 v137, 31, v136
	v_ashrrev_i32_e32 v143, 31, v142
	v_ashrrev_i32_e32 v141, 31, v140
	v_ashrrev_i32_e32 v147, 31, v146
	v_ashrrev_i32_e32 v145, 31, v144
	v_ashrrev_i32_e32 v151, 31, v150
	v_ashrrev_i32_e32 v149, 31, v148
	v_ashrrev_i32_e32 v155, 31, v154
	v_ashrrev_i32_e32 v153, 31, v152
	v_ashrrev_i32_e32 v159, 31, v158
	v_ashrrev_i32_e32 v157, 31, v156
	v_lshlrev_b64 v[118:119], 13, v[118:119]
	v_lshl_add_u64 v[130:131], v[16:17], 0, v[130:131]
	v_lshlrev_b64 v[132:133], 13, v[132:133]
	v_lshlrev_b64 v[134:135], 13, v[134:135]
	v_lshlrev_b64 v[136:137], 13, v[136:137]
	v_lshlrev_b64 v[138:139], 13, v[138:139]
	v_lshlrev_b64 v[140:141], 13, v[140:141]
	v_lshlrev_b64 v[142:143], 13, v[142:143]
	v_lshlrev_b64 v[144:145], 13, v[144:145]
	v_lshlrev_b64 v[146:147], 13, v[146:147]
	v_lshlrev_b64 v[148:149], 13, v[148:149]
	v_lshlrev_b64 v[150:151], 13, v[150:151]
	v_lshlrev_b64 v[152:153], 13, v[152:153]
	v_lshlrev_b64 v[154:155], 13, v[154:155]
	v_lshlrev_b64 v[156:157], 13, v[156:157]
	v_lshlrev_b64 v[158:159], 13, v[158:159]
	v_lshl_add_u64 v[118:119], v[16:17], 0, v[118:119]
	v_lshl_add_u64 v[134:135], v[16:17], 0, v[134:135]
	v_lshl_add_u64 v[132:133], v[16:17], 0, v[132:133]
	v_lshl_add_u64 v[138:139], v[16:17], 0, v[138:139]
	v_lshl_add_u64 v[136:137], v[16:17], 0, v[136:137]
	v_lshl_add_u64 v[142:143], v[16:17], 0, v[142:143]
	v_lshl_add_u64 v[140:141], v[16:17], 0, v[140:141]
	v_lshl_add_u64 v[146:147], v[16:17], 0, v[146:147]
	v_lshl_add_u64 v[144:145], v[16:17], 0, v[144:145]
	v_lshl_add_u64 v[150:151], v[16:17], 0, v[150:151]
	v_lshl_add_u64 v[148:149], v[16:17], 0, v[148:149]
	v_lshl_add_u64 v[154:155], v[16:17], 0, v[154:155]
	v_lshl_add_u64 v[152:153], v[16:17], 0, v[152:153]
	v_lshl_add_u64 v[158:159], v[16:17], 0, v[158:159]
	v_lshl_add_u64 v[156:157], v[16:17], 0, v[156:157]
	global_load_dword v171, v[130:131], off nt
	global_load_dword v172, v[118:119], off nt
	global_load_dword v173, v[134:135], off nt
	global_load_dword v174, v[132:133], off nt
	global_load_dword v175, v[138:139], off nt
	global_load_dword v176, v[136:137], off nt
	global_load_dword v177, v[142:143], off nt
	global_load_dword v178, v[140:141], off nt
	global_load_dword v179, v[146:147], off nt
	global_load_dword v180, v[144:145], off nt
	global_load_dword v181, v[150:151], off nt
	global_load_dword v182, v[148:149], off nt
	global_load_dword v183, v[154:155], off nt
	global_load_dword v184, v[152:153], off nt
	global_load_dword v185, v[158:159], off nt
	global_load_dword v186, v[156:157], off nt
	s_add_i32 s37, s37, 16
	s_add_i32 s36, s36, 16
	s_add_i32 s58, s58, -16
	v_mad_u64_u32 v[118:119], s[60:61], v109, s33, v[6:7]
	v_mad_u64_u32 v[130:131], s[60:61], v104, s33, v[6:7]
	v_mad_u64_u32 v[132:133], s[60:61], v115, s33, v[6:7]
	v_mad_u64_u32 v[134:135], s[60:61], v111, s33, v[6:7]
	v_mad_u64_u32 v[136:137], s[60:61], v160, s33, v[6:7]
	v_mad_u64_u32 v[138:139], s[60:61], v129, s33, v[6:7]
	v_mad_u64_u32 v[140:141], s[60:61], v162, s33, v[6:7]
	v_mad_u64_u32 v[142:143], s[60:61], v161, s33, v[6:7]
	v_mad_u64_u32 v[144:145], s[60:61], v164, s33, v[6:7]
	v_mad_u64_u32 v[146:147], s[60:61], v163, s33, v[6:7]
	v_mad_u64_u32 v[148:149], s[60:61], v166, s33, v[6:7]
	v_mad_u64_u32 v[150:151], s[60:61], v165, s33, v[6:7]
	v_mad_u64_u32 v[152:153], s[60:61], v168, s33, v[6:7]
	v_mad_u64_u32 v[154:155], s[60:61], v167, s33, v[6:7]
	v_mad_u64_u32 v[156:157], s[60:61], v170, s33, v[6:7]
	v_mad_u64_u32 v[158:159], s[60:61], v169, s33, v[6:7]
	s_lshl_b32 s59, s36, 1
	s_lshl_b32 s60, s37, 1
	v_or_b32_e32 v4, s59, v1
	v_or_b32_e32 v9, s60, v2
	s_add_i32 s61, s59, 4
	s_add_i32 s62, s60, 4
	s_add_i32 s63, s59, 8
	s_add_i32 s64, s60, 8
	s_add_i32 s65, s59, 12
	s_add_i32 s66, s60, 12
	s_add_i32 s67, s59, 16
	s_add_i32 s68, s60, 16
	s_add_i32 s69, s59, 20
	s_add_i32 s70, s60, 20
	s_add_i32 s71, s59, 24
	s_add_i32 s72, s60, 24
	s_add_i32 s59, s59, 28
	s_add_i32 s60, s60, 28
	v_add_u32_e32 v30, v9, v14
	v_or_b32_e32 v11, s61, v1
	v_or_b32_e32 v15, s62, v2
	v_or_b32_e32 v29, s63, v1
	v_or_b32_e32 v60, s64, v2
	v_or_b32_e32 v61, s65, v1
	v_or_b32_e32 v62, s66, v2
	v_or_b32_e32 v63, s67, v1
	v_or_b32_e32 v64, s68, v2
	v_or_b32_e32 v65, s69, v1
	v_or_b32_e32 v66, s70, v2
	v_or_b32_e32 v67, s71, v1
	v_or_b32_e32 v68, s72, v2
	v_or_b32_e32 v69, s59, v1
	v_or_b32_e32 v70, s60, v2
	v_add_u32_e32 v18, v4, v3
	v_ashrrev_i32_e32 v31, 31, v30
	v_add_u32_e32 v32, v11, v3
	v_add_u32_e32 v34, v15, v14
	v_add_u32_e32 v36, v29, v3
	v_add_u32_e32 v38, v60, v14
	v_add_u32_e32 v40, v61, v3
	v_add_u32_e32 v42, v62, v14
	v_add_u32_e32 v44, v63, v3
	v_add_u32_e32 v46, v64, v14
	v_add_u32_e32 v48, v65, v3
	v_add_u32_e32 v50, v66, v14
	v_add_u32_e32 v52, v67, v3
	v_add_u32_e32 v54, v68, v14
	v_add_u32_e32 v56, v69, v3
	v_add_u32_e32 v58, v70, v14
	v_ashrrev_i32_e32 v19, 31, v18
	v_lshlrev_b64 v[30:31], 13, v[30:31]
	v_ashrrev_i32_e32 v35, 31, v34
	v_ashrrev_i32_e32 v33, 31, v32
	v_ashrrev_i32_e32 v39, 31, v38
	v_ashrrev_i32_e32 v37, 31, v36
	v_ashrrev_i32_e32 v43, 31, v42
	v_ashrrev_i32_e32 v41, 31, v40
	v_ashrrev_i32_e32 v47, 31, v46
	v_ashrrev_i32_e32 v45, 31, v44
	v_ashrrev_i32_e32 v51, 31, v50
	v_ashrrev_i32_e32 v49, 31, v48
	v_ashrrev_i32_e32 v55, 31, v54
	v_ashrrev_i32_e32 v53, 31, v52
	v_ashrrev_i32_e32 v59, 31, v58
	v_ashrrev_i32_e32 v57, 31, v56
	v_lshlrev_b64 v[18:19], 13, v[18:19]
	v_lshl_add_u64 v[30:31], v[16:17], 0, v[30:31]
	v_lshlrev_b64 v[32:33], 13, v[32:33]
	v_lshlrev_b64 v[34:35], 13, v[34:35]
	v_lshlrev_b64 v[36:37], 13, v[36:37]
	v_lshlrev_b64 v[38:39], 13, v[38:39]
	v_lshlrev_b64 v[40:41], 13, v[40:41]
	v_lshlrev_b64 v[42:43], 13, v[42:43]
	v_lshlrev_b64 v[44:45], 13, v[44:45]
	v_lshlrev_b64 v[46:47], 13, v[46:47]
	v_lshlrev_b64 v[48:49], 13, v[48:49]
	v_lshlrev_b64 v[50:51], 13, v[50:51]
	v_lshlrev_b64 v[52:53], 13, v[52:53]
	v_lshlrev_b64 v[54:55], 13, v[54:55]
	v_lshlrev_b64 v[56:57], 13, v[56:57]
	v_lshlrev_b64 v[58:59], 13, v[58:59]
	v_lshl_add_u64 v[18:19], v[16:17], 0, v[18:19]
	v_lshl_add_u64 v[34:35], v[16:17], 0, v[34:35]
	v_lshl_add_u64 v[32:33], v[16:17], 0, v[32:33]
	v_lshl_add_u64 v[38:39], v[16:17], 0, v[38:39]
	v_lshl_add_u64 v[36:37], v[16:17], 0, v[36:37]
	v_lshl_add_u64 v[42:43], v[16:17], 0, v[42:43]
	v_lshl_add_u64 v[40:41], v[16:17], 0, v[40:41]
	v_lshl_add_u64 v[46:47], v[16:17], 0, v[46:47]
	v_lshl_add_u64 v[44:45], v[16:17], 0, v[44:45]
	v_lshl_add_u64 v[50:51], v[16:17], 0, v[50:51]
	v_lshl_add_u64 v[48:49], v[16:17], 0, v[48:49]
	v_lshl_add_u64 v[54:55], v[16:17], 0, v[54:55]
	v_lshl_add_u64 v[52:53], v[16:17], 0, v[52:53]
	v_lshl_add_u64 v[58:59], v[16:17], 0, v[58:59]
	v_lshl_add_u64 v[56:57], v[16:17], 0, v[56:57]
	global_load_dword v71, v[30:31], off nt
	global_load_dword v72, v[18:19], off nt
	global_load_dword v73, v[34:35], off nt
	global_load_dword v74, v[32:33], off nt
	global_load_dword v75, v[38:39], off nt
	global_load_dword v76, v[36:37], off nt
	global_load_dword v77, v[42:43], off nt
	global_load_dword v78, v[40:41], off nt
	global_load_dword v79, v[46:47], off nt
	global_load_dword v80, v[44:45], off nt
	global_load_dword v81, v[50:51], off nt
	global_load_dword v82, v[48:49], off nt
	global_load_dword v83, v[54:55], off nt
	global_load_dword v84, v[52:53], off nt
	global_load_dword v85, v[58:59], off nt
	global_load_dword v86, v[56:57], off nt
	s_add_i32 s37, s37, 16
	s_add_i32 s36, s36, 16
	s_add_i32 s58, s58, -16
	v_mad_u64_u32 v[18:19], s[60:61], v9, s33, v[6:7]
	v_mad_u64_u32 v[30:31], s[60:61], v4, s33, v[6:7]
	v_mad_u64_u32 v[32:33], s[60:61], v15, s33, v[6:7]
	v_mad_u64_u32 v[34:35], s[60:61], v11, s33, v[6:7]
	v_mad_u64_u32 v[36:37], s[60:61], v60, s33, v[6:7]
	v_mad_u64_u32 v[38:39], s[60:61], v29, s33, v[6:7]
	v_mad_u64_u32 v[40:41], s[60:61], v62, s33, v[6:7]
	v_mad_u64_u32 v[42:43], s[60:61], v61, s33, v[6:7]
	v_mad_u64_u32 v[44:45], s[60:61], v64, s33, v[6:7]
	v_mad_u64_u32 v[46:47], s[60:61], v63, s33, v[6:7]
	v_mad_u64_u32 v[48:49], s[60:61], v66, s33, v[6:7]
	v_mad_u64_u32 v[50:51], s[60:61], v65, s33, v[6:7]
	v_mad_u64_u32 v[52:53], s[60:61], v68, s33, v[6:7]
	v_mad_u64_u32 v[54:55], s[60:61], v67, s33, v[6:7]
	v_mad_u64_u32 v[56:57], s[60:61], v70, s33, v[6:7]
	v_mad_u64_u32 v[58:59], s[60:61], v69, s33, v[6:7]
	s_waitcnt vmcnt(31)
	ds_write_b32 v118, v171
	s_waitcnt vmcnt(30)
	ds_write_b32 v130, v172
	s_waitcnt vmcnt(29)
	ds_write_b32 v132, v173
	s_waitcnt vmcnt(28)
	ds_write_b32 v134, v174
	s_waitcnt vmcnt(27)
	ds_write_b32 v136, v175
	s_waitcnt vmcnt(26)
	ds_write_b32 v138, v176
	s_waitcnt vmcnt(25)
	ds_write_b32 v140, v177
	s_waitcnt vmcnt(24)
	ds_write_b32 v142, v178
	s_waitcnt vmcnt(23)
	ds_write_b32 v144, v179
	s_waitcnt vmcnt(22)
	ds_write_b32 v146, v180
	s_waitcnt vmcnt(21)
	ds_write_b32 v148, v181
	s_waitcnt vmcnt(20)
	ds_write_b32 v150, v182
	s_waitcnt vmcnt(19)
	ds_write_b32 v152, v183
	s_waitcnt vmcnt(18)
	ds_write_b32 v154, v184
	s_waitcnt vmcnt(17)
	ds_write_b32 v156, v185
	s_waitcnt vmcnt(16)
	ds_write_b32 v158, v186
	s_waitcnt vmcnt(15)
	ds_write_b32 v18, v71
	s_waitcnt vmcnt(14)
	ds_write_b32 v30, v72
	s_waitcnt vmcnt(13)
	ds_write_b32 v32, v73
	s_waitcnt vmcnt(12)
	ds_write_b32 v34, v74
	s_waitcnt vmcnt(11)
	ds_write_b32 v36, v75
	s_waitcnt vmcnt(10)
	ds_write_b32 v38, v76
	s_waitcnt vmcnt(9)
	ds_write_b32 v40, v77
	s_waitcnt vmcnt(8)
	ds_write_b32 v42, v78
	s_waitcnt vmcnt(7)
	ds_write_b32 v44, v79
	s_waitcnt vmcnt(6)
	ds_write_b32 v46, v80
	s_waitcnt vmcnt(5)
	ds_write_b32 v48, v81
	s_waitcnt vmcnt(4)
	ds_write_b32 v50, v82
	s_waitcnt vmcnt(3)
	ds_write_b32 v52, v83
	s_waitcnt vmcnt(2)
	ds_write_b32 v54, v84
	s_waitcnt vmcnt(1)
	ds_write_b32 v56, v85
	s_waitcnt vmcnt(0)
	ds_write_b32 v58, v86
	s_waitcnt lgkmcnt(0)
	ds_read2_b32 v[18:19], v22 offset1:8
	ds_read2_b32 v[32:33], v22 offset0:33 offset1:41
	ds_read2_b32 v[34:35], v22 offset0:66 offset1:74
	ds_read2_b32 v[36:37], v22 offset0:99 offset1:107
	v_mov_b64_e32 v[16:17], s[12:13]
	s_waitcnt lgkmcnt(3)
	v_bfe_u32 v3, v18, 16, 1
	v_mad_i64_i32 v[16:17], s[36:37], v12, s50, v[16:17]
	v_mov_b32_e32 v15, v5
	v_add3_u32 v3, v18, v3, s45
	s_waitcnt lgkmcnt(2)
	v_bfe_u32 v4, v32, 16, 1
	ds_read2_b32 v[38:39], v22 offset0:132 offset1:140
	v_lshl_add_u64 v[14:15], v[14:15], 1, v[16:17]
	v_mov_b32_e32 v11, v5
	v_lshrrev_b32_e32 v3, 16, v3
	v_add3_u32 v4, v32, v4, s45
	ds_read2_b32 v[40:41], v22 offset0:165 offset1:173
	v_lshl_add_u64 v[30:31], v[14:15], 0, v[10:11]
	v_and_or_b32 v14, v4, s46, v3
	s_waitcnt lgkmcnt(3)
	v_bfe_u32 v3, v34, 16, 1
	v_add3_u32 v3, v34, v3, s45
	s_waitcnt lgkmcnt(2)
	v_bfe_u32 v4, v36, 16, 1
	ds_read2_b32 v[42:43], v22 offset0:198 offset1:206
	v_lshrrev_b32_e32 v3, 16, v3
	v_add3_u32 v4, v36, v4, s45
	ds_read2_b32 v[44:45], v22 offset0:231 offset1:239
	v_and_or_b32 v15, v4, s46, v3
	s_waitcnt lgkmcnt(3)
	v_bfe_u32 v3, v38, 16, 1
	v_add3_u32 v3, v38, v3, s45
	s_waitcnt lgkmcnt(2)
	v_bfe_u32 v4, v40, 16, 1
	v_lshrrev_b32_e32 v3, 16, v3
	v_add3_u32 v4, v40, v4, s45
	v_and_or_b32 v16, v4, s46, v3
	s_waitcnt lgkmcnt(1)
	v_bfe_u32 v3, v42, 16, 1
	v_add3_u32 v3, v42, v3, s45
	s_waitcnt lgkmcnt(0)
	v_bfe_u32 v4, v44, 16, 1
	v_lshrrev_b32_e32 v3, 16, v3
	v_add3_u32 v4, v44, v4, s45
	v_and_or_b32 v17, v4, s46, v3
	v_or_b32_e32 v3, v13, v21
	v_mul_u32_u24_e32 v3, 0x1600, v3
	v_lshlrev_b32_e32 v4, 1, v3
	v_bfe_u32 v3, v19, 16, 1
	v_lshl_add_u64 v[46:47], v[30:31], 0, v[4:5]
	v_add3_u32 v3, v19, v3, s45
	v_bfe_u32 v4, v33, 16, 1
	v_lshrrev_b32_e32 v3, 16, v3
	v_add3_u32 v4, v33, v4, s45
	global_store_dwordx4 v[46:47], v[14:17], off
	ds_read2_b32 v[18:19], v22 offset0:16 offset1:24
	v_readlane_b32 s66, v253, 1
	v_and_or_b32 v14, v4, s46, v3
	v_bfe_u32 v3, v35, 16, 1
	v_add3_u32 v3, v35, v3, s45
	v_bfe_u32 v4, v37, 16, 1
	v_lshrrev_b32_e32 v3, 16, v3
	v_add3_u32 v4, v37, v4, s45
	v_and_or_b32 v15, v4, s46, v3
	v_bfe_u32 v3, v39, 16, 1
	v_add3_u32 v3, v39, v3, s45
	v_bfe_u32 v4, v41, 16, 1
	v_lshrrev_b32_e32 v3, 16, v3
	v_add3_u32 v4, v41, v4, s45
	v_and_or_b32 v16, v4, s46, v3
	v_bfe_u32 v3, v43, 16, 1
	v_add3_u32 v3, v43, v3, s45
	v_bfe_u32 v4, v45, 16, 1
	v_lshrrev_b32_e32 v3, 16, v3
	v_add3_u32 v4, v45, v4, s45
	v_and_or_b32 v17, v4, s46, v3
	v_or_b32_e32 v3, v13, v23
	v_mul_u32_u24_e32 v3, 0x1600, v3
	v_lshlrev_b32_e32 v4, 1, v3
	v_lshl_add_u64 v[32:33], v[30:31], 0, v[4:5]
	global_store_dwordx4 v[32:33], v[14:17], off
	ds_read2_b32 v[32:33], v22 offset0:49 offset1:57
	ds_read2_b32 v[34:35], v22 offset0:82 offset1:90
	ds_read2_b32 v[36:37], v22 offset0:115 offset1:123
	s_waitcnt lgkmcnt(3)
	v_bfe_u32 v3, v18, 16, 1
	v_add3_u32 v3, v18, v3, s45
	s_waitcnt lgkmcnt(2)
	v_bfe_u32 v4, v32, 16, 1
	ds_read2_b32 v[38:39], v22 offset0:148 offset1:156
	v_lshrrev_b32_e32 v3, 16, v3
	v_add3_u32 v4, v32, v4, s45
	ds_read2_b32 v[40:41], v22 offset0:181 offset1:189
	v_and_or_b32 v14, v4, s46, v3
	s_waitcnt lgkmcnt(3)
	v_bfe_u32 v3, v34, 16, 1
	v_add3_u32 v3, v34, v3, s45
	s_waitcnt lgkmcnt(2)
	v_bfe_u32 v4, v36, 16, 1
	ds_read2_b32 v[42:43], v22 offset0:214 offset1:222
	v_lshrrev_b32_e32 v3, 16, v3
	v_add3_u32 v4, v36, v4, s45
	ds_read2_b32 v[44:45], v22 offset0:247 offset1:255
	v_and_or_b32 v15, v4, s46, v3
	s_waitcnt lgkmcnt(3)
	v_bfe_u32 v3, v38, 16, 1
	v_add3_u32 v3, v38, v3, s45
	s_waitcnt lgkmcnt(2)
	v_bfe_u32 v4, v40, 16, 1
	v_lshrrev_b32_e32 v3, 16, v3
	v_add3_u32 v4, v40, v4, s45
	v_and_or_b32 v16, v4, s46, v3
	s_waitcnt lgkmcnt(1)
	v_bfe_u32 v3, v42, 16, 1
	v_add3_u32 v3, v42, v3, s45
	s_waitcnt lgkmcnt(0)
	v_bfe_u32 v4, v44, 16, 1
	v_lshrrev_b32_e32 v3, 16, v3
	v_add3_u32 v4, v44, v4, s45
	v_and_or_b32 v17, v4, s46, v3
	v_or_b32_e32 v3, v13, v24
	v_mul_u32_u24_e32 v3, 0x1600, v3
	v_lshlrev_b32_e32 v4, 1, v3
	v_bfe_u32 v3, v19, 16, 1
	v_lshl_add_u64 v[46:47], v[30:31], 0, v[4:5]
	v_add3_u32 v3, v19, v3, s45
	v_bfe_u32 v4, v33, 16, 1
	v_lshrrev_b32_e32 v3, 16, v3
	v_add3_u32 v4, v33, v4, s45
	global_store_dwordx4 v[46:47], v[14:17], off
	s_nop 1
	v_and_or_b32 v14, v4, s46, v3
	v_bfe_u32 v3, v35, 16, 1
	v_add3_u32 v3, v35, v3, s45
	v_bfe_u32 v4, v37, 16, 1
	v_lshrrev_b32_e32 v3, 16, v3
	v_add3_u32 v4, v37, v4, s45
	v_and_or_b32 v15, v4, s46, v3
	v_bfe_u32 v3, v39, 16, 1
	v_add3_u32 v3, v39, v3, s45
	v_bfe_u32 v4, v41, 16, 1
	v_lshrrev_b32_e32 v3, 16, v3
	v_add3_u32 v4, v41, v4, s45
	v_and_or_b32 v16, v4, s46, v3
	v_bfe_u32 v3, v43, 16, 1
	v_add3_u32 v3, v43, v3, s45
	v_bfe_u32 v4, v45, 16, 1
	v_lshrrev_b32_e32 v3, 16, v3
	v_add3_u32 v4, v45, v4, s45
	v_and_or_b32 v17, v4, s46, v3
	v_or_b32_e32 v3, v13, v25
	v_mul_u32_u24_e32 v3, 0x1600, v3
	v_lshlrev_b32_e32 v4, 1, v3
	v_lshl_add_u64 v[12:13], v[30:31], 0, v[4:5]
	global_store_dwordx4 v[12:13], v[14:17], off
	s_waitcnt lgkmcnt(0)

.LBB0_125:
	s_andn2_saveexec_b64 s[30:31], s[30:31]
	s_cbranch_execz .LBB0_129
	s_load_dwordx2 s[34:35], s[6:7], 0x98
	v_add_u16_e32 v3, 0xd1c0, v3
	v_mul_u32_u24_e32 v4, 0xba2f, v3
	v_lshrrev_b32_e32 v4, 23, v4
	v_mul_lo_u16_e32 v9, 0xb0, v4
	v_sub_u16_e32 v13, v3, v9
	s_waitcnt lgkmcnt(0)
	v_mov_b64_e32 v[16:17], s[34:35]
	v_mad_i64_i32 v[14:15], s[36:37], v12, s49, 0
	v_mad_i64_i32 v[16:17], s[34:35], v12, s49, v[16:17]
	v_lshlrev_b16_e32 v12, 6, v4
	v_lshlrev_b32_e32 v4, 7, v13
	v_lshl_add_u64 v[16:17], v[16:17], 0, v[4:5]
	v_mov_b32_e32 v9, v5
	v_lshlrev_b32_e32 v11, 5, v13
	v_lshl_add_u64 v[16:17], v[16:17], 0, v[8:9]
	v_mov_b32_e32 v3, v12
	s_mov_b32 s34, 1
	s_mov_b32 s35, 0
	s_mov_b32 s36, 32
	s_lshl_b32 s37, s34, 1
	s_lshl_b32 s58, s35, 1
	v_or_b32_e32 v104, s37, v1
	v_or_b32_e32 v109, s58, v2
	s_add_i32 s59, s37, 4
	s_add_i32 s60, s58, 4
	s_add_i32 s61, s37, 8
	s_add_i32 s62, s58, 8
	s_add_i32 s63, s37, 12
	s_add_i32 s64, s58, 12
	s_add_i32 s65, s37, 16
	s_add_i32 s66, s58, 16
	s_add_i32 s67, s37, 20
	s_add_i32 s68, s58, 20
	s_add_i32 s69, s37, 24
	s_add_i32 s70, s58, 24
	s_add_i32 s37, s37, 28
	s_add_i32 s58, s58, 28
	v_add_u32_e32 v129, v104, v3
	v_add_u32_e32 v118, v109, v12
	v_or_b32_e32 v160, s59, v1
	v_or_b32_e32 v161, s60, v2
	v_or_b32_e32 v162, s61, v1
	v_or_b32_e32 v163, s62, v2
	v_or_b32_e32 v164, s63, v1
	v_or_b32_e32 v165, s64, v2
	v_or_b32_e32 v166, s65, v1
	v_or_b32_e32 v167, s66, v2
	v_or_b32_e32 v168, s67, v1
	v_or_b32_e32 v169, s68, v2
	v_or_b32_e32 v170, s69, v1
	v_or_b32_e32 v171, s70, v2
	v_or_b32_e32 v172, s37, v1
	v_or_b32_e32 v173, s58, v2
	v_mad_u64_u32 v[118:119], s[58:59], v118, s51, v[16:17]
	v_mad_u64_u32 v[130:131], s[58:59], v129, s51, v[16:17]
	v_add_u32_e32 v129, v160, v3
	v_add_u32_e32 v132, v161, v12
	v_add_u32_e32 v138, v162, v3
	v_add_u32_e32 v136, v163, v12
	v_add_u32_e32 v142, v164, v3
	v_add_u32_e32 v140, v165, v12
	v_add_u32_e32 v146, v166, v3
	v_add_u32_e32 v144, v167, v12
	v_add_u32_e32 v150, v168, v3
	v_add_u32_e32 v148, v169, v12
	v_add_u32_e32 v154, v170, v3
	v_add_u32_e32 v152, v171, v12
	v_add_u32_e32 v158, v172, v3
	v_add_u32_e32 v156, v173, v12
	v_mad_u64_u32 v[132:133], s[58:59], v132, s51, v[16:17]
	v_mad_u64_u32 v[134:135], s[58:59], v129, s51, v[16:17]
	v_mad_u64_u32 v[136:137], s[58:59], v136, s51, v[16:17]
	v_mad_u64_u32 v[138:139], s[58:59], v138, s51, v[16:17]
	v_mad_u64_u32 v[140:141], s[58:59], v140, s51, v[16:17]
	v_mad_u64_u32 v[142:143], s[58:59], v142, s51, v[16:17]
	v_mad_u64_u32 v[144:145], s[58:59], v144, s51, v[16:17]
	v_mad_u64_u32 v[146:147], s[58:59], v146, s51, v[16:17]
	v_mad_u64_u32 v[148:149], s[58:59], v148, s51, v[16:17]
	v_mad_u64_u32 v[150:151], s[58:59], v150, s51, v[16:17]
	v_mad_u64_u32 v[152:153], s[58:59], v152, s51, v[16:17]
	v_mad_u64_u32 v[154:155], s[58:59], v154, s51, v[16:17]
	v_mad_u64_u32 v[156:157], s[58:59], v156, s51, v[16:17]
	v_mad_u64_u32 v[158:159], s[58:59], v158, s51, v[16:17]
	global_load_dword v129, v[118:119], off nt
	global_load_dword v174, v[130:131], off nt
	global_load_dword v175, v[132:133], off nt
	global_load_dword v176, v[134:135], off nt
	global_load_dword v177, v[136:137], off nt
	global_load_dword v178, v[138:139], off nt
	global_load_dword v179, v[140:141], off nt
	global_load_dword v180, v[142:143], off nt
	global_load_dword v181, v[144:145], off nt
	global_load_dword v182, v[146:147], off nt
	global_load_dword v183, v[148:149], off nt
	global_load_dword v184, v[150:151], off nt
	global_load_dword v185, v[152:153], off nt
	global_load_dword v186, v[154:155], off nt
	global_load_dword v187, v[156:157], off nt
	global_load_dword v188, v[158:159], off nt
	s_add_i32 s35, s35, 16
	s_add_i32 s34, s34, 16
	s_add_i32 s36, s36, -16
	v_mad_u64_u32 v[118:119], s[58:59], v109, s33, v[6:7]
	v_mad_u64_u32 v[130:131], s[58:59], v104, s33, v[6:7]
	v_mad_u64_u32 v[132:133], s[58:59], v161, s33, v[6:7]
	v_mad_u64_u32 v[134:135], s[58:59], v160, s33, v[6:7]
	v_mad_u64_u32 v[136:137], s[58:59], v163, s33, v[6:7]
	v_mad_u64_u32 v[138:139], s[58:59], v162, s33, v[6:7]
	v_mad_u64_u32 v[140:141], s[58:59], v165, s33, v[6:7]
	v_mad_u64_u32 v[142:143], s[58:59], v164, s33, v[6:7]
	v_mad_u64_u32 v[144:145], s[58:59], v167, s33, v[6:7]
	v_mad_u64_u32 v[146:147], s[58:59], v166, s33, v[6:7]
	v_mad_u64_u32 v[148:149], s[58:59], v169, s33, v[6:7]
	v_mad_u64_u32 v[150:151], s[58:59], v168, s33, v[6:7]
	v_mad_u64_u32 v[152:153], s[58:59], v171, s33, v[6:7]
	v_mad_u64_u32 v[154:155], s[58:59], v170, s33, v[6:7]
	v_mad_u64_u32 v[156:157], s[58:59], v173, s33, v[6:7]
	v_mad_u64_u32 v[158:159], s[58:59], v172, s33, v[6:7]
	s_lshl_b32 s37, s34, 1
	s_lshl_b32 s58, s35, 1
	v_or_b32_e32 v4, s37, v1
	v_or_b32_e32 v9, s58, v2
	s_add_i32 s59, s37, 4
	s_add_i32 s60, s58, 4
	s_add_i32 s61, s37, 8
	s_add_i32 s62, s58, 8
	s_add_i32 s63, s37, 12
	s_add_i32 s64, s58, 12
	s_add_i32 s65, s37, 16
	s_add_i32 s66, s58, 16
	s_add_i32 s67, s37, 20
	s_add_i32 s68, s58, 20
	s_add_i32 s69, s37, 24
	s_add_i32 s70, s58, 24
	s_add_i32 s37, s37, 28
	s_add_i32 s58, s58, 28
	v_add_u32_e32 v29, v4, v3
	v_add_u32_e32 v18, v9, v12
	v_or_b32_e32 v60, s59, v1
	v_or_b32_e32 v61, s60, v2
	v_or_b32_e32 v62, s61, v1
	v_or_b32_e32 v63, s62, v2
	v_or_b32_e32 v64, s63, v1
	v_or_b32_e32 v65, s64, v2
	v_or_b32_e32 v66, s65, v1
	v_or_b32_e32 v67, s66, v2
	v_or_b32_e32 v68, s67, v1
	v_or_b32_e32 v69, s68, v2
	v_or_b32_e32 v70, s69, v1
	v_or_b32_e32 v71, s70, v2
	v_or_b32_e32 v72, s37, v1
	v_or_b32_e32 v73, s58, v2
	v_mad_u64_u32 v[18:19], s[58:59], v18, s51, v[16:17]
	v_mad_u64_u32 v[30:31], s[58:59], v29, s51, v[16:17]
	v_add_u32_e32 v29, v60, v3
	v_add_u32_e32 v32, v61, v12
	v_add_u32_e32 v38, v62, v3
	v_add_u32_e32 v36, v63, v12
	v_add_u32_e32 v42, v64, v3
	v_add_u32_e32 v40, v65, v12
	v_add_u32_e32 v46, v66, v3
	v_add_u32_e32 v44, v67, v12
	v_add_u32_e32 v50, v68, v3
	v_add_u32_e32 v48, v69, v12
	v_add_u32_e32 v54, v70, v3
	v_add_u32_e32 v52, v71, v12
	v_add_u32_e32 v58, v72, v3
	v_add_u32_e32 v56, v73, v12
	v_mad_u64_u32 v[32:33], s[58:59], v32, s51, v[16:17]
	v_mad_u64_u32 v[34:35], s[58:59], v29, s51, v[16:17]
	v_mad_u64_u32 v[36:37], s[58:59], v36, s51, v[16:17]
	v_mad_u64_u32 v[38:39], s[58:59], v38, s51, v[16:17]
	v_mad_u64_u32 v[40:41], s[58:59], v40, s51, v[16:17]
	v_mad_u64_u32 v[42:43], s[58:59], v42, s51, v[16:17]
	v_mad_u64_u32 v[44:45], s[58:59], v44, s51, v[16:17]
	v_mad_u64_u32 v[46:47], s[58:59], v46, s51, v[16:17]
	v_mad_u64_u32 v[48:49], s[58:59], v48, s51, v[16:17]
	v_mad_u64_u32 v[50:51], s[58:59], v50, s51, v[16:17]
	v_mad_u64_u32 v[52:53], s[58:59], v52, s51, v[16:17]
	v_mad_u64_u32 v[54:55], s[58:59], v54, s51, v[16:17]
	v_mad_u64_u32 v[56:57], s[58:59], v56, s51, v[16:17]
	v_mad_u64_u32 v[58:59], s[58:59], v58, s51, v[16:17]
	global_load_dword v29, v[18:19], off nt
	global_load_dword v74, v[30:31], off nt
	global_load_dword v75, v[32:33], off nt
	global_load_dword v76, v[34:35], off nt
	global_load_dword v77, v[36:37], off nt
	global_load_dword v78, v[38:39], off nt
	global_load_dword v79, v[40:41], off nt
	global_load_dword v80, v[42:43], off nt
	global_load_dword v81, v[44:45], off nt
	global_load_dword v82, v[46:47], off nt
	global_load_dword v83, v[48:49], off nt
	global_load_dword v84, v[50:51], off nt
	global_load_dword v85, v[52:53], off nt
	global_load_dword v86, v[54:55], off nt
	global_load_dword v87, v[56:57], off nt
	global_load_dword v88, v[58:59], off nt
	s_add_i32 s35, s35, 16
	s_add_i32 s34, s34, 16
	s_add_i32 s36, s36, -16
	v_mad_u64_u32 v[18:19], s[58:59], v9, s33, v[6:7]
	v_mad_u64_u32 v[30:31], s[58:59], v4, s33, v[6:7]
	v_mad_u64_u32 v[32:33], s[58:59], v61, s33, v[6:7]
	v_mad_u64_u32 v[34:35], s[58:59], v60, s33, v[6:7]
	v_mad_u64_u32 v[36:37], s[58:59], v63, s33, v[6:7]
	v_mad_u64_u32 v[38:39], s[58:59], v62, s33, v[6:7]
	v_mad_u64_u32 v[40:41], s[58:59], v65, s33, v[6:7]
	v_mad_u64_u32 v[42:43], s[58:59], v64, s33, v[6:7]
	v_mad_u64_u32 v[44:45], s[58:59], v67, s33, v[6:7]
	v_mad_u64_u32 v[46:47], s[58:59], v66, s33, v[6:7]
	v_mad_u64_u32 v[48:49], s[58:59], v69, s33, v[6:7]
	v_mad_u64_u32 v[50:51], s[58:59], v68, s33, v[6:7]
	v_mad_u64_u32 v[52:53], s[58:59], v71, s33, v[6:7]
	v_mad_u64_u32 v[54:55], s[58:59], v70, s33, v[6:7]
	v_mad_u64_u32 v[56:57], s[58:59], v73, s33, v[6:7]
	v_mad_u64_u32 v[58:59], s[58:59], v72, s33, v[6:7]
	s_waitcnt vmcnt(31)
	ds_write_b32 v118, v129
	s_waitcnt vmcnt(30)
	ds_write_b32 v130, v174
	s_waitcnt vmcnt(29)
	ds_write_b32 v132, v175
	s_waitcnt vmcnt(28)
	ds_write_b32 v134, v176
	s_waitcnt vmcnt(27)
	ds_write_b32 v136, v177
	s_waitcnt vmcnt(26)
	ds_write_b32 v138, v178
	s_waitcnt vmcnt(25)
	ds_write_b32 v140, v179
	s_waitcnt vmcnt(24)
	ds_write_b32 v142, v180
	s_waitcnt vmcnt(23)
	ds_write_b32 v144, v181
	s_waitcnt vmcnt(22)
	ds_write_b32 v146, v182
	s_waitcnt vmcnt(21)
	ds_write_b32 v148, v183
	s_waitcnt vmcnt(20)
	ds_write_b32 v150, v184
	s_waitcnt vmcnt(19)
	ds_write_b32 v152, v185
	s_waitcnt vmcnt(18)
	ds_write_b32 v154, v186
	s_waitcnt vmcnt(17)
	ds_write_b32 v156, v187
	s_waitcnt vmcnt(16)
	ds_write_b32 v158, v188
	s_waitcnt vmcnt(15)
	ds_write_b32 v18, v29
	s_waitcnt vmcnt(14)
	ds_write_b32 v30, v74
	s_waitcnt vmcnt(13)
	ds_write_b32 v32, v75
	s_waitcnt vmcnt(12)
	ds_write_b32 v34, v76
	s_waitcnt vmcnt(11)
	ds_write_b32 v36, v77
	s_waitcnt vmcnt(10)
	ds_write_b32 v38, v78
	s_waitcnt vmcnt(9)
	ds_write_b32 v40, v79
	s_waitcnt vmcnt(8)
	ds_write_b32 v42, v80
	s_waitcnt vmcnt(7)
	ds_write_b32 v44, v81
	s_waitcnt vmcnt(6)
	ds_write_b32 v46, v82
	s_waitcnt vmcnt(5)
	ds_write_b32 v48, v83
	s_waitcnt vmcnt(4)
	ds_write_b32 v50, v84
	s_waitcnt vmcnt(3)
	ds_write_b32 v52, v85
	s_waitcnt vmcnt(2)
	ds_write_b32 v54, v86
	s_waitcnt vmcnt(1)
	ds_write_b32 v56, v87
	s_waitcnt vmcnt(0)
	ds_write_b32 v58, v88
	s_waitcnt lgkmcnt(0)
	ds_read2_b32 v[16:17], v22 offset1:8
	ds_read2_b32 v[30:31], v22 offset0:33 offset1:41
	v_lshlrev_b32_e32 v3, 6, v13
	v_and_b32_e32 v3, 0x3f00, v3
	v_and_b32_e32 v4, 0x60, v11
	ds_read2_b32 v[32:33], v22 offset0:66 offset1:74
	v_lshl_add_u64 v[14:15], s[14:15], 0, v[14:15]
	v_or3_b32 v3, v3, v4, s53
	v_lshlrev_b32_e32 v4, 1, v12
	ds_read2_b32 v[34:35], v22 offset0:99 offset1:107
	v_lshl_add_u64 v[12:13], v[14:15], 0, v[4:5]
	s_waitcnt lgkmcnt(3)
	v_bfe_u32 v4, v16, 16, 1
	v_add3_u32 v4, v16, v4, s45
	s_waitcnt lgkmcnt(2)
	v_bfe_u32 v9, v30, 16, 1
	ds_read2_b32 v[36:37], v22 offset0:132 offset1:140
	v_mov_b32_e32 v11, v5
	v_lshrrev_b32_e32 v4, 16, v4
	v_add3_u32 v9, v30, v9, s45
	ds_read2_b32 v[38:39], v22 offset0:165 offset1:173
	v_lshl_add_u64 v[18:19], v[12:13], 0, v[10:11]
	v_and_or_b32 v12, v9, s46, v4
	s_waitcnt lgkmcnt(3)
	v_bfe_u32 v4, v32, 16, 1
	v_add3_u32 v4, v32, v4, s45
	s_waitcnt lgkmcnt(2)
	v_bfe_u32 v9, v34, 16, 1
	ds_read2_b32 v[40:41], v22 offset0:198 offset1:206
	v_lshrrev_b32_e32 v4, 16, v4
	v_add3_u32 v9, v34, v9, s45
	ds_read2_b32 v[42:43], v22 offset0:231 offset1:239
	v_and_or_b32 v13, v9, s46, v4
	s_waitcnt lgkmcnt(3)
	v_bfe_u32 v4, v36, 16, 1
	v_add3_u32 v4, v36, v4, s45
	s_waitcnt lgkmcnt(2)
	v_bfe_u32 v9, v38, 16, 1
	v_lshrrev_b32_e32 v4, 16, v4
	v_add3_u32 v9, v38, v9, s45
	v_and_or_b32 v14, v9, s46, v4
	s_waitcnt lgkmcnt(1)
	v_bfe_u32 v4, v40, 16, 1
	v_add3_u32 v4, v40, v4, s45
	s_waitcnt lgkmcnt(0)
	v_bfe_u32 v9, v42, 16, 1
	v_lshrrev_b32_e32 v4, 16, v4
	v_add3_u32 v9, v42, v9, s45
	v_and_or_b32 v15, v9, s46, v4
	v_or_b32_e32 v4, v3, v21
	v_lshlrev_b32_e32 v4, 12, v4
	v_lshl_add_u64 v[44:45], v[18:19], 0, v[4:5]
	v_bfe_u32 v4, v17, 16, 1
	v_add3_u32 v4, v17, v4, s45
	v_bfe_u32 v9, v31, 16, 1
	v_lshrrev_b32_e32 v4, 16, v4
	v_add3_u32 v9, v31, v9, s45
	global_store_dwordx4 v[44:45], v[12:15], off
	ds_read2_b32 v[16:17], v22 offset0:16 offset1:24
	v_readlane_b32 s66, v253, 1
	v_and_or_b32 v12, v9, s46, v4
	v_bfe_u32 v4, v33, 16, 1
	v_add3_u32 v4, v33, v4, s45
	v_bfe_u32 v9, v35, 16, 1
	v_lshrrev_b32_e32 v4, 16, v4
	v_add3_u32 v9, v35, v9, s45
	v_and_or_b32 v13, v9, s46, v4
	v_bfe_u32 v4, v37, 16, 1
	v_add3_u32 v4, v37, v4, s45
	v_bfe_u32 v9, v39, 16, 1
	v_lshrrev_b32_e32 v4, 16, v4
	v_add3_u32 v9, v39, v9, s45
	v_and_or_b32 v14, v9, s46, v4
	v_bfe_u32 v4, v41, 16, 1
	v_add3_u32 v4, v41, v4, s45
	v_bfe_u32 v9, v43, 16, 1
	v_lshrrev_b32_e32 v4, 16, v4
	v_add3_u32 v9, v43, v9, s45
	v_and_or_b32 v15, v9, s46, v4
	v_or_b32_e32 v4, v3, v23
	v_lshlrev_b32_e32 v4, 12, v4
	v_lshl_add_u64 v[30:31], v[18:19], 0, v[4:5]
	global_store_dwordx4 v[30:31], v[12:15], off
	ds_read2_b32 v[30:31], v22 offset0:49 offset1:57
	ds_read2_b32 v[32:33], v22 offset0:82 offset1:90
	ds_read2_b32 v[34:35], v22 offset0:115 offset1:123
	s_waitcnt lgkmcnt(3)
	v_bfe_u32 v4, v16, 16, 1
	v_add3_u32 v4, v16, v4, s45
	s_waitcnt lgkmcnt(2)
	v_bfe_u32 v9, v30, 16, 1
	ds_read2_b32 v[36:37], v22 offset0:148 offset1:156
	v_lshrrev_b32_e32 v4, 16, v4
	v_add3_u32 v9, v30, v9, s45
	ds_read2_b32 v[38:39], v22 offset0:181 offset1:189
	v_and_or_b32 v12, v9, s46, v4
	s_waitcnt lgkmcnt(3)
	v_bfe_u32 v4, v32, 16, 1
	v_add3_u32 v4, v32, v4, s45
	s_waitcnt lgkmcnt(2)
	v_bfe_u32 v9, v34, 16, 1
	ds_read2_b32 v[40:41], v22 offset0:214 offset1:222
	v_lshrrev_b32_e32 v4, 16, v4
	v_add3_u32 v9, v34, v9, s45
	ds_read2_b32 v[42:43], v22 offset0:247 offset1:255
	v_and_or_b32 v13, v9, s46, v4
	s_waitcnt lgkmcnt(3)
	v_bfe_u32 v4, v36, 16, 1
	v_add3_u32 v4, v36, v4, s45
	s_waitcnt lgkmcnt(2)
	v_bfe_u32 v9, v38, 16, 1
	v_lshrrev_b32_e32 v4, 16, v4
	v_add3_u32 v9, v38, v9, s45
	v_and_or_b32 v14, v9, s46, v4
	s_waitcnt lgkmcnt(1)
	v_bfe_u32 v4, v40, 16, 1
	v_add3_u32 v4, v40, v4, s45
	s_waitcnt lgkmcnt(0)
	v_bfe_u32 v9, v42, 16, 1
	v_lshrrev_b32_e32 v4, 16, v4
	v_add3_u32 v9, v42, v9, s45
	v_and_or_b32 v15, v9, s46, v4
	v_or_b32_e32 v4, v3, v24
	v_lshlrev_b32_e32 v4, 12, v4
	v_lshl_add_u64 v[44:45], v[18:19], 0, v[4:5]
	v_bfe_u32 v4, v17, 16, 1
	v_add3_u32 v4, v17, v4, s45
	v_bfe_u32 v9, v31, 16, 1
	v_lshrrev_b32_e32 v4, 16, v4
	v_add3_u32 v9, v31, v9, s45
	global_store_dwordx4 v[44:45], v[12:15], off
	v_or_b32_e32 v3, v3, v25
	s_nop 0
	v_and_or_b32 v12, v9, s46, v4
	v_bfe_u32 v4, v33, 16, 1
	v_add3_u32 v4, v33, v4, s45
	v_bfe_u32 v9, v35, 16, 1
	v_lshrrev_b32_e32 v4, 16, v4
	v_add3_u32 v9, v35, v9, s45
	v_and_or_b32 v13, v9, s46, v4
	v_bfe_u32 v4, v37, 16, 1
	v_add3_u32 v4, v37, v4, s45
	v_bfe_u32 v9, v39, 16, 1
	v_lshrrev_b32_e32 v4, 16, v4
	v_add3_u32 v9, v39, v9, s45
	v_and_or_b32 v14, v9, s46, v4
	v_bfe_u32 v4, v41, 16, 1
	v_add3_u32 v4, v41, v4, s45
	v_bfe_u32 v9, v43, 16, 1
	v_lshrrev_b32_e32 v4, 16, v4
	v_add3_u32 v9, v43, v9, s45
	v_and_or_b32 v15, v9, s46, v4
	v_lshlrev_b32_e32 v4, 12, v3
	v_lshl_add_u64 v[16:17], v[18:19], 0, v[4:5]
	global_store_dwordx4 v[16:17], v[12:15], off
	s_waitcnt lgkmcnt(0)

.LBB0_130:
	s_andn2_saveexec_b64 s[28:29], s[28:29]
	s_cbranch_execz .LBB0_134
	s_load_dwordx2 s[30:31], s[6:7], 0x90
	v_add_u16_e32 v3, 0xe7c0, v3
	v_mul_u32_u24_e32 v4, 0xba2f, v3
	v_lshrrev_b32_e32 v4, 23, v4
	v_mul_lo_u16_e32 v9, 0xb0, v4
	v_sub_u16_e32 v11, v3, v9
	s_waitcnt lgkmcnt(0)
	v_mov_b64_e32 v[16:17], s[30:31]
	v_mad_i64_i32 v[14:15], s[34:35], v12, s49, 0
	v_mad_i64_i32 v[16:17], s[30:31], v12, s49, v[16:17]
	v_lshlrev_b16_e32 v12, 6, v4
	v_lshlrev_b32_e32 v4, 7, v11
	v_lshl_add_u64 v[16:17], v[16:17], 0, v[4:5]
	v_mov_b32_e32 v9, v5
	v_lshlrev_b32_e32 v13, 5, v11
	v_lshl_add_u64 v[16:17], v[16:17], 0, v[8:9]
	v_mov_b32_e32 v3, v12
	s_mov_b32 s30, 1
	s_mov_b32 s31, 0
	s_mov_b32 s34, 32
	s_lshl_b32 s35, s30, 1
	s_lshl_b32 s36, s31, 1
	v_or_b32_e32 v104, s35, v1
	v_or_b32_e32 v109, s36, v2
	s_add_i32 s37, s35, 4
	s_add_i32 s58, s36, 4
	s_add_i32 s59, s35, 8
	s_add_i32 s60, s36, 8
	s_add_i32 s61, s35, 12
	s_add_i32 s62, s36, 12
	s_add_i32 s63, s35, 16
	s_add_i32 s64, s36, 16
	s_add_i32 s65, s35, 20
	s_add_i32 s66, s36, 20
	s_add_i32 s67, s35, 24
	s_add_i32 s68, s36, 24
	s_add_i32 s35, s35, 28
	s_add_i32 s36, s36, 28
	v_add_u32_e32 v129, v104, v3
	v_add_u32_e32 v118, v109, v12
	v_or_b32_e32 v160, s37, v1
	v_or_b32_e32 v161, s58, v2
	v_or_b32_e32 v162, s59, v1
	v_or_b32_e32 v163, s60, v2
	v_or_b32_e32 v164, s61, v1
	v_or_b32_e32 v165, s62, v2
	v_or_b32_e32 v166, s63, v1
	v_or_b32_e32 v167, s64, v2
	v_or_b32_e32 v168, s65, v1
	v_or_b32_e32 v169, s66, v2
	v_or_b32_e32 v170, s67, v1
	v_or_b32_e32 v171, s68, v2
	v_or_b32_e32 v172, s35, v1
	v_or_b32_e32 v173, s36, v2
	v_mad_u64_u32 v[118:119], s[36:37], v118, s51, v[16:17]
	v_mad_u64_u32 v[130:131], s[36:37], v129, s51, v[16:17]
	v_add_u32_e32 v129, v160, v3
	v_add_u32_e32 v132, v161, v12
	v_add_u32_e32 v138, v162, v3
	v_add_u32_e32 v136, v163, v12
	v_add_u32_e32 v142, v164, v3
	v_add_u32_e32 v140, v165, v12
	v_add_u32_e32 v146, v166, v3
	v_add_u32_e32 v144, v167, v12
	v_add_u32_e32 v150, v168, v3
	v_add_u32_e32 v148, v169, v12
	v_add_u32_e32 v154, v170, v3
	v_add_u32_e32 v152, v171, v12
	v_add_u32_e32 v158, v172, v3
	v_add_u32_e32 v156, v173, v12
	v_mad_u64_u32 v[132:133], s[36:37], v132, s51, v[16:17]
	v_mad_u64_u32 v[134:135], s[36:37], v129, s51, v[16:17]
	v_mad_u64_u32 v[136:137], s[36:37], v136, s51, v[16:17]
	v_mad_u64_u32 v[138:139], s[36:37], v138, s51, v[16:17]
	v_mad_u64_u32 v[140:141], s[36:37], v140, s51, v[16:17]
	v_mad_u64_u32 v[142:143], s[36:37], v142, s51, v[16:17]
	v_mad_u64_u32 v[144:145], s[36:37], v144, s51, v[16:17]
	v_mad_u64_u32 v[146:147], s[36:37], v146, s51, v[16:17]
	v_mad_u64_u32 v[148:149], s[36:37], v148, s51, v[16:17]
	v_mad_u64_u32 v[150:151], s[36:37], v150, s51, v[16:17]
	v_mad_u64_u32 v[152:153], s[36:37], v152, s51, v[16:17]
	v_mad_u64_u32 v[154:155], s[36:37], v154, s51, v[16:17]
	v_mad_u64_u32 v[156:157], s[36:37], v156, s51, v[16:17]
	v_mad_u64_u32 v[158:159], s[36:37], v158, s51, v[16:17]
	global_load_dword v129, v[118:119], off nt
	global_load_dword v174, v[130:131], off nt
	global_load_dword v175, v[132:133], off nt
	global_load_dword v176, v[134:135], off nt
	global_load_dword v177, v[136:137], off nt
	global_load_dword v178, v[138:139], off nt
	global_load_dword v179, v[140:141], off nt
	global_load_dword v180, v[142:143], off nt
	global_load_dword v181, v[144:145], off nt
	global_load_dword v182, v[146:147], off nt
	global_load_dword v183, v[148:149], off nt
	global_load_dword v184, v[150:151], off nt
	global_load_dword v185, v[152:153], off nt
	global_load_dword v186, v[154:155], off nt
	global_load_dword v187, v[156:157], off nt
	global_load_dword v188, v[158:159], off nt
	s_add_i32 s31, s31, 16
	s_add_i32 s30, s30, 16
	s_add_i32 s34, s34, -16
	v_mad_u64_u32 v[118:119], s[36:37], v109, s33, v[6:7]
	v_mad_u64_u32 v[130:131], s[36:37], v104, s33, v[6:7]
	v_mad_u64_u32 v[132:133], s[36:37], v161, s33, v[6:7]
	v_mad_u64_u32 v[134:135], s[36:37], v160, s33, v[6:7]
	v_mad_u64_u32 v[136:137], s[36:37], v163, s33, v[6:7]
	v_mad_u64_u32 v[138:139], s[36:37], v162, s33, v[6:7]
	v_mad_u64_u32 v[140:141], s[36:37], v165, s33, v[6:7]
	v_mad_u64_u32 v[142:143], s[36:37], v164, s33, v[6:7]
	v_mad_u64_u32 v[144:145], s[36:37], v167, s33, v[6:7]
	v_mad_u64_u32 v[146:147], s[36:37], v166, s33, v[6:7]
	v_mad_u64_u32 v[148:149], s[36:37], v169, s33, v[6:7]
	v_mad_u64_u32 v[150:151], s[36:37], v168, s33, v[6:7]
	v_mad_u64_u32 v[152:153], s[36:37], v171, s33, v[6:7]
	v_mad_u64_u32 v[154:155], s[36:37], v170, s33, v[6:7]
	v_mad_u64_u32 v[156:157], s[36:37], v173, s33, v[6:7]
	v_mad_u64_u32 v[158:159], s[36:37], v172, s33, v[6:7]
	s_lshl_b32 s35, s30, 1
	s_lshl_b32 s36, s31, 1
	v_or_b32_e32 v4, s35, v1
	v_or_b32_e32 v9, s36, v2
	s_add_i32 s37, s35, 4
	s_add_i32 s58, s36, 4
	s_add_i32 s59, s35, 8
	s_add_i32 s60, s36, 8
	s_add_i32 s61, s35, 12
	s_add_i32 s62, s36, 12
	s_add_i32 s63, s35, 16
	s_add_i32 s64, s36, 16
	s_add_i32 s65, s35, 20
	s_add_i32 s66, s36, 20
	s_add_i32 s67, s35, 24
	s_add_i32 s68, s36, 24
	s_add_i32 s35, s35, 28
	s_add_i32 s36, s36, 28
	v_add_u32_e32 v29, v4, v3
	v_add_u32_e32 v18, v9, v12
	v_or_b32_e32 v60, s37, v1
	v_or_b32_e32 v61, s58, v2
	v_or_b32_e32 v62, s59, v1
	v_or_b32_e32 v63, s60, v2
	v_or_b32_e32 v64, s61, v1
	v_or_b32_e32 v65, s62, v2
	v_or_b32_e32 v66, s63, v1
	v_or_b32_e32 v67, s64, v2
	v_or_b32_e32 v68, s65, v1
	v_or_b32_e32 v69, s66, v2
	v_or_b32_e32 v70, s67, v1
	v_or_b32_e32 v71, s68, v2
	v_or_b32_e32 v72, s35, v1
	v_or_b32_e32 v73, s36, v2
	v_mad_u64_u32 v[18:19], s[36:37], v18, s51, v[16:17]
	v_mad_u64_u32 v[30:31], s[36:37], v29, s51, v[16:17]
	v_add_u32_e32 v29, v60, v3
	v_add_u32_e32 v32, v61, v12
	v_add_u32_e32 v38, v62, v3
	v_add_u32_e32 v36, v63, v12
	v_add_u32_e32 v42, v64, v3
	v_add_u32_e32 v40, v65, v12
	v_add_u32_e32 v46, v66, v3
	v_add_u32_e32 v44, v67, v12
	v_add_u32_e32 v50, v68, v3
	v_add_u32_e32 v48, v69, v12
	v_add_u32_e32 v54, v70, v3
	v_add_u32_e32 v52, v71, v12
	v_add_u32_e32 v58, v72, v3
	v_add_u32_e32 v56, v73, v12
	v_mad_u64_u32 v[32:33], s[36:37], v32, s51, v[16:17]
	v_mad_u64_u32 v[34:35], s[36:37], v29, s51, v[16:17]
	v_mad_u64_u32 v[36:37], s[36:37], v36, s51, v[16:17]
	v_mad_u64_u32 v[38:39], s[36:37], v38, s51, v[16:17]
	v_mad_u64_u32 v[40:41], s[36:37], v40, s51, v[16:17]
	v_mad_u64_u32 v[42:43], s[36:37], v42, s51, v[16:17]
	v_mad_u64_u32 v[44:45], s[36:37], v44, s51, v[16:17]
	v_mad_u64_u32 v[46:47], s[36:37], v46, s51, v[16:17]
	v_mad_u64_u32 v[48:49], s[36:37], v48, s51, v[16:17]
	v_mad_u64_u32 v[50:51], s[36:37], v50, s51, v[16:17]
	v_mad_u64_u32 v[52:53], s[36:37], v52, s51, v[16:17]
	v_mad_u64_u32 v[54:55], s[36:37], v54, s51, v[16:17]
	v_mad_u64_u32 v[56:57], s[36:37], v56, s51, v[16:17]
	v_mad_u64_u32 v[58:59], s[36:37], v58, s51, v[16:17]
	global_load_dword v29, v[18:19], off nt
	global_load_dword v74, v[30:31], off nt
	global_load_dword v75, v[32:33], off nt
	global_load_dword v76, v[34:35], off nt
	global_load_dword v77, v[36:37], off nt
	global_load_dword v78, v[38:39], off nt
	global_load_dword v79, v[40:41], off nt
	global_load_dword v80, v[42:43], off nt
	global_load_dword v81, v[44:45], off nt
	global_load_dword v82, v[46:47], off nt
	global_load_dword v83, v[48:49], off nt
	global_load_dword v84, v[50:51], off nt
	global_load_dword v85, v[52:53], off nt
	global_load_dword v86, v[54:55], off nt
	global_load_dword v87, v[56:57], off nt
	global_load_dword v88, v[58:59], off nt
	s_add_i32 s31, s31, 16
	s_add_i32 s30, s30, 16
	s_add_i32 s34, s34, -16
	v_mad_u64_u32 v[18:19], s[36:37], v9, s33, v[6:7]
	v_mad_u64_u32 v[30:31], s[36:37], v4, s33, v[6:7]
	v_mad_u64_u32 v[32:33], s[36:37], v61, s33, v[6:7]
	v_mad_u64_u32 v[34:35], s[36:37], v60, s33, v[6:7]
	v_mad_u64_u32 v[36:37], s[36:37], v63, s33, v[6:7]
	v_mad_u64_u32 v[38:39], s[36:37], v62, s33, v[6:7]
	v_mad_u64_u32 v[40:41], s[36:37], v65, s33, v[6:7]
	v_mad_u64_u32 v[42:43], s[36:37], v64, s33, v[6:7]
	v_mad_u64_u32 v[44:45], s[36:37], v67, s33, v[6:7]
	v_mad_u64_u32 v[46:47], s[36:37], v66, s33, v[6:7]
	v_mad_u64_u32 v[48:49], s[36:37], v69, s33, v[6:7]
	v_mad_u64_u32 v[50:51], s[36:37], v68, s33, v[6:7]
	v_mad_u64_u32 v[52:53], s[36:37], v71, s33, v[6:7]
	v_mad_u64_u32 v[54:55], s[36:37], v70, s33, v[6:7]
	v_mad_u64_u32 v[56:57], s[36:37], v73, s33, v[6:7]
	v_mad_u64_u32 v[58:59], s[36:37], v72, s33, v[6:7]
	s_waitcnt vmcnt(31)
	ds_write_b32 v118, v129
	s_waitcnt vmcnt(30)
	ds_write_b32 v130, v174
	s_waitcnt vmcnt(29)
	ds_write_b32 v132, v175
	s_waitcnt vmcnt(28)
	ds_write_b32 v134, v176
	s_waitcnt vmcnt(27)
	ds_write_b32 v136, v177
	s_waitcnt vmcnt(26)
	ds_write_b32 v138, v178
	s_waitcnt vmcnt(25)
	ds_write_b32 v140, v179
	s_waitcnt vmcnt(24)
	ds_write_b32 v142, v180
	s_waitcnt vmcnt(23)
	ds_write_b32 v144, v181
	s_waitcnt vmcnt(22)
	ds_write_b32 v146, v182
	s_waitcnt vmcnt(21)
	ds_write_b32 v148, v183
	s_waitcnt vmcnt(20)
	ds_write_b32 v150, v184
	s_waitcnt vmcnt(19)
	ds_write_b32 v152, v185
	s_waitcnt vmcnt(18)
	ds_write_b32 v154, v186
	s_waitcnt vmcnt(17)
	ds_write_b32 v156, v187
	s_waitcnt vmcnt(16)
	ds_write_b32 v158, v188
	s_waitcnt vmcnt(15)
	ds_write_b32 v18, v29
	s_waitcnt vmcnt(14)
	ds_write_b32 v30, v74
	s_waitcnt vmcnt(13)
	ds_write_b32 v32, v75
	s_waitcnt vmcnt(12)
	ds_write_b32 v34, v76
	s_waitcnt vmcnt(11)
	ds_write_b32 v36, v77
	s_waitcnt vmcnt(10)
	ds_write_b32 v38, v78
	s_waitcnt vmcnt(9)
	ds_write_b32 v40, v79
	s_waitcnt vmcnt(8)
	ds_write_b32 v42, v80
	s_waitcnt vmcnt(7)
	ds_write_b32 v44, v81
	s_waitcnt vmcnt(6)
	ds_write_b32 v46, v82
	s_waitcnt vmcnt(5)
	ds_write_b32 v48, v83
	s_waitcnt vmcnt(4)
	ds_write_b32 v50, v84
	s_waitcnt vmcnt(3)
	ds_write_b32 v52, v85
	s_waitcnt vmcnt(2)
	ds_write_b32 v54, v86
	s_waitcnt vmcnt(1)
	ds_write_b32 v56, v87
	s_waitcnt vmcnt(0)
	ds_write_b32 v58, v88
	s_waitcnt lgkmcnt(0)
	ds_read2_b32 v[16:17], v22 offset1:8
	ds_read2_b32 v[30:31], v22 offset0:33 offset1:41
	v_lshlrev_b32_e32 v3, 6, v11
	v_and_b32_e32 v4, 0x60, v13
	ds_read2_b32 v[32:33], v22 offset0:66 offset1:74
	v_lshl_add_u64 v[14:15], s[14:15], 0, v[14:15]
	v_and_or_b32 v3, v3, s52, v4
	v_lshlrev_b32_e32 v4, 1, v12
	ds_read2_b32 v[34:35], v22 offset0:99 offset1:107
	v_lshl_add_u64 v[12:13], v[14:15], 0, v[4:5]
	s_waitcnt lgkmcnt(3)
	v_bfe_u32 v4, v16, 16, 1
	v_add3_u32 v4, v16, v4, s45
	s_waitcnt lgkmcnt(2)
	v_bfe_u32 v9, v30, 16, 1
	ds_read2_b32 v[36:37], v22 offset0:132 offset1:140
	v_mov_b32_e32 v11, v5
	v_lshrrev_b32_e32 v4, 16, v4
	v_add3_u32 v9, v30, v9, s45
	ds_read2_b32 v[38:39], v22 offset0:165 offset1:173
	v_lshl_add_u64 v[18:19], v[12:13], 0, v[10:11]
	v_and_or_b32 v12, v9, s46, v4
	s_waitcnt lgkmcnt(3)
	v_bfe_u32 v4, v32, 16, 1
	v_add3_u32 v4, v32, v4, s45
	s_waitcnt lgkmcnt(2)
	v_bfe_u32 v9, v34, 16, 1
	ds_read2_b32 v[40:41], v22 offset0:198 offset1:206
	v_lshrrev_b32_e32 v4, 16, v4
	v_add3_u32 v9, v34, v9, s45
	ds_read2_b32 v[42:43], v22 offset0:231 offset1:239
	v_and_or_b32 v13, v9, s46, v4
	s_waitcnt lgkmcnt(3)
	v_bfe_u32 v4, v36, 16, 1
	v_add3_u32 v4, v36, v4, s45
	s_waitcnt lgkmcnt(2)
	v_bfe_u32 v9, v38, 16, 1
	v_lshrrev_b32_e32 v4, 16, v4
	v_add3_u32 v9, v38, v9, s45
	v_and_or_b32 v14, v9, s46, v4
	s_waitcnt lgkmcnt(1)
	v_bfe_u32 v4, v40, 16, 1
	v_add3_u32 v4, v40, v4, s45
	s_waitcnt lgkmcnt(0)
	v_bfe_u32 v9, v42, 16, 1
	v_lshrrev_b32_e32 v4, 16, v4
	v_add3_u32 v9, v42, v9, s45
	v_and_or_b32 v15, v9, s46, v4
	v_or_b32_e32 v4, v3, v21
	v_lshlrev_b32_e32 v4, 12, v4
	v_lshl_add_u64 v[44:45], v[18:19], 0, v[4:5]
	v_bfe_u32 v4, v17, 16, 1
	v_add3_u32 v4, v17, v4, s45
	v_bfe_u32 v9, v31, 16, 1
	v_lshrrev_b32_e32 v4, 16, v4
	v_add3_u32 v9, v31, v9, s45
	global_store_dwordx4 v[44:45], v[12:15], off
	ds_read2_b32 v[16:17], v22 offset0:16 offset1:24
	v_readlane_b32 s66, v253, 1
	v_and_or_b32 v12, v9, s46, v4
	v_bfe_u32 v4, v33, 16, 1
	v_add3_u32 v4, v33, v4, s45
	v_bfe_u32 v9, v35, 16, 1
	v_lshrrev_b32_e32 v4, 16, v4
	v_add3_u32 v9, v35, v9, s45
	v_and_or_b32 v13, v9, s46, v4
	v_bfe_u32 v4, v37, 16, 1
	v_add3_u32 v4, v37, v4, s45
	v_bfe_u32 v9, v39, 16, 1
	v_lshrrev_b32_e32 v4, 16, v4
	v_add3_u32 v9, v39, v9, s45
	v_and_or_b32 v14, v9, s46, v4
	v_bfe_u32 v4, v41, 16, 1
	v_add3_u32 v4, v41, v4, s45
	v_bfe_u32 v9, v43, 16, 1
	v_lshrrev_b32_e32 v4, 16, v4
	v_add3_u32 v9, v43, v9, s45
	v_and_or_b32 v15, v9, s46, v4
	v_or_b32_e32 v4, v3, v23
	v_lshlrev_b32_e32 v4, 12, v4
	v_lshl_add_u64 v[30:31], v[18:19], 0, v[4:5]
	global_store_dwordx4 v[30:31], v[12:15], off
	ds_read2_b32 v[30:31], v22 offset0:49 offset1:57
	ds_read2_b32 v[32:33], v22 offset0:82 offset1:90
	ds_read2_b32 v[34:35], v22 offset0:115 offset1:123
	s_waitcnt lgkmcnt(3)
	v_bfe_u32 v4, v16, 16, 1
	v_add3_u32 v4, v16, v4, s45
	s_waitcnt lgkmcnt(2)
	v_bfe_u32 v9, v30, 16, 1
	ds_read2_b32 v[36:37], v22 offset0:148 offset1:156
	v_lshrrev_b32_e32 v4, 16, v4
	v_add3_u32 v9, v30, v9, s45
	ds_read2_b32 v[38:39], v22 offset0:181 offset1:189
	v_and_or_b32 v12, v9, s46, v4
	s_waitcnt lgkmcnt(3)
	v_bfe_u32 v4, v32, 16, 1
	v_add3_u32 v4, v32, v4, s45
	s_waitcnt lgkmcnt(2)
	v_bfe_u32 v9, v34, 16, 1
	ds_read2_b32 v[40:41], v22 offset0:214 offset1:222
	v_lshrrev_b32_e32 v4, 16, v4
	v_add3_u32 v9, v34, v9, s45
	ds_read2_b32 v[42:43], v22 offset0:247 offset1:255
	v_and_or_b32 v13, v9, s46, v4
	s_waitcnt lgkmcnt(3)
	v_bfe_u32 v4, v36, 16, 1
	v_add3_u32 v4, v36, v4, s45
	s_waitcnt lgkmcnt(2)
	v_bfe_u32 v9, v38, 16, 1
	v_lshrrev_b32_e32 v4, 16, v4
	v_add3_u32 v9, v38, v9, s45
	v_and_or_b32 v14, v9, s46, v4
	s_waitcnt lgkmcnt(1)
	v_bfe_u32 v4, v40, 16, 1
	v_add3_u32 v4, v40, v4, s45
	s_waitcnt lgkmcnt(0)
	v_bfe_u32 v9, v42, 16, 1
	v_lshrrev_b32_e32 v4, 16, v4
	v_add3_u32 v9, v42, v9, s45
	v_and_or_b32 v15, v9, s46, v4
	v_or_b32_e32 v4, v3, v24
	v_lshlrev_b32_e32 v4, 12, v4
	v_lshl_add_u64 v[44:45], v[18:19], 0, v[4:5]
	v_bfe_u32 v4, v17, 16, 1
	v_add3_u32 v4, v17, v4, s45
	v_bfe_u32 v9, v31, 16, 1
	v_lshrrev_b32_e32 v4, 16, v4
	v_add3_u32 v9, v31, v9, s45
	global_store_dwordx4 v[44:45], v[12:15], off
	v_or_b32_e32 v3, v3, v25
	s_nop 0
	v_and_or_b32 v12, v9, s46, v4
	v_bfe_u32 v4, v33, 16, 1
	v_add3_u32 v4, v33, v4, s45
	v_bfe_u32 v9, v35, 16, 1
	v_lshrrev_b32_e32 v4, 16, v4
	v_add3_u32 v9, v35, v9, s45
	v_and_or_b32 v13, v9, s46, v4
	v_bfe_u32 v4, v37, 16, 1
	v_add3_u32 v4, v37, v4, s45
	v_bfe_u32 v9, v39, 16, 1
	v_lshrrev_b32_e32 v4, 16, v4
	v_add3_u32 v9, v39, v9, s45
	v_and_or_b32 v14, v9, s46, v4
	v_bfe_u32 v4, v41, 16, 1
	v_add3_u32 v4, v41, v4, s45
	v_bfe_u32 v9, v43, 16, 1
	v_lshrrev_b32_e32 v4, 16, v4
	v_add3_u32 v9, v43, v9, s45
	v_and_or_b32 v15, v9, s46, v4
	v_lshlrev_b32_e32 v4, 12, v3
	v_lshl_add_u64 v[16:17], v[18:19], 0, v[4:5]
	global_store_dwordx4 v[16:17], v[12:15], off
	s_waitcnt lgkmcnt(0)

.LBB0_135:
	s_andn2_saveexec_b64 s[26:27], s[26:27]
	s_cbranch_execz .LBB0_139
	s_load_dwordx2 s[28:29], s[6:7], 0x78
	v_and_b32_e32 v4, 0x1fc0, v3
	v_ashrrev_i32_e32 v13, 31, v12
	v_lshlrev_b32_e32 v3, 5, v3
	v_lshlrev_b64 v[16:17], 22, v[12:13]
	v_lshlrev_b64 v[12:13], 24, v[12:13]
	v_and_b32_e32 v18, 0x7e0, v3
	v_add_u32_e32 v14, 0xffffefc0, v4
	s_waitcnt lgkmcnt(0)
	v_lshl_add_u64 v[12:13], s[28:29], 0, v[12:13]
	v_lshlrev_b32_e32 v4, 2, v18
	v_lshl_add_u64 v[12:13], v[12:13], 0, v[4:5]
	v_mov_b32_e32 v9, v5
	v_lshl_add_u64 v[12:13], v[12:13], 0, v[8:9]
	v_mov_b32_e32 v3, v14
	s_mov_b32 s28, 1
	s_mov_b32 s29, 0
	s_mov_b32 s30, 32
	s_lshl_b32 s31, s28, 1
	s_lshl_b32 s34, s29, 1
	v_or_b32_e32 v104, s31, v1
	v_or_b32_e32 v109, s34, v2
	s_add_i32 s35, s31, 4
	s_add_i32 s36, s34, 4
	s_add_i32 s37, s31, 8
	s_add_i32 s58, s34, 8
	s_add_i32 s59, s31, 12
	s_add_i32 s60, s34, 12
	s_add_i32 s61, s31, 16
	s_add_i32 s62, s34, 16
	s_add_i32 s63, s31, 20
	s_add_i32 s64, s34, 20
	s_add_i32 s65, s31, 24
	s_add_i32 s66, s34, 24
	s_add_i32 s31, s31, 28
	s_add_i32 s34, s34, 28
	v_add_u32_e32 v132, v109, v14
	v_or_b32_e32 v111, s35, v1
	v_or_b32_e32 v115, s36, v2
	v_or_b32_e32 v119, s37, v1
	v_or_b32_e32 v129, s58, v2
	v_or_b32_e32 v162, s59, v1
	v_or_b32_e32 v163, s60, v2
	v_or_b32_e32 v164, s61, v1
	v_or_b32_e32 v165, s62, v2
	v_or_b32_e32 v166, s63, v1
	v_or_b32_e32 v167, s64, v2
	v_or_b32_e32 v168, s65, v1
	v_or_b32_e32 v169, s66, v2
	v_or_b32_e32 v170, s31, v1
	v_or_b32_e32 v171, s34, v2
	v_add_u32_e32 v130, v104, v3
	v_ashrrev_i32_e32 v133, 31, v132
	v_add_u32_e32 v134, v111, v3
	v_add_u32_e32 v136, v115, v14
	v_add_u32_e32 v138, v119, v3
	v_add_u32_e32 v140, v129, v14
	v_add_u32_e32 v142, v162, v3
	v_add_u32_e32 v144, v163, v14
	v_add_u32_e32 v146, v164, v3
	v_add_u32_e32 v148, v165, v14
	v_add_u32_e32 v150, v166, v3
	v_add_u32_e32 v152, v167, v14
	v_add_u32_e32 v154, v168, v3
	v_add_u32_e32 v156, v169, v14
	v_add_u32_e32 v158, v170, v3
	v_add_u32_e32 v160, v171, v14
	v_ashrrev_i32_e32 v131, 31, v130
	v_lshlrev_b64 v[132:133], 13, v[132:133]
	v_ashrrev_i32_e32 v137, 31, v136
	v_ashrrev_i32_e32 v135, 31, v134
	v_ashrrev_i32_e32 v141, 31, v140
	v_ashrrev_i32_e32 v139, 31, v138
	v_ashrrev_i32_e32 v145, 31, v144
	v_ashrrev_i32_e32 v143, 31, v142
	v_ashrrev_i32_e32 v149, 31, v148
	v_ashrrev_i32_e32 v147, 31, v146
	v_ashrrev_i32_e32 v153, 31, v152
	v_ashrrev_i32_e32 v151, 31, v150
	v_ashrrev_i32_e32 v157, 31, v156
	v_ashrrev_i32_e32 v155, 31, v154
	v_ashrrev_i32_e32 v161, 31, v160
	v_ashrrev_i32_e32 v159, 31, v158
	v_lshlrev_b64 v[130:131], 13, v[130:131]
	v_lshl_add_u64 v[132:133], v[12:13], 0, v[132:133]
	v_lshlrev_b64 v[134:135], 13, v[134:135]
	v_lshlrev_b64 v[136:137], 13, v[136:137]
	v_lshlrev_b64 v[138:139], 13, v[138:139]
	v_lshlrev_b64 v[140:141], 13, v[140:141]
	v_lshlrev_b64 v[142:143], 13, v[142:143]
	v_lshlrev_b64 v[144:145], 13, v[144:145]
	v_lshlrev_b64 v[146:147], 13, v[146:147]
	v_lshlrev_b64 v[148:149], 13, v[148:149]
	v_lshlrev_b64 v[150:151], 13, v[150:151]
	v_lshlrev_b64 v[152:153], 13, v[152:153]
	v_lshlrev_b64 v[154:155], 13, v[154:155]
	v_lshlrev_b64 v[156:157], 13, v[156:157]
	v_lshlrev_b64 v[158:159], 13, v[158:159]
	v_lshlrev_b64 v[160:161], 13, v[160:161]
	v_lshl_add_u64 v[130:131], v[12:13], 0, v[130:131]
	v_lshl_add_u64 v[136:137], v[12:13], 0, v[136:137]
	v_lshl_add_u64 v[134:135], v[12:13], 0, v[134:135]
	v_lshl_add_u64 v[140:141], v[12:13], 0, v[140:141]
	v_lshl_add_u64 v[138:139], v[12:13], 0, v[138:139]
	v_lshl_add_u64 v[144:145], v[12:13], 0, v[144:145]
	v_lshl_add_u64 v[142:143], v[12:13], 0, v[142:143]
	v_lshl_add_u64 v[148:149], v[12:13], 0, v[148:149]
	v_lshl_add_u64 v[146:147], v[12:13], 0, v[146:147]
	v_lshl_add_u64 v[152:153], v[12:13], 0, v[152:153]
	v_lshl_add_u64 v[150:151], v[12:13], 0, v[150:151]
	v_lshl_add_u64 v[156:157], v[12:13], 0, v[156:157]
	v_lshl_add_u64 v[154:155], v[12:13], 0, v[154:155]
	v_lshl_add_u64 v[160:161], v[12:13], 0, v[160:161]
	v_lshl_add_u64 v[158:159], v[12:13], 0, v[158:159]
	global_load_dword v172, v[132:133], off nt
	global_load_dword v173, v[130:131], off nt
	global_load_dword v174, v[136:137], off nt
	global_load_dword v175, v[134:135], off nt
	global_load_dword v176, v[140:141], off nt
	global_load_dword v177, v[138:139], off nt
	global_load_dword v178, v[144:145], off nt
	global_load_dword v179, v[142:143], off nt
	global_load_dword v180, v[148:149], off nt
	global_load_dword v181, v[146:147], off nt
	global_load_dword v182, v[152:153], off nt
	global_load_dword v183, v[150:151], off nt
	global_load_dword v184, v[156:157], off nt
	global_load_dword v185, v[154:155], off nt
	global_load_dword v186, v[160:161], off nt
	global_load_dword v187, v[158:159], off nt
	s_add_i32 s29, s29, 16
	s_add_i32 s28, s28, 16
	s_add_i32 s30, s30, -16
	v_mad_u64_u32 v[130:131], s[34:35], v109, s33, v[6:7]
	v_mad_u64_u32 v[132:133], s[34:35], v104, s33, v[6:7]
	v_mad_u64_u32 v[134:135], s[34:35], v115, s33, v[6:7]
	v_mad_u64_u32 v[136:137], s[34:35], v111, s33, v[6:7]
	v_mad_u64_u32 v[138:139], s[34:35], v129, s33, v[6:7]
	v_mad_u64_u32 v[140:141], s[34:35], v119, s33, v[6:7]
	v_mad_u64_u32 v[142:143], s[34:35], v163, s33, v[6:7]
	v_mad_u64_u32 v[144:145], s[34:35], v162, s33, v[6:7]
	v_mad_u64_u32 v[146:147], s[34:35], v165, s33, v[6:7]
	v_mad_u64_u32 v[148:149], s[34:35], v164, s33, v[6:7]
	v_mad_u64_u32 v[150:151], s[34:35], v167, s33, v[6:7]
	v_mad_u64_u32 v[152:153], s[34:35], v166, s33, v[6:7]
	v_mad_u64_u32 v[154:155], s[34:35], v169, s33, v[6:7]
	v_mad_u64_u32 v[156:157], s[34:35], v168, s33, v[6:7]
	v_mad_u64_u32 v[158:159], s[34:35], v171, s33, v[6:7]
	v_mad_u64_u32 v[160:161], s[34:35], v170, s33, v[6:7]
	s_lshl_b32 s31, s28, 1
	s_lshl_b32 s34, s29, 1
	v_or_b32_e32 v4, s31, v1
	v_or_b32_e32 v9, s34, v2
	s_add_i32 s35, s31, 4
	s_add_i32 s36, s34, 4
	s_add_i32 s37, s31, 8
	s_add_i32 s58, s34, 8
	s_add_i32 s59, s31, 12
	s_add_i32 s60, s34, 12
	s_add_i32 s61, s31, 16
	s_add_i32 s62, s34, 16
	s_add_i32 s63, s31, 20
	s_add_i32 s64, s34, 20
	s_add_i32 s65, s31, 24
	s_add_i32 s66, s34, 24
	s_add_i32 s31, s31, 28
	s_add_i32 s34, s34, 28
	v_add_u32_e32 v32, v9, v14
	v_or_b32_e32 v11, s35, v1
	v_or_b32_e32 v15, s36, v2
	v_or_b32_e32 v19, s37, v1
	v_or_b32_e32 v29, s58, v2
	v_or_b32_e32 v62, s59, v1
	v_or_b32_e32 v63, s60, v2
	v_or_b32_e32 v64, s61, v1
	v_or_b32_e32 v65, s62, v2
	v_or_b32_e32 v66, s63, v1
	v_or_b32_e32 v67, s64, v2
	v_or_b32_e32 v68, s65, v1
	v_or_b32_e32 v69, s66, v2
	v_or_b32_e32 v70, s31, v1
	v_or_b32_e32 v71, s34, v2
	v_add_u32_e32 v30, v4, v3
	v_ashrrev_i32_e32 v33, 31, v32
	v_add_u32_e32 v34, v11, v3
	v_add_u32_e32 v36, v15, v14
	v_add_u32_e32 v38, v19, v3
	v_add_u32_e32 v40, v29, v14
	v_add_u32_e32 v42, v62, v3
	v_add_u32_e32 v44, v63, v14
	v_add_u32_e32 v46, v64, v3
	v_add_u32_e32 v48, v65, v14
	v_add_u32_e32 v50, v66, v3
	v_add_u32_e32 v52, v67, v14
	v_add_u32_e32 v54, v68, v3
	v_add_u32_e32 v56, v69, v14
	v_add_u32_e32 v58, v70, v3
	v_add_u32_e32 v60, v71, v14
	v_ashrrev_i32_e32 v31, 31, v30
	v_lshlrev_b64 v[32:33], 13, v[32:33]
	v_ashrrev_i32_e32 v37, 31, v36
	v_ashrrev_i32_e32 v35, 31, v34
	v_ashrrev_i32_e32 v41, 31, v40
	v_ashrrev_i32_e32 v39, 31, v38
	v_ashrrev_i32_e32 v45, 31, v44
	v_ashrrev_i32_e32 v43, 31, v42
	v_ashrrev_i32_e32 v49, 31, v48
	v_ashrrev_i32_e32 v47, 31, v46
	v_ashrrev_i32_e32 v53, 31, v52
	v_ashrrev_i32_e32 v51, 31, v50
	v_ashrrev_i32_e32 v57, 31, v56
	v_ashrrev_i32_e32 v55, 31, v54
	v_ashrrev_i32_e32 v61, 31, v60
	v_ashrrev_i32_e32 v59, 31, v58
	v_lshlrev_b64 v[30:31], 13, v[30:31]
	v_lshl_add_u64 v[32:33], v[12:13], 0, v[32:33]
	v_lshlrev_b64 v[34:35], 13, v[34:35]
	v_lshlrev_b64 v[36:37], 13, v[36:37]
	v_lshlrev_b64 v[38:39], 13, v[38:39]
	v_lshlrev_b64 v[40:41], 13, v[40:41]
	v_lshlrev_b64 v[42:43], 13, v[42:43]
	v_lshlrev_b64 v[44:45], 13, v[44:45]
	v_lshlrev_b64 v[46:47], 13, v[46:47]
	v_lshlrev_b64 v[48:49], 13, v[48:49]
	v_lshlrev_b64 v[50:51], 13, v[50:51]
	v_lshlrev_b64 v[52:53], 13, v[52:53]
	v_lshlrev_b64 v[54:55], 13, v[54:55]
	v_lshlrev_b64 v[56:57], 13, v[56:57]
	v_lshlrev_b64 v[58:59], 13, v[58:59]
	v_lshlrev_b64 v[60:61], 13, v[60:61]
	v_lshl_add_u64 v[30:31], v[12:13], 0, v[30:31]
	v_lshl_add_u64 v[36:37], v[12:13], 0, v[36:37]
	v_lshl_add_u64 v[34:35], v[12:13], 0, v[34:35]
	v_lshl_add_u64 v[40:41], v[12:13], 0, v[40:41]
	v_lshl_add_u64 v[38:39], v[12:13], 0, v[38:39]
	v_lshl_add_u64 v[44:45], v[12:13], 0, v[44:45]
	v_lshl_add_u64 v[42:43], v[12:13], 0, v[42:43]
	v_lshl_add_u64 v[48:49], v[12:13], 0, v[48:49]
	v_lshl_add_u64 v[46:47], v[12:13], 0, v[46:47]
	v_lshl_add_u64 v[52:53], v[12:13], 0, v[52:53]
	v_lshl_add_u64 v[50:51], v[12:13], 0, v[50:51]
	v_lshl_add_u64 v[56:57], v[12:13], 0, v[56:57]
	v_lshl_add_u64 v[54:55], v[12:13], 0, v[54:55]
	v_lshl_add_u64 v[60:61], v[12:13], 0, v[60:61]
	v_lshl_add_u64 v[58:59], v[12:13], 0, v[58:59]
	global_load_dword v72, v[32:33], off nt
	global_load_dword v73, v[30:31], off nt
	global_load_dword v74, v[36:37], off nt
	global_load_dword v75, v[34:35], off nt
	global_load_dword v76, v[40:41], off nt
	global_load_dword v77, v[38:39], off nt
	global_load_dword v78, v[44:45], off nt
	global_load_dword v79, v[42:43], off nt
	global_load_dword v80, v[48:49], off nt
	global_load_dword v81, v[46:47], off nt
	global_load_dword v82, v[52:53], off nt
	global_load_dword v83, v[50:51], off nt
	global_load_dword v84, v[56:57], off nt
	global_load_dword v85, v[54:55], off nt
	global_load_dword v86, v[60:61], off nt
	global_load_dword v87, v[58:59], off nt
	s_add_i32 s29, s29, 16
	s_add_i32 s28, s28, 16
	s_add_i32 s30, s30, -16
	v_mad_u64_u32 v[30:31], s[34:35], v9, s33, v[6:7]
	v_mad_u64_u32 v[32:33], s[34:35], v4, s33, v[6:7]
	v_mad_u64_u32 v[34:35], s[34:35], v15, s33, v[6:7]
	v_mad_u64_u32 v[36:37], s[34:35], v11, s33, v[6:7]
	v_mad_u64_u32 v[38:39], s[34:35], v29, s33, v[6:7]
	v_mad_u64_u32 v[40:41], s[34:35], v19, s33, v[6:7]
	v_mad_u64_u32 v[42:43], s[34:35], v63, s33, v[6:7]
	v_mad_u64_u32 v[44:45], s[34:35], v62, s33, v[6:7]
	v_mad_u64_u32 v[46:47], s[34:35], v65, s33, v[6:7]
	v_mad_u64_u32 v[48:49], s[34:35], v64, s33, v[6:7]
	v_mad_u64_u32 v[50:51], s[34:35], v67, s33, v[6:7]
	v_mad_u64_u32 v[52:53], s[34:35], v66, s33, v[6:7]
	v_mad_u64_u32 v[54:55], s[34:35], v69, s33, v[6:7]
	v_mad_u64_u32 v[56:57], s[34:35], v68, s33, v[6:7]
	v_mad_u64_u32 v[58:59], s[34:35], v71, s33, v[6:7]
	v_mad_u64_u32 v[60:61], s[34:35], v70, s33, v[6:7]
	s_waitcnt vmcnt(31)
	ds_write_b32 v130, v172
	s_waitcnt vmcnt(30)
	ds_write_b32 v132, v173
	s_waitcnt vmcnt(29)
	ds_write_b32 v134, v174
	s_waitcnt vmcnt(28)
	ds_write_b32 v136, v175
	s_waitcnt vmcnt(27)
	ds_write_b32 v138, v176
	s_waitcnt vmcnt(26)
	ds_write_b32 v140, v177
	s_waitcnt vmcnt(25)
	ds_write_b32 v142, v178
	s_waitcnt vmcnt(24)
	ds_write_b32 v144, v179
	s_waitcnt vmcnt(23)
	ds_write_b32 v146, v180
	s_waitcnt vmcnt(22)
	ds_write_b32 v148, v181
	s_waitcnt vmcnt(21)
	ds_write_b32 v150, v182
	s_waitcnt vmcnt(20)
	ds_write_b32 v152, v183
	s_waitcnt vmcnt(19)
	ds_write_b32 v154, v184
	s_waitcnt vmcnt(18)
	ds_write_b32 v156, v185
	s_waitcnt vmcnt(17)
	ds_write_b32 v158, v186
	s_waitcnt vmcnt(16)
	ds_write_b32 v160, v187
	s_waitcnt vmcnt(15)
	ds_write_b32 v30, v72
	s_waitcnt vmcnt(14)
	ds_write_b32 v32, v73
	s_waitcnt vmcnt(13)
	ds_write_b32 v34, v74
	s_waitcnt vmcnt(12)
	ds_write_b32 v36, v75
	s_waitcnt vmcnt(11)
	ds_write_b32 v38, v76
	s_waitcnt vmcnt(10)
	ds_write_b32 v40, v77
	s_waitcnt vmcnt(9)
	ds_write_b32 v42, v78
	s_waitcnt vmcnt(8)
	ds_write_b32 v44, v79
	s_waitcnt vmcnt(7)
	ds_write_b32 v46, v80
	s_waitcnt vmcnt(6)
	ds_write_b32 v48, v81
	s_waitcnt vmcnt(5)
	ds_write_b32 v50, v82
	s_waitcnt vmcnt(4)
	ds_write_b32 v52, v83
	s_waitcnt vmcnt(3)
	ds_write_b32 v54, v84
	s_waitcnt vmcnt(2)
	ds_write_b32 v56, v85
	s_waitcnt vmcnt(1)
	ds_write_b32 v58, v86
	s_waitcnt vmcnt(0)
	ds_write_b32 v60, v87
	s_waitcnt lgkmcnt(0)
	v_lshl_add_u64 v[12:13], v[16:17], 1, s[16:17]
	ds_read2_b32 v[16:17], v22 offset1:8
	ds_read2_b32 v[32:33], v22 offset0:33 offset1:41
	ds_read2_b32 v[34:35], v22 offset0:66 offset1:74
	ds_read2_b32 v[36:37], v22 offset0:99 offset1:107
	v_mov_b32_e32 v15, v5
	s_waitcnt lgkmcnt(3)
	v_bfe_u32 v3, v16, 16, 1
	v_add3_u32 v3, v16, v3, s45
	s_waitcnt lgkmcnt(2)
	v_bfe_u32 v4, v32, 16, 1
	ds_read2_b32 v[38:39], v22 offset0:132 offset1:140
	v_lshl_add_u64 v[12:13], v[14:15], 1, v[12:13]
	v_mov_b32_e32 v11, v5
	v_lshrrev_b32_e32 v3, 16, v3
	v_add3_u32 v4, v32, v4, s45
	ds_read2_b32 v[40:41], v22 offset0:165 offset1:173
	v_lshl_add_u64 v[30:31], v[12:13], 0, v[10:11]
	v_and_or_b32 v12, v4, s46, v3
	s_waitcnt lgkmcnt(3)
	v_bfe_u32 v3, v34, 16, 1
	v_add3_u32 v3, v34, v3, s45
	s_waitcnt lgkmcnt(2)
	v_bfe_u32 v4, v36, 16, 1
	ds_read2_b32 v[42:43], v22 offset0:198 offset1:206
	v_lshrrev_b32_e32 v3, 16, v3
	v_add3_u32 v4, v36, v4, s45
	ds_read2_b32 v[44:45], v22 offset0:231 offset1:239
	v_and_or_b32 v13, v4, s46, v3
	s_waitcnt lgkmcnt(3)
	v_bfe_u32 v3, v38, 16, 1
	v_add3_u32 v3, v38, v3, s45
	s_waitcnt lgkmcnt(2)
	v_bfe_u32 v4, v40, 16, 1
	v_lshrrev_b32_e32 v3, 16, v3
	v_add3_u32 v4, v40, v4, s45
	v_and_or_b32 v14, v4, s46, v3
	s_waitcnt lgkmcnt(1)
	v_bfe_u32 v3, v42, 16, 1
	v_add3_u32 v3, v42, v3, s45
	s_waitcnt lgkmcnt(0)
	v_bfe_u32 v4, v44, 16, 1
	v_lshrrev_b32_e32 v3, 16, v3
	v_add3_u32 v4, v44, v4, s45
	v_and_or_b32 v15, v4, s46, v3
	v_or_b32_e32 v3, v18, v21
	v_lshlrev_b32_e32 v4, 12, v3
	v_bfe_u32 v3, v17, 16, 1
	v_lshl_add_u64 v[46:47], v[30:31], 0, v[4:5]
	v_add3_u32 v3, v17, v3, s45
	v_bfe_u32 v4, v33, 16, 1
	v_lshrrev_b32_e32 v3, 16, v3
	v_add3_u32 v4, v33, v4, s45
	global_store_dwordx4 v[46:47], v[12:15], off
	ds_read2_b32 v[16:17], v22 offset0:16 offset1:24
	v_readlane_b32 s66, v253, 1
	v_and_or_b32 v12, v4, s46, v3
	v_bfe_u32 v3, v35, 16, 1
	v_add3_u32 v3, v35, v3, s45
	v_bfe_u32 v4, v37, 16, 1
	v_lshrrev_b32_e32 v3, 16, v3
	v_add3_u32 v4, v37, v4, s45
	v_and_or_b32 v13, v4, s46, v3
	v_bfe_u32 v3, v39, 16, 1
	v_add3_u32 v3, v39, v3, s45
	v_bfe_u32 v4, v41, 16, 1
	v_lshrrev_b32_e32 v3, 16, v3
	v_add3_u32 v4, v41, v4, s45
	v_and_or_b32 v14, v4, s46, v3
	v_bfe_u32 v3, v43, 16, 1
	v_add3_u32 v3, v43, v3, s45
	v_bfe_u32 v4, v45, 16, 1
	v_lshrrev_b32_e32 v3, 16, v3
	v_add3_u32 v4, v45, v4, s45
	v_and_or_b32 v15, v4, s46, v3
	v_or_b32_e32 v3, v18, v23
	v_lshlrev_b32_e32 v4, 12, v3
	v_lshl_add_u64 v[32:33], v[30:31], 0, v[4:5]
	global_store_dwordx4 v[32:33], v[12:15], off
	ds_read2_b32 v[32:33], v22 offset0:49 offset1:57
	ds_read2_b32 v[34:35], v22 offset0:82 offset1:90
	ds_read2_b32 v[36:37], v22 offset0:115 offset1:123
	s_waitcnt lgkmcnt(3)
	v_bfe_u32 v3, v16, 16, 1
	v_add3_u32 v3, v16, v3, s45
	s_waitcnt lgkmcnt(2)
	v_bfe_u32 v4, v32, 16, 1
	ds_read2_b32 v[38:39], v22 offset0:148 offset1:156
	v_lshrrev_b32_e32 v3, 16, v3
	v_add3_u32 v4, v32, v4, s45
	ds_read2_b32 v[40:41], v22 offset0:181 offset1:189
	v_and_or_b32 v12, v4, s46, v3
	s_waitcnt lgkmcnt(3)
	v_bfe_u32 v3, v34, 16, 1
	v_add3_u32 v3, v34, v3, s45
	s_waitcnt lgkmcnt(2)
	v_bfe_u32 v4, v36, 16, 1
	ds_read2_b32 v[42:43], v22 offset0:214 offset1:222
	v_lshrrev_b32_e32 v3, 16, v3
	v_add3_u32 v4, v36, v4, s45
	ds_read2_b32 v[44:45], v22 offset0:247 offset1:255
	v_and_or_b32 v13, v4, s46, v3
	s_waitcnt lgkmcnt(3)
	v_bfe_u32 v3, v38, 16, 1
	v_add3_u32 v3, v38, v3, s45
	s_waitcnt lgkmcnt(2)
	v_bfe_u32 v4, v40, 16, 1
	v_lshrrev_b32_e32 v3, 16, v3
	v_add3_u32 v4, v40, v4, s45
	v_and_or_b32 v14, v4, s46, v3
	s_waitcnt lgkmcnt(1)
	v_bfe_u32 v3, v42, 16, 1
	v_add3_u32 v3, v42, v3, s45
	s_waitcnt lgkmcnt(0)
	v_bfe_u32 v4, v44, 16, 1
	v_lshrrev_b32_e32 v3, 16, v3
	v_add3_u32 v4, v44, v4, s45
	v_and_or_b32 v15, v4, s46, v3
	v_or_b32_e32 v3, v18, v24
	v_lshlrev_b32_e32 v4, 12, v3
	v_bfe_u32 v3, v17, 16, 1
	v_lshl_add_u64 v[46:47], v[30:31], 0, v[4:5]
	v_add3_u32 v3, v17, v3, s45
	v_bfe_u32 v4, v33, 16, 1
	v_lshrrev_b32_e32 v3, 16, v3
	v_add3_u32 v4, v33, v4, s45
	global_store_dwordx4 v[46:47], v[12:15], off
	s_nop 1
	v_and_or_b32 v12, v4, s46, v3
	v_bfe_u32 v3, v35, 16, 1
	v_add3_u32 v3, v35, v3, s45
	v_bfe_u32 v4, v37, 16, 1
	v_lshrrev_b32_e32 v3, 16, v3
	v_add3_u32 v4, v37, v4, s45
	v_and_or_b32 v13, v4, s46, v3
	v_bfe_u32 v3, v39, 16, 1
	v_add3_u32 v3, v39, v3, s45
	v_bfe_u32 v4, v41, 16, 1
	v_lshrrev_b32_e32 v3, 16, v3
	v_add3_u32 v4, v41, v4, s45
	v_and_or_b32 v14, v4, s46, v3
	v_bfe_u32 v3, v43, 16, 1
	v_add3_u32 v3, v43, v3, s45
	v_bfe_u32 v4, v45, 16, 1
	v_lshrrev_b32_e32 v3, 16, v3
	v_add3_u32 v4, v45, v4, s45
	v_and_or_b32 v15, v4, s46, v3
	v_or_b32_e32 v3, v18, v25
	v_lshlrev_b32_e32 v4, 12, v3
	v_lshl_add_u64 v[16:17], v[30:31], 0, v[4:5]
	global_store_dwordx4 v[16:17], v[12:15], off
	s_waitcnt lgkmcnt(0)

.LBB0_140:
	s_andn2_saveexec_b64 s[24:25], s[24:25]
	s_cbranch_execz .LBB0_105
	s_load_dwordx2 s[26:27], s[6:7], 0x30
	v_mul_i32_i24_e32 v4, 0xfc1, v3
	v_lshrrev_b32_e32 v9, 31, v4
	v_ashrrev_i32_e32 v4, 19, v4
	v_add_u16_e32 v4, v4, v9
	v_mul_lo_u16_e32 v9, 0x82, v4
	v_sub_u16_e32 v3, v3, v9
	s_waitcnt lgkmcnt(0)
	v_mov_b64_e32 v[14:15], s[26:27]
	v_mad_i64_i32 v[18:19], s[26:27], v12, s54, v[14:15]
	v_lshlrev_b32_sdwa v14, v26, sext(v3) dst_sel:DWORD dst_unused:UNUSED_PAD src0_sel:DWORD src1_sel:WORD_0
	v_ashrrev_i32_e32 v15, 31, v14
	v_lshlrev_b32_sdwa v16, v28, sext(v4) dst_sel:DWORD dst_unused:UNUSED_PAD src0_sel:DWORD src1_sel:WORD_0
	v_lshl_add_u64 v[18:19], v[14:15], 2, v[18:19]
	v_mov_b32_e32 v9, v5
	v_lshl_add_u64 v[18:19], v[18:19], 0, v[8:9]
	v_mov_b32_e32 v3, v16
	s_mov_b32 s26, 1
	s_mov_b32 s27, 0
	s_mov_b32 s28, 32
	s_lshl_b32 s29, s26, 1
	s_lshl_b32 s30, s27, 1
	v_or_b32_e32 v104, s29, v1
	v_or_b32_e32 v109, s30, v2
	s_add_i32 s31, s29, 4
	s_add_i32 s34, s30, 4
	s_add_i32 s35, s29, 8
	s_add_i32 s36, s30, 8
	s_add_i32 s37, s29, 12
	s_add_i32 s58, s30, 12
	s_add_i32 s59, s29, 16
	s_add_i32 s60, s30, 16
	s_add_i32 s61, s29, 20
	s_add_i32 s62, s30, 20
	s_add_i32 s63, s29, 24
	s_add_i32 s64, s30, 24
	s_add_i32 s29, s29, 28
	s_add_i32 s30, s30, 28
	v_add_u32_e32 v111, v104, v3
	v_add_u32_e32 v113, v109, v16
	v_or_b32_e32 v115, s31, v1
	v_or_b32_e32 v117, s34, v2
	v_or_b32_e32 v129, s35, v1
	v_or_b32_e32 v162, s36, v2
	v_or_b32_e32 v163, s37, v1
	v_or_b32_e32 v164, s58, v2
	v_or_b32_e32 v165, s59, v1
	v_or_b32_e32 v166, s60, v2
	v_or_b32_e32 v167, s61, v1
	v_or_b32_e32 v168, s62, v2
	v_or_b32_e32 v169, s63, v1
	v_or_b32_e32 v170, s64, v2
	v_or_b32_e32 v171, s29, v1
	v_or_b32_e32 v172, s30, v2
	v_mad_i64_i32 v[130:131], s[30:31], v113, s55, v[18:19]
	v_mad_i64_i32 v[132:133], s[30:31], v111, s55, v[18:19]
	v_add_u32_e32 v111, v115, v3
	v_add_u32_e32 v113, v117, v16
	v_add_u32_e32 v140, v129, v3
	v_add_u32_e32 v138, v162, v16
	v_add_u32_e32 v144, v163, v3
	v_add_u32_e32 v142, v164, v16
	v_add_u32_e32 v148, v165, v3
	v_add_u32_e32 v146, v166, v16
	v_add_u32_e32 v152, v167, v3
	v_add_u32_e32 v150, v168, v16
	v_add_u32_e32 v156, v169, v3
	v_add_u32_e32 v154, v170, v16
	v_add_u32_e32 v160, v171, v3
	v_add_u32_e32 v158, v172, v16
	v_mad_i64_i32 v[134:135], s[30:31], v113, s55, v[18:19]
	v_mad_i64_i32 v[136:137], s[30:31], v111, s55, v[18:19]
	v_mad_i64_i32 v[138:139], s[30:31], v138, s55, v[18:19]
	v_mad_i64_i32 v[140:141], s[30:31], v140, s55, v[18:19]
	v_mad_i64_i32 v[142:143], s[30:31], v142, s55, v[18:19]
	v_mad_i64_i32 v[144:145], s[30:31], v144, s55, v[18:19]
	v_mad_i64_i32 v[146:147], s[30:31], v146, s55, v[18:19]
	v_mad_i64_i32 v[148:149], s[30:31], v148, s55, v[18:19]
	v_mad_i64_i32 v[150:151], s[30:31], v150, s55, v[18:19]
	v_mad_i64_i32 v[152:153], s[30:31], v152, s55, v[18:19]
	v_mad_i64_i32 v[154:155], s[30:31], v154, s55, v[18:19]
	v_mad_i64_i32 v[156:157], s[30:31], v156, s55, v[18:19]
	v_mad_i64_i32 v[158:159], s[30:31], v158, s55, v[18:19]
	v_mad_i64_i32 v[160:161], s[30:31], v160, s55, v[18:19]
	global_load_dword v111, v[130:131], off nt
	global_load_dword v113, v[132:133], off nt
	global_load_dword v173, v[134:135], off nt
	global_load_dword v174, v[136:137], off nt
	global_load_dword v175, v[138:139], off nt
	global_load_dword v176, v[140:141], off nt
	global_load_dword v177, v[142:143], off nt
	global_load_dword v178, v[144:145], off nt
	global_load_dword v179, v[146:147], off nt
	global_load_dword v180, v[148:149], off nt
	global_load_dword v181, v[150:151], off nt
	global_load_dword v182, v[152:153], off nt
	global_load_dword v183, v[154:155], off nt
	global_load_dword v184, v[156:157], off nt
	global_load_dword v185, v[158:159], off nt
	global_load_dword v186, v[160:161], off nt
	s_add_i32 s27, s27, 16
	s_add_i32 s26, s26, 16
	s_add_i32 s28, s28, -16
	v_mad_u64_u32 v[130:131], s[30:31], v109, s33, v[6:7]
	v_mad_u64_u32 v[132:133], s[30:31], v104, s33, v[6:7]
	v_mad_u64_u32 v[134:135], s[30:31], v117, s33, v[6:7]
	v_mad_u64_u32 v[136:137], s[30:31], v115, s33, v[6:7]
	v_mad_u64_u32 v[138:139], s[30:31], v162, s33, v[6:7]
	v_mad_u64_u32 v[140:141], s[30:31], v129, s33, v[6:7]
	v_mad_u64_u32 v[142:143], s[30:31], v164, s33, v[6:7]
	v_mad_u64_u32 v[144:145], s[30:31], v163, s33, v[6:7]
	v_mad_u64_u32 v[146:147], s[30:31], v166, s33, v[6:7]
	v_mad_u64_u32 v[148:149], s[30:31], v165, s33, v[6:7]
	v_mad_u64_u32 v[150:151], s[30:31], v168, s33, v[6:7]
	v_mad_u64_u32 v[152:153], s[30:31], v167, s33, v[6:7]
	v_mad_u64_u32 v[154:155], s[30:31], v170, s33, v[6:7]
	v_mad_u64_u32 v[156:157], s[30:31], v169, s33, v[6:7]
	v_mad_u64_u32 v[158:159], s[30:31], v172, s33, v[6:7]
	v_mad_u64_u32 v[160:161], s[30:31], v171, s33, v[6:7]
	s_lshl_b32 s29, s26, 1
	s_lshl_b32 s30, s27, 1
	v_or_b32_e32 v4, s29, v1
	v_or_b32_e32 v9, s30, v2
	s_add_i32 s31, s29, 4
	s_add_i32 s34, s30, 4
	s_add_i32 s35, s29, 8
	s_add_i32 s36, s30, 8
	s_add_i32 s37, s29, 12
	s_add_i32 s58, s30, 12
	s_add_i32 s59, s29, 16
	s_add_i32 s60, s30, 16
	s_add_i32 s61, s29, 20
	s_add_i32 s62, s30, 20
	s_add_i32 s63, s29, 24
	s_add_i32 s64, s30, 24
	s_add_i32 s29, s29, 28
	s_add_i32 s30, s30, 28
	v_add_u32_e32 v11, v4, v3
	v_add_u32_e32 v13, v9, v16
	v_or_b32_e32 v15, s31, v1
	v_or_b32_e32 v17, s34, v2
	v_or_b32_e32 v29, s35, v1
	v_or_b32_e32 v62, s36, v2
	v_or_b32_e32 v63, s37, v1
	v_or_b32_e32 v64, s58, v2
	v_or_b32_e32 v65, s59, v1
	v_or_b32_e32 v66, s60, v2
	v_or_b32_e32 v67, s61, v1
	v_or_b32_e32 v68, s62, v2
	v_or_b32_e32 v69, s63, v1
	v_or_b32_e32 v70, s64, v2
	v_or_b32_e32 v71, s29, v1
	v_or_b32_e32 v72, s30, v2
	v_mad_i64_i32 v[30:31], s[30:31], v13, s55, v[18:19]
	v_mad_i64_i32 v[32:33], s[30:31], v11, s55, v[18:19]
	v_add_u32_e32 v11, v15, v3
	v_add_u32_e32 v13, v17, v16
	v_add_u32_e32 v40, v29, v3
	v_add_u32_e32 v38, v62, v16
	v_add_u32_e32 v44, v63, v3
	v_add_u32_e32 v42, v64, v16
	v_add_u32_e32 v48, v65, v3
	v_add_u32_e32 v46, v66, v16
	v_add_u32_e32 v52, v67, v3
	v_add_u32_e32 v50, v68, v16
	v_add_u32_e32 v56, v69, v3
	v_add_u32_e32 v54, v70, v16
	v_add_u32_e32 v60, v71, v3
	v_add_u32_e32 v58, v72, v16
	v_mad_i64_i32 v[34:35], s[30:31], v13, s55, v[18:19]
	v_mad_i64_i32 v[36:37], s[30:31], v11, s55, v[18:19]
	v_mad_i64_i32 v[38:39], s[30:31], v38, s55, v[18:19]
	v_mad_i64_i32 v[40:41], s[30:31], v40, s55, v[18:19]
	v_mad_i64_i32 v[42:43], s[30:31], v42, s55, v[18:19]
	v_mad_i64_i32 v[44:45], s[30:31], v44, s55, v[18:19]
	v_mad_i64_i32 v[46:47], s[30:31], v46, s55, v[18:19]
	v_mad_i64_i32 v[48:49], s[30:31], v48, s55, v[18:19]
	v_mad_i64_i32 v[50:51], s[30:31], v50, s55, v[18:19]
	v_mad_i64_i32 v[52:53], s[30:31], v52, s55, v[18:19]
	v_mad_i64_i32 v[54:55], s[30:31], v54, s55, v[18:19]
	v_mad_i64_i32 v[56:57], s[30:31], v56, s55, v[18:19]
	v_mad_i64_i32 v[58:59], s[30:31], v58, s55, v[18:19]
	v_mad_i64_i32 v[60:61], s[30:31], v60, s55, v[18:19]
	global_load_dword v11, v[30:31], off nt
	global_load_dword v13, v[32:33], off nt
	global_load_dword v73, v[34:35], off nt
	global_load_dword v74, v[36:37], off nt
	global_load_dword v75, v[38:39], off nt
	global_load_dword v76, v[40:41], off nt
	global_load_dword v77, v[42:43], off nt
	global_load_dword v78, v[44:45], off nt
	global_load_dword v79, v[46:47], off nt
	global_load_dword v80, v[48:49], off nt
	global_load_dword v81, v[50:51], off nt
	global_load_dword v82, v[52:53], off nt
	global_load_dword v83, v[54:55], off nt
	global_load_dword v84, v[56:57], off nt
	global_load_dword v85, v[58:59], off nt
	global_load_dword v86, v[60:61], off nt
	s_add_i32 s27, s27, 16
	s_add_i32 s26, s26, 16
	s_add_i32 s28, s28, -16
	v_mad_u64_u32 v[30:31], s[30:31], v9, s33, v[6:7]
	v_mad_u64_u32 v[32:33], s[30:31], v4, s33, v[6:7]
	v_mad_u64_u32 v[34:35], s[30:31], v17, s33, v[6:7]
	v_mad_u64_u32 v[36:37], s[30:31], v15, s33, v[6:7]
	v_mad_u64_u32 v[38:39], s[30:31], v62, s33, v[6:7]
	v_mad_u64_u32 v[40:41], s[30:31], v29, s33, v[6:7]
	v_mad_u64_u32 v[42:43], s[30:31], v64, s33, v[6:7]
	v_mad_u64_u32 v[44:45], s[30:31], v63, s33, v[6:7]
	v_mad_u64_u32 v[46:47], s[30:31], v66, s33, v[6:7]
	v_mad_u64_u32 v[48:49], s[30:31], v65, s33, v[6:7]
	v_mad_u64_u32 v[50:51], s[30:31], v68, s33, v[6:7]
	v_mad_u64_u32 v[52:53], s[30:31], v67, s33, v[6:7]
	v_mad_u64_u32 v[54:55], s[30:31], v70, s33, v[6:7]
	v_mad_u64_u32 v[56:57], s[30:31], v69, s33, v[6:7]
	v_mad_u64_u32 v[58:59], s[30:31], v72, s33, v[6:7]
	v_mad_u64_u32 v[60:61], s[30:31], v71, s33, v[6:7]
	s_waitcnt vmcnt(31)
	ds_write_b32 v130, v111
	s_waitcnt vmcnt(30)
	ds_write_b32 v132, v113
	s_waitcnt vmcnt(29)
	ds_write_b32 v134, v173
	s_waitcnt vmcnt(28)
	ds_write_b32 v136, v174
	s_waitcnt vmcnt(27)
	ds_write_b32 v138, v175
	s_waitcnt vmcnt(26)
	ds_write_b32 v140, v176
	s_waitcnt vmcnt(25)
	ds_write_b32 v142, v177
	s_waitcnt vmcnt(24)
	ds_write_b32 v144, v178
	s_waitcnt vmcnt(23)
	ds_write_b32 v146, v179
	s_waitcnt vmcnt(22)
	ds_write_b32 v148, v180
	s_waitcnt vmcnt(21)
	ds_write_b32 v150, v181
	s_waitcnt vmcnt(20)
	ds_write_b32 v152, v182
	s_waitcnt vmcnt(19)
	ds_write_b32 v154, v183
	s_waitcnt vmcnt(18)
	ds_write_b32 v156, v184
	s_waitcnt vmcnt(17)
	ds_write_b32 v158, v185
	s_waitcnt vmcnt(16)
	ds_write_b32 v160, v186
	s_waitcnt vmcnt(15)
	ds_write_b32 v30, v11
	s_waitcnt vmcnt(14)
	ds_write_b32 v32, v13
	s_waitcnt vmcnt(13)
	ds_write_b32 v34, v73
	s_waitcnt vmcnt(12)
	ds_write_b32 v36, v74
	s_waitcnt vmcnt(11)
	ds_write_b32 v38, v75
	s_waitcnt vmcnt(10)
	ds_write_b32 v40, v76
	s_waitcnt vmcnt(9)
	ds_write_b32 v42, v77
	s_waitcnt vmcnt(8)
	ds_write_b32 v44, v78
	s_waitcnt vmcnt(7)
	ds_write_b32 v46, v79
	s_waitcnt vmcnt(6)
	ds_write_b32 v48, v80
	s_waitcnt vmcnt(5)
	ds_write_b32 v50, v81
	s_waitcnt vmcnt(4)
	ds_write_b32 v52, v82
	s_waitcnt vmcnt(3)
	ds_write_b32 v54, v83
	s_waitcnt vmcnt(2)
	ds_write_b32 v56, v84
	s_waitcnt vmcnt(1)
	ds_write_b32 v58, v85
	s_waitcnt vmcnt(0)
	ds_write_b32 v60, v86
	s_waitcnt lgkmcnt(0)
	ds_read2_b32 v[30:31], v22 offset1:8
	ds_read2_b32 v[32:33], v22 offset0:33 offset1:41
	ds_read2_b32 v[34:35], v22 offset0:66 offset1:74
	ds_read2_b32 v[36:37], v22 offset0:99 offset1:107
	v_mov_b64_e32 v[18:19], s[18:19]
	s_waitcnt lgkmcnt(3)
	v_bfe_u32 v3, v30, 16, 1
	v_add3_u32 v3, v30, v3, s45
	s_waitcnt lgkmcnt(2)
	v_bfe_u32 v4, v32, 16, 1
	ds_read2_b32 v[38:39], v22 offset0:132 offset1:140
	v_mad_i64_i32 v[12:13], s[26:27], v12, s56, v[18:19]
	v_ashrrev_i32_e32 v17, 31, v16
	v_lshrrev_b32_e32 v3, 16, v3
	v_add3_u32 v4, v32, v4, s45
	ds_read2_b32 v[40:41], v22 offset0:165 offset1:173
	v_lshl_add_u64 v[12:13], v[16:17], 1, v[12:13]
	v_and_or_b32 v16, v4, s46, v3
	s_waitcnt lgkmcnt(3)
	v_bfe_u32 v3, v34, 16, 1
	v_add3_u32 v3, v34, v3, s45
	s_waitcnt lgkmcnt(2)
	v_bfe_u32 v4, v36, 16, 1
	ds_read2_b32 v[42:43], v22 offset0:198 offset1:206
	v_lshrrev_b32_e32 v3, 16, v3
	v_add3_u32 v4, v36, v4, s45
	ds_read2_b32 v[44:45], v22 offset0:231 offset1:239
	v_and_or_b32 v17, v4, s46, v3
	s_waitcnt lgkmcnt(3)
	v_bfe_u32 v3, v38, 16, 1
	v_add3_u32 v3, v38, v3, s45
	s_waitcnt lgkmcnt(2)
	v_bfe_u32 v4, v40, 16, 1
	v_lshrrev_b32_e32 v3, 16, v3
	v_add3_u32 v4, v40, v4, s45
	v_and_or_b32 v18, v4, s46, v3
	s_waitcnt lgkmcnt(1)
	v_bfe_u32 v3, v42, 16, 1
	v_add3_u32 v3, v42, v3, s45
	s_waitcnt lgkmcnt(0)
	v_bfe_u32 v4, v44, 16, 1
	v_lshrrev_b32_e32 v3, 16, v3
	v_add3_u32 v4, v44, v4, s45
	v_or_b32_e32 v46, v14, v21
	v_mov_b32_e32 v11, v5
	v_and_or_b32 v19, v4, s46, v3
	v_ashrrev_i32_e32 v47, 31, v46
	v_bfe_u32 v3, v31, 16, 1
	v_lshl_add_u64 v[12:13], v[12:13], 0, v[10:11]
	v_lshlrev_b64 v[46:47], 12, v[46:47]
	v_add3_u32 v3, v31, v3, s45
	v_bfe_u32 v4, v33, 16, 1
	v_lshl_add_u64 v[46:47], v[12:13], 0, v[46:47]
	v_lshrrev_b32_e32 v3, 16, v3
	v_add3_u32 v4, v33, v4, s45
	global_store_dwordx4 v[46:47], v[16:19], off
	v_or_b32_e32 v30, v14, v23
	v_ashrrev_i32_e32 v31, 31, v30
	v_and_or_b32 v16, v4, s46, v3
	v_bfe_u32 v3, v35, 16, 1
	v_add3_u32 v3, v35, v3, s45
	v_bfe_u32 v4, v37, 16, 1
	v_lshrrev_b32_e32 v3, 16, v3
	v_add3_u32 v4, v37, v4, s45
	v_and_or_b32 v17, v4, s46, v3
	v_bfe_u32 v3, v39, 16, 1
	v_add3_u32 v3, v39, v3, s45
	v_bfe_u32 v4, v41, 16, 1
	v_lshrrev_b32_e32 v3, 16, v3
	v_add3_u32 v4, v41, v4, s45
	v_and_or_b32 v18, v4, s46, v3
	v_bfe_u32 v3, v43, 16, 1
	v_add3_u32 v3, v43, v3, s45
	v_bfe_u32 v4, v45, 16, 1
	v_lshrrev_b32_e32 v3, 16, v3
	v_add3_u32 v4, v45, v4, s45
	v_lshlrev_b64 v[30:31], 12, v[30:31]
	v_and_or_b32 v19, v4, s46, v3
	ds_read2_b32 v[32:33], v22 offset0:16 offset1:24
	v_lshl_add_u64 v[30:31], v[12:13], 0, v[30:31]
	global_store_dwordx4 v[30:31], v[16:19], off
	ds_read2_b32 v[30:31], v22 offset0:49 offset1:57
	ds_read2_b32 v[34:35], v22 offset0:82 offset1:90
	ds_read2_b32 v[36:37], v22 offset0:115 offset1:123
	s_waitcnt lgkmcnt(3)
	v_bfe_u32 v3, v32, 16, 1
	v_add3_u32 v3, v32, v3, s45
	s_waitcnt lgkmcnt(2)
	v_bfe_u32 v4, v30, 16, 1
	ds_read2_b32 v[38:39], v22 offset0:148 offset1:156
	v_lshrrev_b32_e32 v3, 16, v3
	v_add3_u32 v4, v30, v4, s45
	ds_read2_b32 v[40:41], v22 offset0:181 offset1:189
	v_and_or_b32 v16, v4, s46, v3
	s_waitcnt lgkmcnt(3)
	v_bfe_u32 v3, v34, 16, 1
	v_add3_u32 v3, v34, v3, s45
	s_waitcnt lgkmcnt(2)
	v_bfe_u32 v4, v36, 16, 1
	ds_read2_b32 v[42:43], v22 offset0:214 offset1:222
	v_lshrrev_b32_e32 v3, 16, v3
	v_add3_u32 v4, v36, v4, s45
	ds_read2_b32 v[44:45], v22 offset0:247 offset1:255
	v_and_or_b32 v17, v4, s46, v3
	s_waitcnt lgkmcnt(3)
	v_bfe_u32 v3, v38, 16, 1
	v_add3_u32 v3, v38, v3, s45
	s_waitcnt lgkmcnt(2)
	v_bfe_u32 v4, v40, 16, 1
	v_lshrrev_b32_e32 v3, 16, v3
	v_add3_u32 v4, v40, v4, s45
	v_and_or_b32 v18, v4, s46, v3
	s_waitcnt lgkmcnt(1)
	v_bfe_u32 v3, v42, 16, 1
	v_add3_u32 v3, v42, v3, s45
	s_waitcnt lgkmcnt(0)
	v_bfe_u32 v4, v44, 16, 1
	v_lshrrev_b32_e32 v3, 16, v3
	v_add3_u32 v4, v44, v4, s45
	v_or_b32_e32 v46, v14, v24
	v_and_or_b32 v19, v4, s46, v3
	v_ashrrev_i32_e32 v47, 31, v46
	v_bfe_u32 v3, v33, 16, 1
	v_lshlrev_b64 v[46:47], 12, v[46:47]
	v_add3_u32 v3, v33, v3, s45
	v_bfe_u32 v4, v31, 16, 1
	v_lshl_add_u64 v[46:47], v[12:13], 0, v[46:47]
	v_lshrrev_b32_e32 v3, 16, v3
	v_add3_u32 v4, v31, v4, s45
	global_store_dwordx4 v[46:47], v[16:19], off
	v_or_b32_e32 v14, v14, v25
	v_ashrrev_i32_e32 v15, 31, v14
	v_and_or_b32 v16, v4, s46, v3
	v_bfe_u32 v3, v35, 16, 1
	v_add3_u32 v3, v35, v3, s45
	v_bfe_u32 v4, v37, 16, 1
	v_lshrrev_b32_e32 v3, 16, v3
	v_add3_u32 v4, v37, v4, s45
	v_and_or_b32 v17, v4, s46, v3
	v_bfe_u32 v3, v39, 16, 1
	v_add3_u32 v3, v39, v3, s45
	v_bfe_u32 v4, v41, 16, 1
	v_lshrrev_b32_e32 v3, 16, v3
	v_add3_u32 v4, v41, v4, s45
	v_and_or_b32 v18, v4, s46, v3
	v_bfe_u32 v3, v43, 16, 1
	v_add3_u32 v3, v43, v3, s45
	v_bfe_u32 v4, v45, 16, 1
	v_lshrrev_b32_e32 v3, 16, v3
	v_add3_u32 v4, v45, v4, s45
	v_lshlrev_b64 v[14:15], 12, v[14:15]
	v_and_or_b32 v19, v4, s46, v3
	v_lshl_add_u64 v[12:13], v[12:13], 0, v[14:15]
	global_store_dwordx4 v[12:13], v[16:19], off
	s_waitcnt lgkmcnt(0)
	s_branch .LBB0_105
